# Oacc
# speedup vs baseline: 1.0099x; 1.0099x over previous
; #define PG8_STAGE(bufoff, gbase, voff) do { _Pragma("unroll") for (int _i = 0; _i < 2; ++_i) \
;         __builtin_amdgcn_global_load_lds((const unsigned*)((const char*)(gbase) + (voff)[_i]), (PG8_LAS unsigned*)(lds + (bufoff) + ldsw + _i * 8192), 16, 0, 0); } while (0)
; #define PG8_LDA(dst, b, h) do { _Pragma("unroll") for (int m = 0; m < 4; ++m) _Pragma("unroll") for (int k = 0; k < 2; ++k) dst[m][k] = *(const PG8_LAS bf16x8*)(lds + PG8_SA(b, h) + aoff + m * 2048 + k * 1024); } while (0)
; #define PG8_LDB(dst, b, h) do { _Pragma("unroll") for (int n = 0; n < 2; ++n) _Pragma("unroll") for (int k = 0; k < 2; ++k) dst[n][k] = *(const PG8_LAS bf16x8*)(lds + PG8_SB(b, h) + boff + n * 2048 + k * 1024); } while (0)
; #define PG8_MMA(ai, bj, At, Bt) do { __builtin_amdgcn_s_setprio(1); _Pragma("unroll") for (int m = 0; m < 4; ++m) _Pragma("unroll") for (int n = 0; n < 2; ++n) _Pragma("unroll") for (int k = 0; k < 2; ++k) \
;         acc[ai][bj][m][n] = __builtin_amdgcn_mfma_f32_16x16x32_bf16(Bt[n][k], At[m][k], acc[ai][bj][m][n], 0, 0, 0); __builtin_amdgcn_s_setprio(0); } while (0)
; #define PG8_WAIT_V(n) asm volatile("s_waitcnt vmcnt(" #n ")" ::: "memory")
; #define PG8_BAR __builtin_amdgcn_s_barrier()
; template <class Epi, class Sched, bool ALIGN_EPI = false, bool SP2 = false, bool DUAL = false>
; __device__ __forceinline__ void gemm_phase(PG8_LAS unsigned char* lds, const Gemm g, const Sched& S, const Epi& E) {
;     ...
;         for (int t = 0; t < nt; t += 2) {
;             const bool last = (t == nt - 2);
;             const char* a1 = cA + (size_t)(t + 1) * kstep;
;             const char* a2 = last ? nA : cA + (size_t)(t + 2) * kstep; const char* b2 = last ? nB : cB + (size_t)(t + 2) * kstep;
;             const char* a3 = a2 + kstep; const char* b3 = b2 + kstep;
;             if (last && has_next) S.a_ready(nxt);
;             if constexpr (SP2) {
;             PG8_LDB(B0, 0, 0); PG8_LDB(B1, 0, 1); PG8_SCHED; PG8_LDA(At, 0, 0); PG8_STAGE(PG8_SA(1, 1), a1 + hstep, voffA);
;             PG8_WAIT_V(8); PG8_WAIT_L(0); PG8_BAR; PG8_MMA(0, 0, At, B0); PG8_MMA(0, 1, At, B1); PG8_BAR; PG8_SCHED;
;             PG8_LDA(At, 0, 1); PG8_STAGE(PG8_SB(0, 0), b2, voffB); PG8_STAGE(PG8_SB(0, 1), b2 + hstep, voffB); PG8_STAGE(PG8_SA(0, 0), a2, voffA);
;             PG8_WAIT_V(8); PG8_WAIT_L(0); PG8_BAR; PG8_MMA(1, 0, At, B0); PG8_MMA(1, 1, At, B1); PG8_BAR; PG8_SCHED;
.LBB0_251:
	s_ashr_i32 s87, s86, 31
	s_lshl_b64 s[16:17], s[86:87], 20
	s_add_u32 s92, s58, s16
	s_addc_u32 s93, s59, s17
	s_and_b64 s[16:17], s[4:5], exec
	s_cselect_b32 s7, s93, s11
	s_cselect_b32 s9, s92, s10
	s_ashr_i32 s1, s0, 31
	s_lshl_b64 s[16:17], s[0:1], 20
	s_add_u32 s88, s90, s16
	s_addc_u32 s89, s91, s17
	s_and_b64 s[16:17], s[4:5], exec
	s_cselect_b32 s1, s89, s15
	s_cselect_b32 s45, s88, s14
	s_add_u32 s10, s10, 0x80080
	s_addc_u32 s11, s11, 0
	s_add_u32 s46, s14, 0x100
	s_addc_u32 s47, s15, 0
	s_mov_b32 s48, -2
	s_add_u32 s14, s10, 0xfff80080
	s_addc_u32 s15, s11, -1
	s_cmp_eq_u32 s48, 28
	s_cselect_b32 s17, s7, s15
	s_cselect_b32 s16, s9, s14
	s_cselect_b32 s15, s1, s47
	s_cselect_b32 s14, s45, s46
	s_waitcnt vmcnt(8)
	s_waitcnt lgkmcnt(0)
	s_setprio 1
	s_barrier
	v_mfma_f32_16x16x32_bf16 v[140:143], v[80:83], v[208:211], 0
	v_mfma_f32_16x16x32_bf16 v[140:143], v[84:87], v[212:215], v[140:143]
	v_mfma_f32_16x16x32_bf16 v[132:135], v[88:91], v[208:211], 0
	v_mfma_f32_16x16x32_bf16 v[132:135], v[92:95], v[212:215], v[132:135]
	v_mfma_f32_16x16x32_bf16 v[124:127], v[80:83], v[216:219], 0
	v_mfma_f32_16x16x32_bf16 v[124:127], v[84:87], v[220:223], v[124:127]
	v_mfma_f32_16x16x32_bf16 v[120:123], v[88:91], v[216:219], 0
	v_mfma_f32_16x16x32_bf16 v[120:123], v[92:95], v[220:223], v[120:123]
	v_mfma_f32_16x16x32_bf16 v[108:111], v[80:83], v[232:235], 0
	v_mfma_f32_16x16x32_bf16 v[108:111], v[84:87], v[236:239], v[108:111]
	v_mfma_f32_16x16x32_bf16 v[104:107], v[88:91], v[232:235], 0
	v_mfma_f32_16x16x32_bf16 v[104:107], v[92:95], v[236:239], v[104:107]
	v_mfma_f32_16x16x32_bf16 v[76:79], v[80:83], v[240:243], 0
	v_mfma_f32_16x16x32_bf16 v[76:79], v[84:87], v[244:247], v[76:79]
	v_mfma_f32_16x16x32_bf16 v[72:75], v[88:91], v[240:243], 0
	v_mfma_f32_16x16x32_bf16 v[72:75], v[92:95], v[244:247], v[72:75]
	s_setprio 0
	s_setprio 1
	v_mfma_f32_16x16x32_bf16 v[136:139], v[144:147], v[208:211], 0
	v_mfma_f32_16x16x32_bf16 v[136:139], v[148:151], v[212:215], v[136:139]
	v_mfma_f32_16x16x32_bf16 v[128:131], v[152:155], v[208:211], 0
	v_mfma_f32_16x16x32_bf16 v[128:131], v[156:159], v[212:215], v[128:131]
	v_mfma_f32_16x16x32_bf16 v[116:119], v[144:147], v[216:219], 0
	v_mfma_f32_16x16x32_bf16 v[116:119], v[148:151], v[220:223], v[116:119]
	v_mfma_f32_16x16x32_bf16 v[112:115], v[152:155], v[216:219], 0
	v_mfma_f32_16x16x32_bf16 v[112:115], v[156:159], v[220:223], v[112:115]
	v_mfma_f32_16x16x32_bf16 v[100:103], v[144:147], v[232:235], 0
	v_mfma_f32_16x16x32_bf16 v[100:103], v[148:151], v[236:239], v[100:103]
	v_mfma_f32_16x16x32_bf16 v[96:99], v[152:155], v[232:235], 0
	v_mfma_f32_16x16x32_bf16 v[96:99], v[156:159], v[236:239], v[96:99]
	v_mfma_f32_16x16x32_bf16 v[68:71], v[144:147], v[240:243], 0
	v_mfma_f32_16x16x32_bf16 v[68:71], v[148:151], v[244:247], v[68:71]
	v_mfma_f32_16x16x32_bf16 v[64:67], v[152:155], v[240:243], 0
	v_mfma_f32_16x16x32_bf16 v[64:67], v[156:159], v[244:247], v[64:67]
	s_barrier
	s_setprio 0
	v_lshl_add_u64 v[192:193], s[10:11], 0, v[186:187]
	s_add_i32 m0, s19, 0xc000
	s_nop 0
	global_load_lds_dwordx4 v[192:193], off
	v_lshl_add_u64 v[192:193], s[10:11], 0, v[188:189]
	s_add_i32 m0, s19, 0xe000
	s_nop 0
	global_load_lds_dwordx4 v[192:193], off
	s_add_i32 s49, s31, s18
	v_lshl_add_u64 v[192:193], s[14:15], 0, v[166:167]
	s_mov_b32 m0, s49
	ds_read_b128 v[208:211], v203 offset:16384
	ds_read_b128 v[212:215], v203 offset:17408
	ds_read_b128 v[216:219], v203 offset:18432
	ds_read_b128 v[220:223], v203 offset:19456
	ds_read_b128 v[232:235], v203 offset:20480
	ds_read_b128 v[236:239], v203 offset:21504
	ds_read_b128 v[240:243], v203 offset:22528
	ds_read_b128 v[244:247], v203 offset:23552
	global_load_lds_dwordx4 v[192:193], off
	s_add_i32 m0, s49, 0x2000
	s_add_u32 s50, s14, 0x80000
	v_lshl_add_u64 v[248:249], s[14:15], 0, v[170:171]
	s_addc_u32 s51, s15, 0
	s_add_i32 s49, s34, s18
	global_load_lds_dwordx4 v[248:249], off
	v_lshl_add_u64 v[250:251], s[50:51], 0, v[166:167]
	s_mov_b32 m0, s49
	v_lshl_add_u64 v[252:253], s[16:17], 0, v[168:169]
	global_load_lds_dwordx4 v[250:251], off
	v_lshl_add_u64 v[250:251], s[50:51], 0, v[170:171]
	s_add_i32 m0, s49, 0x2000
	s_nop 0
	global_load_lds_dwordx4 v[250:251], off
	v_lshl_add_u64 v[250:251], s[16:17], 0, v[164:165]
	s_mov_b32 m0, s19
	s_nop 0
	global_load_lds_dwordx4 v[250:251], off
	s_mov_b32 m0, s20
	s_nop 0
	global_load_lds_dwordx4 v[252:253], off
	s_waitcnt vmcnt(8)
	s_waitcnt lgkmcnt(0)
	s_setprio 1
	s_barrier
	v_mfma_f32_16x16x32_bf16 v[60:63], v[80:83], v[208:211], 0
	v_mfma_f32_16x16x32_bf16 v[60:63], v[84:87], v[212:215], v[60:63]
	v_mfma_f32_16x16x32_bf16 v[56:59], v[88:91], v[208:211], 0
	v_mfma_f32_16x16x32_bf16 v[56:59], v[92:95], v[212:215], v[56:59]
	v_mfma_f32_16x16x32_bf16 v[44:47], v[80:83], v[216:219], 0
	v_mfma_f32_16x16x32_bf16 v[44:47], v[84:87], v[220:223], v[44:47]
	v_mfma_f32_16x16x32_bf16 v[40:43], v[88:91], v[216:219], 0
	v_mfma_f32_16x16x32_bf16 v[40:43], v[92:95], v[220:223], v[40:43]
	v_mfma_f32_16x16x32_bf16 v[28:31], v[80:83], v[232:235], 0
	v_mfma_f32_16x16x32_bf16 v[28:31], v[84:87], v[236:239], v[28:31]
	v_mfma_f32_16x16x32_bf16 v[24:27], v[88:91], v[232:235], 0
	v_mfma_f32_16x16x32_bf16 v[24:27], v[92:95], v[236:239], v[24:27]
	v_mfma_f32_16x16x32_bf16 v[12:15], v[80:83], v[240:243], 0
	v_mfma_f32_16x16x32_bf16 v[12:15], v[84:87], v[244:247], v[12:15]
	v_mfma_f32_16x16x32_bf16 v[8:11], v[88:91], v[240:243], 0
	v_mfma_f32_16x16x32_bf16 v[8:11], v[92:95], v[244:247], v[8:11]
	s_setprio 0
	s_setprio 1
	v_mfma_f32_16x16x32_bf16 v[52:55], v[144:147], v[208:211], 0
	v_mfma_f32_16x16x32_bf16 v[52:55], v[148:151], v[212:215], v[52:55]
	v_mfma_f32_16x16x32_bf16 v[48:51], v[152:155], v[208:211], 0
	v_mfma_f32_16x16x32_bf16 v[48:51], v[156:159], v[212:215], v[48:51]
	v_mfma_f32_16x16x32_bf16 v[36:39], v[144:147], v[216:219], 0
	v_mfma_f32_16x16x32_bf16 v[36:39], v[148:151], v[220:223], v[36:39]
	v_mfma_f32_16x16x32_bf16 v[32:35], v[152:155], v[216:219], 0
	v_mfma_f32_16x16x32_bf16 v[32:35], v[156:159], v[220:223], v[32:35]
	v_mfma_f32_16x16x32_bf16 v[20:23], v[144:147], v[232:235], 0
	v_mfma_f32_16x16x32_bf16 v[20:23], v[148:151], v[236:239], v[20:23]
	v_mfma_f32_16x16x32_bf16 v[16:19], v[152:155], v[232:235], 0
	v_mfma_f32_16x16x32_bf16 v[16:19], v[156:159], v[236:239], v[16:19]
	v_mfma_f32_16x16x32_bf16 v[4:7], v[144:147], v[240:243], 0
	v_mfma_f32_16x16x32_bf16 v[4:7], v[148:151], v[244:247], v[4:7]
	v_mfma_f32_16x16x32_bf16 v[0:3], v[152:155], v[240:243], 0
	v_mfma_f32_16x16x32_bf16 v[0:3], v[156:159], v[244:247], v[0:3]
	s_barrier
; #define PG8_STAGE(bufoff, gbase, voff) do { _Pragma("unroll") for (int _i = 0; _i < 2; ++_i) \
;         __builtin_amdgcn_global_load_lds((const unsigned*)((const char*)(gbase) + (voff)[_i]), (PG8_LAS unsigned*)(lds + (bufoff) + ldsw + _i * 8192), 16, 0, 0); } while (0)
; #define PG8_LDA(dst, b, h) do { _Pragma("unroll") for (int m = 0; m < 4; ++m) _Pragma("unroll") for (int k = 0; k < 2; ++k) dst[m][k] = *(const PG8_LAS bf16x8*)(lds + PG8_SA(b, h) + aoff + m * 2048 + k * 1024); } while (0)
; #define PG8_LDB(dst, b, h) do { _Pragma("unroll") for (int n = 0; n < 2; ++n) _Pragma("unroll") for (int k = 0; k < 2; ++k) dst[n][k] = *(const PG8_LAS bf16x8*)(lds + PG8_SB(b, h) + boff + n * 2048 + k * 1024); } while (0)
; #define PG8_MMA(ai, bj, At, Bt) do { __builtin_amdgcn_s_setprio(1); _Pragma("unroll") for (int m = 0; m < 4; ++m) _Pragma("unroll") for (int n = 0; n < 2; ++n) _Pragma("unroll") for (int k = 0; k < 2; ++k) \
;         acc[ai][bj][m][n] = __builtin_amdgcn_mfma_f32_16x16x32_bf16(Bt[n][k], At[m][k], acc[ai][bj][m][n], 0, 0, 0); __builtin_amdgcn_s_setprio(0); } while (0)
; #define PG8_WAIT_V(n) asm volatile("s_waitcnt vmcnt(" #n ")" ::: "memory")
; #define PG8_WAIT_L(n) asm volatile("s_waitcnt lgkmcnt(" #n ")" ::: "memory")
; #define PG8_BAR __builtin_amdgcn_s_barrier()
; #define PG8_SCHED __builtin_amdgcn_sched_barrier(0)
; template <class Epi, class Sched, bool ALIGN_EPI = false, bool SP2 = false, bool DUAL = false>
; __device__ __forceinline__ void gemm_phase(PG8_LAS unsigned char* lds, const Gemm g, const Sched& S, const Epi& E) {
;     ...
;             PG8_LDB(B0, 1, 0); PG8_LDB(B1, 1, 1); PG8_SCHED; PG8_LDA(At, 1, 0); PG8_STAGE(PG8_SA(0, 1), a2 + hstep, voffA);
;             PG8_WAIT_V(8); PG8_WAIT_L(0); PG8_BAR; PG8_MMA(0, 0, At, B0); PG8_MMA(0, 1, At, B1); PG8_BAR; PG8_SCHED;
;             PG8_LDA(At, 1, 1); PG8_STAGE(PG8_SB(1, 0), b3, voffB); PG8_STAGE(PG8_SB(1, 1), b3 + hstep, voffB); PG8_STAGE(PG8_SA(1, 0), a3, voffA);
;             PG8_WAIT_V(8); PG8_WAIT_L(0); PG8_BAR; PG8_MMA(1, 0, At, B0); PG8_MMA(1, 1, At, B1); PG8_BAR; PG8_SCHED;
	s_setprio 0
	s_add_i32 s49, 0, 0x18000
	s_add_i32 s50, 0, 0x1c000
	v_add_u32_e32 v92, s49, v196
	v_add_u32_e32 v156, s50, v196
	ds_read_b128 v[80:83], v92
	ds_read_b128 v[84:87], v92 offset:1024
	ds_read_b128 v[88:91], v92 offset:2048
	ds_read_b128 v[92:95], v92 offset:3072
	ds_read_b128 v[144:147], v156
	ds_read_b128 v[148:151], v156 offset:1024
	ds_read_b128 v[152:155], v156 offset:2048
	ds_read_b128 v[156:159], v156 offset:3072
	s_add_u32 s16, s16, 0x80000
	s_addc_u32 s17, s17, 0
	s_mov_b32 m0, s21
	v_lshl_add_u64 v[228:229], s[16:17], 0, v[164:165]
	ds_read_b128 v[208:211], v203 offset:32768
	ds_read_b128 v[212:215], v203 offset:33792
	ds_read_b128 v[216:219], v203 offset:34816
	ds_read_b128 v[220:223], v203 offset:35840
	ds_read_b128 v[232:235], v203 offset:36864
	ds_read_b128 v[236:239], v203 offset:37888
	ds_read_b128 v[240:243], v203 offset:38912
	ds_read_b128 v[244:247], v203 offset:39936
	global_load_lds_dwordx4 v[228:229], off
	v_lshl_add_u64 v[228:229], s[16:17], 0, v[168:169]
	s_mov_b32 m0, s22
	s_nop 0
	global_load_lds_dwordx4 v[228:229], off
	s_waitcnt vmcnt(8)
	s_waitcnt lgkmcnt(0)
	s_setprio 1
	s_barrier
	v_mfma_f32_16x16x32_bf16 v[140:143], v[80:83], v[208:211], v[140:143]
	v_mfma_f32_16x16x32_bf16 v[140:143], v[84:87], v[212:215], v[140:143]
	v_mfma_f32_16x16x32_bf16 v[132:135], v[88:91], v[208:211], v[132:135]
	v_mfma_f32_16x16x32_bf16 v[132:135], v[92:95], v[212:215], v[132:135]
	v_mfma_f32_16x16x32_bf16 v[124:127], v[80:83], v[216:219], v[124:127]
	v_mfma_f32_16x16x32_bf16 v[124:127], v[84:87], v[220:223], v[124:127]
	v_mfma_f32_16x16x32_bf16 v[120:123], v[88:91], v[216:219], v[120:123]
	v_mfma_f32_16x16x32_bf16 v[120:123], v[92:95], v[220:223], v[120:123]
	v_mfma_f32_16x16x32_bf16 v[108:111], v[80:83], v[232:235], v[108:111]
	v_mfma_f32_16x16x32_bf16 v[108:111], v[84:87], v[236:239], v[108:111]
	v_mfma_f32_16x16x32_bf16 v[104:107], v[88:91], v[232:235], v[104:107]
	v_mfma_f32_16x16x32_bf16 v[104:107], v[92:95], v[236:239], v[104:107]
	v_mfma_f32_16x16x32_bf16 v[76:79], v[80:83], v[240:243], v[76:79]
	v_mfma_f32_16x16x32_bf16 v[76:79], v[84:87], v[244:247], v[76:79]
	v_mfma_f32_16x16x32_bf16 v[72:75], v[88:91], v[240:243], v[72:75]
	v_mfma_f32_16x16x32_bf16 v[72:75], v[92:95], v[244:247], v[72:75]
	s_setprio 0
	s_setprio 1
	v_mfma_f32_16x16x32_bf16 v[136:139], v[144:147], v[208:211], v[136:139]
	v_mfma_f32_16x16x32_bf16 v[136:139], v[148:151], v[212:215], v[136:139]
	v_mfma_f32_16x16x32_bf16 v[128:131], v[152:155], v[208:211], v[128:131]
	v_mfma_f32_16x16x32_bf16 v[128:131], v[156:159], v[212:215], v[128:131]
	v_mfma_f32_16x16x32_bf16 v[116:119], v[144:147], v[216:219], v[116:119]
	v_mfma_f32_16x16x32_bf16 v[116:119], v[148:151], v[220:223], v[116:119]
	v_mfma_f32_16x16x32_bf16 v[112:115], v[152:155], v[216:219], v[112:115]
	v_mfma_f32_16x16x32_bf16 v[112:115], v[156:159], v[220:223], v[112:115]
	v_mfma_f32_16x16x32_bf16 v[100:103], v[144:147], v[232:235], v[100:103]
	v_mfma_f32_16x16x32_bf16 v[100:103], v[148:151], v[236:239], v[100:103]
	v_mfma_f32_16x16x32_bf16 v[96:99], v[152:155], v[232:235], v[96:99]
	v_mfma_f32_16x16x32_bf16 v[96:99], v[156:159], v[236:239], v[96:99]
	v_mfma_f32_16x16x32_bf16 v[68:71], v[144:147], v[240:243], v[68:71]
	v_mfma_f32_16x16x32_bf16 v[68:71], v[148:151], v[244:247], v[68:71]
	v_mfma_f32_16x16x32_bf16 v[64:67], v[152:155], v[240:243], v[64:67]
	v_mfma_f32_16x16x32_bf16 v[64:67], v[156:159], v[244:247], v[64:67]
	s_barrier
	s_setprio 0
	s_add_i32 s16, s49, s18
	v_lshl_add_u64 v[192:193], v[192:193], 0, s[76:77]
	s_mov_b32 m0, s16
	ds_read_b128 v[208:211], v203 offset:49152
	ds_read_b128 v[212:215], v203 offset:50176
	ds_read_b128 v[216:219], v203 offset:51200
	ds_read_b128 v[220:223], v203 offset:52224
	ds_read_b128 v[232:235], v203 offset:53248
	ds_read_b128 v[236:239], v203 offset:54272
	ds_read_b128 v[240:243], v203 offset:55296
	ds_read_b128 v[244:247], v203 offset:56320
	global_load_lds_dwordx4 v[192:193], off
	s_add_i32 m0, s16, 0x2000
	s_add_u32 s14, s14, 0x80080
	v_lshl_add_u64 v[192:193], v[248:249], 0, s[76:77]
	s_addc_u32 s15, s15, 0
	s_add_i32 s16, s50, s18
	global_load_lds_dwordx4 v[192:193], off
	v_lshl_add_u64 v[192:193], s[14:15], 0, v[166:167]
	s_mov_b32 m0, s16
	s_nop 0
	global_load_lds_dwordx4 v[192:193], off
	v_lshl_add_u64 v[192:193], s[14:15], 0, v[170:171]
	s_add_i32 m0, s16, 0x2000
	s_nop 0
	global_load_lds_dwordx4 v[192:193], off
	v_lshl_add_u64 v[192:193], v[250:251], 0, s[76:77]
	s_mov_b32 m0, s27
	s_nop 0
	global_load_lds_dwordx4 v[192:193], off
	v_lshl_add_u64 v[192:193], v[252:253], 0, s[76:77]
	s_mov_b32 m0, s28
	s_nop 0
	global_load_lds_dwordx4 v[192:193], off
	s_waitcnt vmcnt(8)
	s_waitcnt lgkmcnt(0)
	s_setprio 1
	s_barrier
	v_mfma_f32_16x16x32_bf16 v[60:63], v[80:83], v[208:211], v[60:63]
	v_mfma_f32_16x16x32_bf16 v[60:63], v[84:87], v[212:215], v[60:63]
	v_mfma_f32_16x16x32_bf16 v[56:59], v[88:91], v[208:211], v[56:59]
	v_mfma_f32_16x16x32_bf16 v[56:59], v[92:95], v[212:215], v[56:59]
	v_mfma_f32_16x16x32_bf16 v[44:47], v[80:83], v[216:219], v[44:47]
	v_mfma_f32_16x16x32_bf16 v[44:47], v[84:87], v[220:223], v[44:47]
	v_mfma_f32_16x16x32_bf16 v[40:43], v[88:91], v[216:219], v[40:43]
	v_mfma_f32_16x16x32_bf16 v[40:43], v[92:95], v[220:223], v[40:43]
	v_mfma_f32_16x16x32_bf16 v[28:31], v[80:83], v[232:235], v[28:31]
	v_mfma_f32_16x16x32_bf16 v[28:31], v[84:87], v[236:239], v[28:31]
	v_mfma_f32_16x16x32_bf16 v[24:27], v[88:91], v[232:235], v[24:27]
	v_mfma_f32_16x16x32_bf16 v[24:27], v[92:95], v[236:239], v[24:27]
	v_mfma_f32_16x16x32_bf16 v[12:15], v[80:83], v[240:243], v[12:15]
	v_mfma_f32_16x16x32_bf16 v[12:15], v[84:87], v[244:247], v[12:15]
	v_mfma_f32_16x16x32_bf16 v[8:11], v[88:91], v[240:243], v[8:11]
	v_mfma_f32_16x16x32_bf16 v[8:11], v[92:95], v[244:247], v[8:11]
	s_setprio 0
	s_setprio 1
	v_mfma_f32_16x16x32_bf16 v[52:55], v[144:147], v[208:211], v[52:55]
	v_mfma_f32_16x16x32_bf16 v[52:55], v[148:151], v[212:215], v[52:55]
	v_mfma_f32_16x16x32_bf16 v[48:51], v[152:155], v[208:211], v[48:51]
	v_mfma_f32_16x16x32_bf16 v[48:51], v[156:159], v[212:215], v[48:51]
	v_mfma_f32_16x16x32_bf16 v[36:39], v[144:147], v[216:219], v[36:39]
	v_mfma_f32_16x16x32_bf16 v[36:39], v[148:151], v[220:223], v[36:39]
	v_mfma_f32_16x16x32_bf16 v[32:35], v[152:155], v[216:219], v[32:35]
	v_mfma_f32_16x16x32_bf16 v[32:35], v[156:159], v[220:223], v[32:35]
	v_mfma_f32_16x16x32_bf16 v[20:23], v[144:147], v[232:235], v[20:23]
	v_mfma_f32_16x16x32_bf16 v[20:23], v[148:151], v[236:239], v[20:23]
	v_mfma_f32_16x16x32_bf16 v[16:19], v[152:155], v[232:235], v[16:19]
	v_mfma_f32_16x16x32_bf16 v[16:19], v[156:159], v[236:239], v[16:19]
	v_mfma_f32_16x16x32_bf16 v[4:7], v[144:147], v[240:243], v[4:7]
	v_mfma_f32_16x16x32_bf16 v[4:7], v[148:151], v[244:247], v[4:7]
	v_mfma_f32_16x16x32_bf16 v[0:3], v[152:155], v[240:243], v[0:3]
	v_mfma_f32_16x16x32_bf16 v[0:3], v[156:159], v[244:247], v[0:3]
	s_barrier
	s_setprio 0
	s_add_i32 s48, s48, 2
	s_add_u32 s10, s10, 0x100
	s_addc_u32 s11, s11, 0
	s_add_u32 s46, s46, 0x100
	s_addc_u32 s47, s47, 0
; #define PG8_STAGE(bufoff, gbase, voff) do { _Pragma("unroll") for (int _i = 0; _i < 2; ++_i) \
;         __builtin_amdgcn_global_load_lds((const unsigned*)((const char*)(gbase) + (voff)[_i]), (PG8_LAS unsigned*)(lds + (bufoff) + ldsw + _i * 8192), 16, 0, 0); } while (0)
; #define PG8_LDA(dst, b, h) do { _Pragma("unroll") for (int m = 0; m < 4; ++m) _Pragma("unroll") for (int k = 0; k < 2; ++k) dst[m][k] = *(const PG8_LAS bf16x8*)(lds + PG8_SA(b, h) + aoff + m * 2048 + k * 1024); } while (0)
; #define PG8_LDB(dst, b, h) do { _Pragma("unroll") for (int n = 0; n < 2; ++n) _Pragma("unroll") for (int k = 0; k < 2; ++k) dst[n][k] = *(const PG8_LAS bf16x8*)(lds + PG8_SB(b, h) + boff + n * 2048 + k * 1024); } while (0)
; #define PG8_MMA(ai, bj, At, Bt) do { __builtin_amdgcn_s_setprio(1); _Pragma("unroll") for (int m = 0; m < 4; ++m) _Pragma("unroll") for (int n = 0; n < 2; ++n) _Pragma("unroll") for (int k = 0; k < 2; ++k) \
;         acc[ai][bj][m][n] = __builtin_amdgcn_mfma_f32_16x16x32_bf16(Bt[n][k], At[m][k], acc[ai][bj][m][n], 0, 0, 0); __builtin_amdgcn_s_setprio(0); } while (0)
; #define PG8_WAIT_V(n) asm volatile("s_waitcnt vmcnt(" #n ")" ::: "memory")
; #define PG8_BAR __builtin_amdgcn_s_barrier()
; template <class Epi, class Sched, bool ALIGN_EPI = false, bool SP2 = false, bool DUAL = false>
; __device__ __forceinline__ void gemm_phase(PG8_LAS unsigned char* lds, const Gemm g, const Sched& S, const Epi& E) {
;     ...
;         for (int t = 0; t < nt; t += 2) {
;             const bool last = (t == nt - 2);
;             const char* a1 = cA + (size_t)(t + 1) * kstep;
;             const char* a2 = last ? nA : cA + (size_t)(t + 2) * kstep; const char* b2 = last ? nB : cB + (size_t)(t + 2) * kstep;
;             const char* a3 = a2 + kstep; const char* b3 = b2 + kstep;
;             if (last && has_next) S.a_ready(nxt);
;             if constexpr (SP2) {
;             PG8_LDB(B0, 0, 0); PG8_LDB(B1, 0, 1); PG8_SCHED; PG8_LDA(At, 0, 0); PG8_STAGE(PG8_SA(1, 1), a1 + hstep, voffA);
;             PG8_WAIT_V(8); PG8_WAIT_L(0); PG8_BAR; PG8_MMA(0, 0, At, B0); PG8_MMA(0, 1, At, B1); PG8_BAR; PG8_SCHED;
;             PG8_LDA(At, 0, 1); PG8_STAGE(PG8_SB(0, 0), b2, voffB); PG8_STAGE(PG8_SB(0, 1), b2 + hstep, voffB); PG8_STAGE(PG8_SA(0, 0), a2, voffA);
;             PG8_WAIT_V(8); PG8_WAIT_L(0); PG8_BAR; PG8_MMA(1, 0, At, B0); PG8_MMA(1, 1, At, B1); PG8_BAR; PG8_SCHED;
.LBB0_252:
	ds_read_b128 v[80:83], v199
	ds_read_b128 v[84:87], v199 offset:1024
	ds_read_b128 v[88:91], v199 offset:2048
	ds_read_b128 v[92:95], v199 offset:3072
	ds_read_b128 v[144:147], v202
	ds_read_b128 v[148:151], v202 offset:1024
	ds_read_b128 v[152:155], v202 offset:2048
	ds_read_b128 v[156:159], v202 offset:3072
	s_add_u32 s14, s10, 0xfff80080
	s_addc_u32 s15, s11, -1
	s_cmp_eq_u32 s48, 28
	s_cselect_b32 s17, s7, s15
	s_cselect_b32 s16, s9, s14
	s_cselect_b32 s15, s1, s47
	s_cselect_b32 s14, s45, s46
	v_lshl_add_u64 v[192:193], s[10:11], 0, v[186:187]
	s_add_i32 m0, s19, 0xc000
	ds_read_b128 v[208:211], v203
	ds_read_b128 v[212:215], v203 offset:1024
	ds_read_b128 v[216:219], v203 offset:2048
	ds_read_b128 v[220:223], v203 offset:3072
	ds_read_b128 v[232:235], v203 offset:4096
	ds_read_b128 v[236:239], v203 offset:5120
	ds_read_b128 v[240:243], v203 offset:6144
	ds_read_b128 v[244:247], v203 offset:7168
	global_load_lds_dwordx4 v[192:193], off
	v_lshl_add_u64 v[192:193], s[10:11], 0, v[188:189]
	s_add_i32 m0, s19, 0xe000
	s_nop 0
	global_load_lds_dwordx4 v[192:193], off
	s_waitcnt vmcnt(8)
	s_waitcnt lgkmcnt(0)
	s_setprio 1
	s_barrier
	v_mfma_f32_16x16x32_bf16 v[140:143], v[80:83], v[208:211], v[140:143]
	v_mfma_f32_16x16x32_bf16 v[140:143], v[84:87], v[212:215], v[140:143]
	v_mfma_f32_16x16x32_bf16 v[132:135], v[88:91], v[208:211], v[132:135]
	v_mfma_f32_16x16x32_bf16 v[132:135], v[92:95], v[212:215], v[132:135]
	v_mfma_f32_16x16x32_bf16 v[124:127], v[80:83], v[216:219], v[124:127]
	v_mfma_f32_16x16x32_bf16 v[124:127], v[84:87], v[220:223], v[124:127]
	v_mfma_f32_16x16x32_bf16 v[120:123], v[88:91], v[216:219], v[120:123]
	v_mfma_f32_16x16x32_bf16 v[120:123], v[92:95], v[220:223], v[120:123]
	v_mfma_f32_16x16x32_bf16 v[108:111], v[80:83], v[232:235], v[108:111]
	v_mfma_f32_16x16x32_bf16 v[108:111], v[84:87], v[236:239], v[108:111]
	v_mfma_f32_16x16x32_bf16 v[104:107], v[88:91], v[232:235], v[104:107]
	v_mfma_f32_16x16x32_bf16 v[104:107], v[92:95], v[236:239], v[104:107]
	v_mfma_f32_16x16x32_bf16 v[76:79], v[80:83], v[240:243], v[76:79]
	v_mfma_f32_16x16x32_bf16 v[76:79], v[84:87], v[244:247], v[76:79]
	v_mfma_f32_16x16x32_bf16 v[72:75], v[88:91], v[240:243], v[72:75]
	v_mfma_f32_16x16x32_bf16 v[72:75], v[92:95], v[244:247], v[72:75]
	s_setprio 0
	s_setprio 1
	v_mfma_f32_16x16x32_bf16 v[136:139], v[144:147], v[208:211], v[136:139]
	v_mfma_f32_16x16x32_bf16 v[136:139], v[148:151], v[212:215], v[136:139]
	v_mfma_f32_16x16x32_bf16 v[128:131], v[152:155], v[208:211], v[128:131]
	v_mfma_f32_16x16x32_bf16 v[128:131], v[156:159], v[212:215], v[128:131]
	v_mfma_f32_16x16x32_bf16 v[116:119], v[144:147], v[216:219], v[116:119]
	v_mfma_f32_16x16x32_bf16 v[116:119], v[148:151], v[220:223], v[116:119]
	v_mfma_f32_16x16x32_bf16 v[112:115], v[152:155], v[216:219], v[112:115]
	v_mfma_f32_16x16x32_bf16 v[112:115], v[156:159], v[220:223], v[112:115]
	v_mfma_f32_16x16x32_bf16 v[100:103], v[144:147], v[232:235], v[100:103]
	v_mfma_f32_16x16x32_bf16 v[100:103], v[148:151], v[236:239], v[100:103]
	v_mfma_f32_16x16x32_bf16 v[96:99], v[152:155], v[232:235], v[96:99]
	v_mfma_f32_16x16x32_bf16 v[96:99], v[156:159], v[236:239], v[96:99]
	v_mfma_f32_16x16x32_bf16 v[68:71], v[144:147], v[240:243], v[68:71]
	v_mfma_f32_16x16x32_bf16 v[68:71], v[148:151], v[244:247], v[68:71]
	v_mfma_f32_16x16x32_bf16 v[64:67], v[152:155], v[240:243], v[64:67]
	v_mfma_f32_16x16x32_bf16 v[64:67], v[156:159], v[244:247], v[64:67]
	s_barrier
	s_setprio 0
	s_add_i32 s49, s31, s18
	v_lshl_add_u64 v[192:193], s[14:15], 0, v[166:167]
	s_mov_b32 m0, s49
	ds_read_b128 v[208:211], v203 offset:16384
	ds_read_b128 v[212:215], v203 offset:17408
	ds_read_b128 v[216:219], v203 offset:18432
	ds_read_b128 v[220:223], v203 offset:19456
	ds_read_b128 v[232:235], v203 offset:20480
	ds_read_b128 v[236:239], v203 offset:21504
	ds_read_b128 v[240:243], v203 offset:22528
	ds_read_b128 v[244:247], v203 offset:23552
	global_load_lds_dwordx4 v[192:193], off
	s_add_i32 m0, s49, 0x2000
	s_add_u32 s50, s14, 0x80000
	v_lshl_add_u64 v[248:249], s[14:15], 0, v[170:171]
	s_addc_u32 s51, s15, 0
	s_add_i32 s49, s34, s18
	global_load_lds_dwordx4 v[248:249], off
	v_lshl_add_u64 v[250:251], s[50:51], 0, v[166:167]
	s_mov_b32 m0, s49
	v_lshl_add_u64 v[252:253], s[16:17], 0, v[168:169]
	global_load_lds_dwordx4 v[250:251], off
	v_lshl_add_u64 v[250:251], s[50:51], 0, v[170:171]
	s_add_i32 m0, s49, 0x2000
	s_nop 0
	global_load_lds_dwordx4 v[250:251], off
	v_lshl_add_u64 v[250:251], s[16:17], 0, v[164:165]
	s_mov_b32 m0, s19
	s_nop 0
	global_load_lds_dwordx4 v[250:251], off
	s_mov_b32 m0, s20
	s_nop 0
	global_load_lds_dwordx4 v[252:253], off
	s_waitcnt vmcnt(8)
	s_waitcnt lgkmcnt(0)
	s_setprio 1
	s_barrier
; #define PG8_STAGE(bufoff, gbase, voff) do { _Pragma("unroll") for (int _i = 0; _i < 2; ++_i) \
;         __builtin_amdgcn_global_load_lds((const unsigned*)((const char*)(gbase) + (voff)[_i]), (PG8_LAS unsigned*)(lds + (bufoff) + ldsw + _i * 8192), 16, 0, 0); } while (0)
; #define PG8_LDA(dst, b, h) do { _Pragma("unroll") for (int m = 0; m < 4; ++m) _Pragma("unroll") for (int k = 0; k < 2; ++k) dst[m][k] = *(const PG8_LAS bf16x8*)(lds + PG8_SA(b, h) + aoff + m * 2048 + k * 1024); } while (0)
; #define PG8_LDB(dst, b, h) do { _Pragma("unroll") for (int n = 0; n < 2; ++n) _Pragma("unroll") for (int k = 0; k < 2; ++k) dst[n][k] = *(const PG8_LAS bf16x8*)(lds + PG8_SB(b, h) + boff + n * 2048 + k * 1024); } while (0)
; #define PG8_MMA(ai, bj, At, Bt) do { __builtin_amdgcn_s_setprio(1); _Pragma("unroll") for (int m = 0; m < 4; ++m) _Pragma("unroll") for (int n = 0; n < 2; ++n) _Pragma("unroll") for (int k = 0; k < 2; ++k) \
;         acc[ai][bj][m][n] = __builtin_amdgcn_mfma_f32_16x16x32_bf16(Bt[n][k], At[m][k], acc[ai][bj][m][n], 0, 0, 0); __builtin_amdgcn_s_setprio(0); } while (0)
; #define PG8_WAIT_V(n) asm volatile("s_waitcnt vmcnt(" #n ")" ::: "memory")
; #define PG8_WAIT_L(n) asm volatile("s_waitcnt lgkmcnt(" #n ")" ::: "memory")
; #define PG8_BAR __builtin_amdgcn_s_barrier()
; #define PG8_SCHED __builtin_amdgcn_sched_barrier(0)
; template <class Epi, class Sched, bool ALIGN_EPI = false, bool SP2 = false, bool DUAL = false>
; __device__ __forceinline__ void gemm_phase(PG8_LAS unsigned char* lds, const Gemm g, const Sched& S, const Epi& E) {
;     ...
;             PG8_WAIT_V(8); PG8_WAIT_L(0); PG8_BAR; PG8_MMA(0, 0, At, B0); PG8_MMA(0, 1, At, B1); PG8_BAR; PG8_SCHED;
;             PG8_LDA(At, 0, 1); PG8_STAGE(PG8_SB(0, 0), b2, voffB); PG8_STAGE(PG8_SB(0, 1), b2 + hstep, voffB); PG8_STAGE(PG8_SA(0, 0), a2, voffA);
;             PG8_WAIT_V(8); PG8_WAIT_L(0); PG8_BAR; PG8_MMA(1, 0, At, B0); PG8_MMA(1, 1, At, B1); PG8_BAR; PG8_SCHED;
;             PG8_LDB(B0, 1, 0); PG8_LDB(B1, 1, 1); PG8_SCHED; PG8_LDA(At, 1, 0); PG8_STAGE(PG8_SA(0, 1), a2 + hstep, voffA);
;             PG8_WAIT_V(8); PG8_WAIT_L(0); PG8_BAR; PG8_MMA(0, 0, At, B0); PG8_MMA(0, 1, At, B1); PG8_BAR; PG8_SCHED;
	v_mfma_f32_16x16x32_bf16 v[60:63], v[80:83], v[208:211], v[60:63]
	v_mfma_f32_16x16x32_bf16 v[60:63], v[84:87], v[212:215], v[60:63]
	v_mfma_f32_16x16x32_bf16 v[56:59], v[88:91], v[208:211], v[56:59]
	v_mfma_f32_16x16x32_bf16 v[56:59], v[92:95], v[212:215], v[56:59]
	v_mfma_f32_16x16x32_bf16 v[44:47], v[80:83], v[216:219], v[44:47]
	v_mfma_f32_16x16x32_bf16 v[44:47], v[84:87], v[220:223], v[44:47]
	v_mfma_f32_16x16x32_bf16 v[40:43], v[88:91], v[216:219], v[40:43]
	v_mfma_f32_16x16x32_bf16 v[40:43], v[92:95], v[220:223], v[40:43]
	v_mfma_f32_16x16x32_bf16 v[28:31], v[80:83], v[232:235], v[28:31]
	v_mfma_f32_16x16x32_bf16 v[28:31], v[84:87], v[236:239], v[28:31]
	v_mfma_f32_16x16x32_bf16 v[24:27], v[88:91], v[232:235], v[24:27]
	v_mfma_f32_16x16x32_bf16 v[24:27], v[92:95], v[236:239], v[24:27]
	v_mfma_f32_16x16x32_bf16 v[12:15], v[80:83], v[240:243], v[12:15]
	v_mfma_f32_16x16x32_bf16 v[12:15], v[84:87], v[244:247], v[12:15]
	v_mfma_f32_16x16x32_bf16 v[8:11], v[88:91], v[240:243], v[8:11]
	v_mfma_f32_16x16x32_bf16 v[8:11], v[92:95], v[244:247], v[8:11]
	s_setprio 0
	s_setprio 1
	v_mfma_f32_16x16x32_bf16 v[52:55], v[144:147], v[208:211], v[52:55]
	v_mfma_f32_16x16x32_bf16 v[52:55], v[148:151], v[212:215], v[52:55]
	v_mfma_f32_16x16x32_bf16 v[48:51], v[152:155], v[208:211], v[48:51]
	v_mfma_f32_16x16x32_bf16 v[48:51], v[156:159], v[212:215], v[48:51]
	v_mfma_f32_16x16x32_bf16 v[36:39], v[144:147], v[216:219], v[36:39]
	v_mfma_f32_16x16x32_bf16 v[36:39], v[148:151], v[220:223], v[36:39]
	v_mfma_f32_16x16x32_bf16 v[32:35], v[152:155], v[216:219], v[32:35]
	v_mfma_f32_16x16x32_bf16 v[32:35], v[156:159], v[220:223], v[32:35]
	v_mfma_f32_16x16x32_bf16 v[20:23], v[144:147], v[232:235], v[20:23]
	v_mfma_f32_16x16x32_bf16 v[20:23], v[148:151], v[236:239], v[20:23]
	v_mfma_f32_16x16x32_bf16 v[16:19], v[152:155], v[232:235], v[16:19]
	v_mfma_f32_16x16x32_bf16 v[16:19], v[156:159], v[236:239], v[16:19]
	v_mfma_f32_16x16x32_bf16 v[4:7], v[144:147], v[240:243], v[4:7]
	v_mfma_f32_16x16x32_bf16 v[4:7], v[148:151], v[244:247], v[4:7]
	v_mfma_f32_16x16x32_bf16 v[0:3], v[152:155], v[240:243], v[0:3]
	v_mfma_f32_16x16x32_bf16 v[0:3], v[156:159], v[244:247], v[0:3]
	s_barrier
	s_setprio 0
	s_add_i32 s49, 0, 0x18000
	s_add_i32 s50, 0, 0x1c000
	v_add_u32_e32 v92, s49, v196
	v_add_u32_e32 v156, s50, v196
	ds_read_b128 v[80:83], v92
	ds_read_b128 v[84:87], v92 offset:1024
	ds_read_b128 v[88:91], v92 offset:2048
	ds_read_b128 v[92:95], v92 offset:3072
	ds_read_b128 v[144:147], v156
	ds_read_b128 v[148:151], v156 offset:1024
	ds_read_b128 v[152:155], v156 offset:2048
	ds_read_b128 v[156:159], v156 offset:3072
	s_add_u32 s16, s16, 0x80000
	s_addc_u32 s17, s17, 0
	s_mov_b32 m0, s21
	v_lshl_add_u64 v[228:229], s[16:17], 0, v[164:165]
	ds_read_b128 v[208:211], v203 offset:32768
	ds_read_b128 v[212:215], v203 offset:33792
	ds_read_b128 v[216:219], v203 offset:34816
	ds_read_b128 v[220:223], v203 offset:35840
	ds_read_b128 v[232:235], v203 offset:36864
	ds_read_b128 v[236:239], v203 offset:37888
	ds_read_b128 v[240:243], v203 offset:38912
	ds_read_b128 v[244:247], v203 offset:39936
	global_load_lds_dwordx4 v[228:229], off
	v_lshl_add_u64 v[228:229], s[16:17], 0, v[168:169]
	s_mov_b32 m0, s22
	s_nop 0
	global_load_lds_dwordx4 v[228:229], off
	s_waitcnt vmcnt(8)
	s_waitcnt lgkmcnt(0)
	s_setprio 1
	s_barrier
	v_mfma_f32_16x16x32_bf16 v[140:143], v[80:83], v[208:211], v[140:143]
	v_mfma_f32_16x16x32_bf16 v[140:143], v[84:87], v[212:215], v[140:143]
	v_mfma_f32_16x16x32_bf16 v[132:135], v[88:91], v[208:211], v[132:135]
	v_mfma_f32_16x16x32_bf16 v[132:135], v[92:95], v[212:215], v[132:135]
	v_mfma_f32_16x16x32_bf16 v[124:127], v[80:83], v[216:219], v[124:127]
	v_mfma_f32_16x16x32_bf16 v[124:127], v[84:87], v[220:223], v[124:127]
	v_mfma_f32_16x16x32_bf16 v[120:123], v[88:91], v[216:219], v[120:123]
	v_mfma_f32_16x16x32_bf16 v[120:123], v[92:95], v[220:223], v[120:123]
	v_mfma_f32_16x16x32_bf16 v[108:111], v[80:83], v[232:235], v[108:111]
	v_mfma_f32_16x16x32_bf16 v[108:111], v[84:87], v[236:239], v[108:111]
	v_mfma_f32_16x16x32_bf16 v[104:107], v[88:91], v[232:235], v[104:107]
	v_mfma_f32_16x16x32_bf16 v[104:107], v[92:95], v[236:239], v[104:107]
	v_mfma_f32_16x16x32_bf16 v[76:79], v[80:83], v[240:243], v[76:79]
	v_mfma_f32_16x16x32_bf16 v[76:79], v[84:87], v[244:247], v[76:79]
	v_mfma_f32_16x16x32_bf16 v[72:75], v[88:91], v[240:243], v[72:75]
	v_mfma_f32_16x16x32_bf16 v[72:75], v[92:95], v[244:247], v[72:75]
	s_setprio 0
	s_setprio 1
	v_mfma_f32_16x16x32_bf16 v[136:139], v[144:147], v[208:211], v[136:139]
	v_mfma_f32_16x16x32_bf16 v[136:139], v[148:151], v[212:215], v[136:139]
	v_mfma_f32_16x16x32_bf16 v[128:131], v[152:155], v[208:211], v[128:131]
	v_mfma_f32_16x16x32_bf16 v[128:131], v[156:159], v[212:215], v[128:131]
	v_mfma_f32_16x16x32_bf16 v[116:119], v[144:147], v[216:219], v[116:119]
	v_mfma_f32_16x16x32_bf16 v[116:119], v[148:151], v[220:223], v[116:119]
	v_mfma_f32_16x16x32_bf16 v[112:115], v[152:155], v[216:219], v[112:115]
	v_mfma_f32_16x16x32_bf16 v[112:115], v[156:159], v[220:223], v[112:115]
	v_mfma_f32_16x16x32_bf16 v[100:103], v[144:147], v[232:235], v[100:103]
	v_mfma_f32_16x16x32_bf16 v[100:103], v[148:151], v[236:239], v[100:103]
	v_mfma_f32_16x16x32_bf16 v[96:99], v[152:155], v[232:235], v[96:99]
	v_mfma_f32_16x16x32_bf16 v[96:99], v[156:159], v[236:239], v[96:99]
	v_mfma_f32_16x16x32_bf16 v[68:71], v[144:147], v[240:243], v[68:71]
	v_mfma_f32_16x16x32_bf16 v[68:71], v[148:151], v[244:247], v[68:71]
	v_mfma_f32_16x16x32_bf16 v[64:67], v[152:155], v[240:243], v[64:67]
	v_mfma_f32_16x16x32_bf16 v[64:67], v[156:159], v[244:247], v[64:67]
	s_barrier
; #define PG8_STAGE(bufoff, gbase, voff) do { _Pragma("unroll") for (int _i = 0; _i < 2; ++_i) \
;         __builtin_amdgcn_global_load_lds((const unsigned*)((const char*)(gbase) + (voff)[_i]), (PG8_LAS unsigned*)(lds + (bufoff) + ldsw + _i * 8192), 16, 0, 0); } while (0)
; #define PG8_LDA(dst, b, h) do { _Pragma("unroll") for (int m = 0; m < 4; ++m) _Pragma("unroll") for (int k = 0; k < 2; ++k) dst[m][k] = *(const PG8_LAS bf16x8*)(lds + PG8_SA(b, h) + aoff + m * 2048 + k * 1024); } while (0)
; #define PG8_MMA(ai, bj, At, Bt) do { __builtin_amdgcn_s_setprio(1); _Pragma("unroll") for (int m = 0; m < 4; ++m) _Pragma("unroll") for (int n = 0; n < 2; ++n) _Pragma("unroll") for (int k = 0; k < 2; ++k) \
;         acc[ai][bj][m][n] = __builtin_amdgcn_mfma_f32_16x16x32_bf16(Bt[n][k], At[m][k], acc[ai][bj][m][n], 0, 0, 0); __builtin_amdgcn_s_setprio(0); } while (0)
; #define PG8_WAIT_V(n) asm volatile("s_waitcnt vmcnt(" #n ")" ::: "memory")
; #define PG8_WAIT_L(n) asm volatile("s_waitcnt lgkmcnt(" #n ")" ::: "memory")
; #define PG8_BAR __builtin_amdgcn_s_barrier()
; #define PG8_SCHED __builtin_amdgcn_sched_barrier(0)
; template <class Epi, class Sched, bool ALIGN_EPI = false, bool SP2 = false, bool DUAL = false>
; __device__ __forceinline__ void gemm_phase(PG8_LAS unsigned char* lds, const Gemm g, const Sched& S, const Epi& E) {
;     ...
;             PG8_LDA(At, 1, 1); PG8_STAGE(PG8_SB(1, 0), b3, voffB); PG8_STAGE(PG8_SB(1, 1), b3 + hstep, voffB); PG8_STAGE(PG8_SA(1, 0), a3, voffA);
;             PG8_WAIT_V(8); PG8_WAIT_L(0); PG8_BAR; PG8_MMA(1, 0, At, B0); PG8_MMA(1, 1, At, B1); PG8_BAR; PG8_SCHED;
;     ...
;         if constexpr (ALIGN_EPI) { if (wr == 0) PG8_BAR; }
	s_setprio 0
	s_add_i32 s16, s49, s18
	v_lshl_add_u64 v[192:193], v[192:193], 0, s[76:77]
	s_mov_b32 m0, s16
	ds_read_b128 v[208:211], v203 offset:49152
	ds_read_b128 v[212:215], v203 offset:50176
	ds_read_b128 v[216:219], v203 offset:51200
	ds_read_b128 v[220:223], v203 offset:52224
	ds_read_b128 v[232:235], v203 offset:53248
	ds_read_b128 v[236:239], v203 offset:54272
	ds_read_b128 v[240:243], v203 offset:55296
	ds_read_b128 v[244:247], v203 offset:56320
	global_load_lds_dwordx4 v[192:193], off
	s_add_i32 m0, s16, 0x2000
	s_add_u32 s14, s14, 0x80080
	v_lshl_add_u64 v[192:193], v[248:249], 0, s[76:77]
	s_addc_u32 s15, s15, 0
	s_add_i32 s16, s50, s18
	global_load_lds_dwordx4 v[192:193], off
	v_lshl_add_u64 v[192:193], s[14:15], 0, v[166:167]
	s_mov_b32 m0, s16
	s_nop 0
	global_load_lds_dwordx4 v[192:193], off
	v_lshl_add_u64 v[192:193], s[14:15], 0, v[170:171]
	s_add_i32 m0, s16, 0x2000
	s_nop 0
	global_load_lds_dwordx4 v[192:193], off
	v_lshl_add_u64 v[192:193], v[250:251], 0, s[76:77]
	s_mov_b32 m0, s27
	s_nop 0
	global_load_lds_dwordx4 v[192:193], off
	v_lshl_add_u64 v[192:193], v[252:253], 0, s[76:77]
	s_mov_b32 m0, s28
	s_nop 0
	global_load_lds_dwordx4 v[192:193], off
	s_waitcnt vmcnt(8)
	s_waitcnt lgkmcnt(0)
	s_setprio 1
	s_barrier
	v_mfma_f32_16x16x32_bf16 v[60:63], v[80:83], v[208:211], v[60:63]
	v_mfma_f32_16x16x32_bf16 v[60:63], v[84:87], v[212:215], v[60:63]
	v_mfma_f32_16x16x32_bf16 v[56:59], v[88:91], v[208:211], v[56:59]
	v_mfma_f32_16x16x32_bf16 v[56:59], v[92:95], v[212:215], v[56:59]
	v_mfma_f32_16x16x32_bf16 v[44:47], v[80:83], v[216:219], v[44:47]
	v_mfma_f32_16x16x32_bf16 v[44:47], v[84:87], v[220:223], v[44:47]
	v_mfma_f32_16x16x32_bf16 v[40:43], v[88:91], v[216:219], v[40:43]
	v_mfma_f32_16x16x32_bf16 v[40:43], v[92:95], v[220:223], v[40:43]
	v_mfma_f32_16x16x32_bf16 v[28:31], v[80:83], v[232:235], v[28:31]
	v_mfma_f32_16x16x32_bf16 v[28:31], v[84:87], v[236:239], v[28:31]
	v_mfma_f32_16x16x32_bf16 v[24:27], v[88:91], v[232:235], v[24:27]
	v_mfma_f32_16x16x32_bf16 v[24:27], v[92:95], v[236:239], v[24:27]
	v_mfma_f32_16x16x32_bf16 v[12:15], v[80:83], v[240:243], v[12:15]
	v_mfma_f32_16x16x32_bf16 v[12:15], v[84:87], v[244:247], v[12:15]
	v_mfma_f32_16x16x32_bf16 v[8:11], v[88:91], v[240:243], v[8:11]
	v_mfma_f32_16x16x32_bf16 v[8:11], v[92:95], v[244:247], v[8:11]
	s_setprio 0
	s_setprio 1
	v_mfma_f32_16x16x32_bf16 v[52:55], v[144:147], v[208:211], v[52:55]
	v_mfma_f32_16x16x32_bf16 v[52:55], v[148:151], v[212:215], v[52:55]
	v_mfma_f32_16x16x32_bf16 v[48:51], v[152:155], v[208:211], v[48:51]
	v_mfma_f32_16x16x32_bf16 v[48:51], v[156:159], v[212:215], v[48:51]
	v_mfma_f32_16x16x32_bf16 v[36:39], v[144:147], v[216:219], v[36:39]
	v_mfma_f32_16x16x32_bf16 v[36:39], v[148:151], v[220:223], v[36:39]
	v_mfma_f32_16x16x32_bf16 v[32:35], v[152:155], v[216:219], v[32:35]
	v_mfma_f32_16x16x32_bf16 v[32:35], v[156:159], v[220:223], v[32:35]
	v_mfma_f32_16x16x32_bf16 v[20:23], v[144:147], v[232:235], v[20:23]
	v_mfma_f32_16x16x32_bf16 v[20:23], v[148:151], v[236:239], v[20:23]
	v_mfma_f32_16x16x32_bf16 v[16:19], v[152:155], v[232:235], v[16:19]
	v_mfma_f32_16x16x32_bf16 v[16:19], v[156:159], v[236:239], v[16:19]
	v_mfma_f32_16x16x32_bf16 v[4:7], v[144:147], v[240:243], v[4:7]
	v_mfma_f32_16x16x32_bf16 v[4:7], v[148:151], v[244:247], v[4:7]
	v_mfma_f32_16x16x32_bf16 v[0:3], v[152:155], v[240:243], v[0:3]
	v_mfma_f32_16x16x32_bf16 v[0:3], v[156:159], v[244:247], v[0:3]
	s_barrier
	s_setprio 0
	s_add_i32 s48, s48, 2
	s_add_u32 s10, s10, 0x100
	s_addc_u32 s11, s11, 0
	s_add_u32 s46, s46, 0x100
	s_addc_u32 s47, s47, 0
	s_cmp_gt_u32 s48, 29
	s_cbranch_scc0 .LBB0_252
	s_and_b64 vcc, exec, s[38:39]
	s_cbranch_vccz .LBB0_255
	s_barrier

; #define PG8_STAGE(bufoff, gbase, voff) do { _Pragma("unroll") for (int _i = 0; _i < 2; ++_i) \
;         __builtin_amdgcn_global_load_lds((const unsigned*)((const char*)(gbase) + (voff)[_i]), (PG8_LAS unsigned*)(lds + (bufoff) + ldsw + _i * 8192), 16, 0, 0); } while (0)
; #define PG8_LDA(dst, b, h) do { _Pragma("unroll") for (int m = 0; m < 4; ++m) _Pragma("unroll") for (int k = 0; k < 2; ++k) dst[m][k] = *(const PG8_LAS bf16x8*)(lds + PG8_SA(b, h) + aoff + m * 2048 + k * 1024); } while (0)
; #define PG8_LDB(dst, b, h) do { _Pragma("unroll") for (int n = 0; n < 2; ++n) _Pragma("unroll") for (int k = 0; k < 2; ++k) dst[n][k] = *(const PG8_LAS bf16x8*)(lds + PG8_SB(b, h) + boff + n * 2048 + k * 1024); } while (0)
; #define PG8_MMA(ai, bj, At, Bt) do { __builtin_amdgcn_s_setprio(1); _Pragma("unroll") for (int m = 0; m < 4; ++m) _Pragma("unroll") for (int n = 0; n < 2; ++n) _Pragma("unroll") for (int k = 0; k < 2; ++k) \
;         acc[ai][bj][m][n] = __builtin_amdgcn_mfma_f32_16x16x32_bf16(Bt[n][k], At[m][k], acc[ai][bj][m][n], 0, 0, 0); __builtin_amdgcn_s_setprio(0); } while (0)
; #define PG8_WAIT_V(n) asm volatile("s_waitcnt vmcnt(" #n ")" ::: "memory")
; #define PG8_BAR __builtin_amdgcn_s_barrier()
; template <class Epi, class Sched, bool ALIGN_EPI = false, bool SP2 = false, bool DUAL = false>
; __device__ __forceinline__ void gemm_phase(PG8_LAS unsigned char* lds, const Gemm g, const Sched& S, const Epi& E) {
;     ...
;         for (int t = 0; t < nt; t += 2) {
;             const bool last = (t == nt - 2);
;             const char* a1 = cA + (size_t)(t + 1) * kstep;
;             const char* a2 = last ? nA : cA + (size_t)(t + 2) * kstep; const char* b2 = last ? nB : cB + (size_t)(t + 2) * kstep;
;             const char* a3 = a2 + kstep; const char* b3 = b2 + kstep;
;             if (last && has_next) S.a_ready(nxt);
;             if constexpr (SP2) {
;             PG8_LDB(B0, 0, 0); PG8_LDB(B1, 0, 1); PG8_SCHED; PG8_LDA(At, 0, 0); PG8_STAGE(PG8_SA(1, 1), a1 + hstep, voffA);
;             PG8_WAIT_V(8); PG8_WAIT_L(0); PG8_BAR; PG8_MMA(0, 0, At, B0); PG8_MMA(0, 1, At, B1); PG8_BAR; PG8_SCHED;
;             PG8_LDA(At, 0, 1); PG8_STAGE(PG8_SB(0, 0), b2, voffB); PG8_STAGE(PG8_SB(0, 1), b2 + hstep, voffB); PG8_STAGE(PG8_SA(0, 0), a2, voffA);
;             PG8_WAIT_V(8); PG8_WAIT_L(0); PG8_BAR; PG8_MMA(1, 0, At, B0); PG8_MMA(1, 1, At, B1); PG8_BAR; PG8_SCHED;
.LBB0_805:
	v_add_u32_e32 v1, s44, v235
	ds_read_b128 v[132:135], v1
	ds_read_b128 v[136:139], v1 offset:1024
	ds_read_b128 v[140:143], v1 offset:2048
	ds_read_b128 v[144:147], v1 offset:3072
	v_add_u32_e32 v1, s45, v235
	ds_read_b128 v[148:151], v1
	ds_read_b128 v[152:155], v1 offset:1024
	ds_read_b128 v[156:159], v1 offset:2048
	ds_read_b128 v[160:163], v1 offset:3072
	s_add_u32 s16, s14, 0xfff80080
	s_addc_u32 s17, s15, -1
	s_cmp_eq_u32 s75, 28
	s_cselect_b32 s19, s50, s17
	s_cselect_b32 s18, s51, s16
	s_cselect_b32 s17, s65, s73
	s_cselect_b32 s16, s67, s72
	v_lshl_add_u64 v[2:3], s[14:15], 0, v[192:193]
	s_add_i32 m0, s28, 0xc000
	ds_read_b128 v[164:167], v237
	ds_read_b128 v[168:171], v237 offset:1024
	ds_read_b128 v[172:175], v237 offset:2048
	ds_read_b128 v[176:179], v237 offset:3072
	ds_read_b128 v[180:183], v237 offset:4096
	ds_read_b128 v[202:205], v237 offset:5120
	ds_read_b128 v[206:209], v237 offset:6144
	ds_read_b128 v[210:213], v237 offset:7168
	global_load_lds_dwordx4 v[2:3], off
	v_lshl_add_u64 v[2:3], s[14:15], 0, v[194:195]
	s_add_i32 m0, s28, 0xe000
	s_nop 0
	global_load_lds_dwordx4 v[2:3], off
	s_waitcnt vmcnt(8)
	s_waitcnt lgkmcnt(0)
	s_setprio 1
	s_barrier
	v_mfma_f32_16x16x32_bf16 v[128:131], v[132:135], v[164:167], v[128:131]
	v_mfma_f32_16x16x32_bf16 v[128:131], v[136:139], v[168:171], v[128:131]
	v_mfma_f32_16x16x32_bf16 v[124:127], v[140:143], v[164:167], v[124:127]
	v_mfma_f32_16x16x32_bf16 v[124:127], v[144:147], v[168:171], v[124:127]
	v_mfma_f32_16x16x32_bf16 v[120:123], v[132:135], v[172:175], v[120:123]
	v_mfma_f32_16x16x32_bf16 v[120:123], v[136:139], v[176:179], v[120:123]
	v_mfma_f32_16x16x32_bf16 v[116:119], v[140:143], v[172:175], v[116:119]
	v_mfma_f32_16x16x32_bf16 v[116:119], v[144:147], v[176:179], v[116:119]
	v_mfma_f32_16x16x32_bf16 v[112:115], v[132:135], v[180:183], v[112:115]
	v_mfma_f32_16x16x32_bf16 v[112:115], v[136:139], v[202:205], v[112:115]
	v_mfma_f32_16x16x32_bf16 v[108:111], v[140:143], v[180:183], v[108:111]
	v_mfma_f32_16x16x32_bf16 v[108:111], v[144:147], v[202:205], v[108:111]
	v_mfma_f32_16x16x32_bf16 v[104:107], v[132:135], v[206:209], v[104:107]
	v_mfma_f32_16x16x32_bf16 v[104:107], v[136:139], v[210:213], v[104:107]
	v_mfma_f32_16x16x32_bf16 v[100:103], v[140:143], v[206:209], v[100:103]
	v_mfma_f32_16x16x32_bf16 v[100:103], v[144:147], v[210:213], v[100:103]
	s_setprio 0
	s_setprio 1
	v_mfma_f32_16x16x32_bf16 v[96:99], v[148:151], v[164:167], v[96:99]
	v_mfma_f32_16x16x32_bf16 v[96:99], v[152:155], v[168:171], v[96:99]
	v_mfma_f32_16x16x32_bf16 v[92:95], v[156:159], v[164:167], v[92:95]
	v_mfma_f32_16x16x32_bf16 v[92:95], v[160:163], v[168:171], v[92:95]
	v_mfma_f32_16x16x32_bf16 v[88:91], v[148:151], v[172:175], v[88:91]
	v_mfma_f32_16x16x32_bf16 v[88:91], v[152:155], v[176:179], v[88:91]
	v_mfma_f32_16x16x32_bf16 v[84:87], v[156:159], v[172:175], v[84:87]
	v_mfma_f32_16x16x32_bf16 v[84:87], v[160:163], v[176:179], v[84:87]
	v_mfma_f32_16x16x32_bf16 v[80:83], v[148:151], v[180:183], v[80:83]
	v_mfma_f32_16x16x32_bf16 v[80:83], v[152:155], v[202:205], v[80:83]
	v_mfma_f32_16x16x32_bf16 v[76:79], v[156:159], v[180:183], v[76:79]
	v_mfma_f32_16x16x32_bf16 v[76:79], v[160:163], v[202:205], v[76:79]
	v_mfma_f32_16x16x32_bf16 v[72:75], v[148:151], v[206:209], v[72:75]
	v_mfma_f32_16x16x32_bf16 v[72:75], v[152:155], v[210:213], v[72:75]
	v_mfma_f32_16x16x32_bf16 v[68:71], v[156:159], v[206:209], v[68:71]
	v_mfma_f32_16x16x32_bf16 v[68:71], v[160:163], v[210:213], v[68:71]
	s_barrier
	s_setprio 0
	s_add_i32 s76, s44, s27
	v_lshl_add_u64 v[214:215], s[16:17], 0, v[186:187]
	s_mov_b32 m0, s76
	ds_read_b128 v[164:167], v237 offset:16384
	ds_read_b128 v[168:171], v237 offset:17408
	ds_read_b128 v[172:175], v237 offset:18432
	ds_read_b128 v[176:179], v237 offset:19456
	ds_read_b128 v[180:183], v237 offset:20480
	ds_read_b128 v[202:205], v237 offset:21504
	ds_read_b128 v[206:209], v237 offset:22528
	ds_read_b128 v[210:213], v237 offset:23552
	global_load_lds_dwordx4 v[214:215], off
	s_add_i32 m0, s76, 0x2000
	s_add_u32 s76, s16, 0x80000
	v_lshl_add_u64 v[216:217], s[16:17], 0, v[190:191]
	s_addc_u32 s77, s17, 0
	s_add_i32 s78, s45, s27
	global_load_lds_dwordx4 v[216:217], off
	v_lshl_add_u64 v[2:3], s[76:77], 0, v[186:187]
	s_mov_b32 m0, s78
	v_lshl_add_u64 v[218:219], s[18:19], 0, v[184:185]
	global_load_lds_dwordx4 v[2:3], off
	v_lshl_add_u64 v[2:3], s[76:77], 0, v[190:191]
	s_add_i32 m0, s78, 0x2000
	v_lshl_add_u64 v[220:221], s[18:19], 0, v[188:189]
	global_load_lds_dwordx4 v[2:3], off
	s_mov_b32 m0, s28
	s_nop 0
	global_load_lds_dwordx4 v[218:219], off
	s_mov_b32 m0, s29
	s_nop 0
	global_load_lds_dwordx4 v[220:221], off
	s_waitcnt vmcnt(8)
	s_waitcnt lgkmcnt(0)
	s_setprio 1
	s_barrier
; #define PG8_STAGE(bufoff, gbase, voff) do { _Pragma("unroll") for (int _i = 0; _i < 2; ++_i) \
;         __builtin_amdgcn_global_load_lds((const unsigned*)((const char*)(gbase) + (voff)[_i]), (PG8_LAS unsigned*)(lds + (bufoff) + ldsw + _i * 8192), 16, 0, 0); } while (0)
; #define PG8_LDA(dst, b, h) do { _Pragma("unroll") for (int m = 0; m < 4; ++m) _Pragma("unroll") for (int k = 0; k < 2; ++k) dst[m][k] = *(const PG8_LAS bf16x8*)(lds + PG8_SA(b, h) + aoff + m * 2048 + k * 1024); } while (0)
; #define PG8_LDB(dst, b, h) do { _Pragma("unroll") for (int n = 0; n < 2; ++n) _Pragma("unroll") for (int k = 0; k < 2; ++k) dst[n][k] = *(const PG8_LAS bf16x8*)(lds + PG8_SB(b, h) + boff + n * 2048 + k * 1024); } while (0)
; #define PG8_MMA(ai, bj, At, Bt) do { __builtin_amdgcn_s_setprio(1); _Pragma("unroll") for (int m = 0; m < 4; ++m) _Pragma("unroll") for (int n = 0; n < 2; ++n) _Pragma("unroll") for (int k = 0; k < 2; ++k) \
;         acc[ai][bj][m][n] = __builtin_amdgcn_mfma_f32_16x16x32_bf16(Bt[n][k], At[m][k], acc[ai][bj][m][n], 0, 0, 0); __builtin_amdgcn_s_setprio(0); } while (0)
; #define PG8_WAIT_V(n) asm volatile("s_waitcnt vmcnt(" #n ")" ::: "memory")
; #define PG8_WAIT_L(n) asm volatile("s_waitcnt lgkmcnt(" #n ")" ::: "memory")
; #define PG8_BAR __builtin_amdgcn_s_barrier()
; #define PG8_SCHED __builtin_amdgcn_sched_barrier(0)
; template <class Epi, class Sched, bool ALIGN_EPI = false, bool SP2 = false, bool DUAL = false>
; __device__ __forceinline__ void gemm_phase(PG8_LAS unsigned char* lds, const Gemm g, const Sched& S, const Epi& E) {
;     ...
;             PG8_WAIT_V(8); PG8_WAIT_L(0); PG8_BAR; PG8_MMA(1, 0, At, B0); PG8_MMA(1, 1, At, B1); PG8_BAR; PG8_SCHED;
;             PG8_LDB(B0, 1, 0); PG8_LDB(B1, 1, 1); PG8_SCHED; PG8_LDA(At, 1, 0); PG8_STAGE(PG8_SA(0, 1), a2 + hstep, voffA);
;             PG8_WAIT_V(8); PG8_WAIT_L(0); PG8_BAR; PG8_MMA(0, 0, At, B0); PG8_MMA(0, 1, At, B1); PG8_BAR; PG8_SCHED;
	v_mfma_f32_16x16x32_bf16 v[64:67], v[132:135], v[164:167], v[64:67]
	v_mfma_f32_16x16x32_bf16 v[64:67], v[136:139], v[168:171], v[64:67]
	v_mfma_f32_16x16x32_bf16 v[60:63], v[140:143], v[164:167], v[60:63]
	v_mfma_f32_16x16x32_bf16 v[60:63], v[144:147], v[168:171], v[60:63]
	v_mfma_f32_16x16x32_bf16 v[56:59], v[132:135], v[172:175], v[56:59]
	v_mfma_f32_16x16x32_bf16 v[56:59], v[136:139], v[176:179], v[56:59]
	v_mfma_f32_16x16x32_bf16 v[52:55], v[140:143], v[172:175], v[52:55]
	v_mfma_f32_16x16x32_bf16 v[52:55], v[144:147], v[176:179], v[52:55]
	v_mfma_f32_16x16x32_bf16 v[48:51], v[132:135], v[180:183], v[48:51]
	v_mfma_f32_16x16x32_bf16 v[48:51], v[136:139], v[202:205], v[48:51]
	v_mfma_f32_16x16x32_bf16 v[44:47], v[140:143], v[180:183], v[44:47]
	v_mfma_f32_16x16x32_bf16 v[44:47], v[144:147], v[202:205], v[44:47]
	v_mfma_f32_16x16x32_bf16 v[40:43], v[132:135], v[206:209], v[40:43]
	v_mfma_f32_16x16x32_bf16 v[40:43], v[136:139], v[210:213], v[40:43]
	v_mfma_f32_16x16x32_bf16 v[36:39], v[140:143], v[206:209], v[36:39]
	v_mfma_f32_16x16x32_bf16 v[36:39], v[144:147], v[210:213], v[36:39]
	s_setprio 0
	s_setprio 1
	v_mfma_f32_16x16x32_bf16 v[32:35], v[148:151], v[164:167], v[32:35]
	v_mfma_f32_16x16x32_bf16 v[32:35], v[152:155], v[168:171], v[32:35]
	v_mfma_f32_16x16x32_bf16 v[28:31], v[156:159], v[164:167], v[28:31]
	v_mfma_f32_16x16x32_bf16 v[28:31], v[160:163], v[168:171], v[28:31]
	v_mfma_f32_16x16x32_bf16 v[24:27], v[148:151], v[172:175], v[24:27]
	v_mfma_f32_16x16x32_bf16 v[24:27], v[152:155], v[176:179], v[24:27]
	v_mfma_f32_16x16x32_bf16 v[20:23], v[156:159], v[172:175], v[20:23]
	v_mfma_f32_16x16x32_bf16 v[20:23], v[160:163], v[176:179], v[20:23]
	v_mfma_f32_16x16x32_bf16 v[16:19], v[148:151], v[180:183], v[16:19]
	v_mfma_f32_16x16x32_bf16 v[16:19], v[152:155], v[202:205], v[16:19]
	v_mfma_f32_16x16x32_bf16 v[12:15], v[156:159], v[180:183], v[12:15]
	v_mfma_f32_16x16x32_bf16 v[12:15], v[160:163], v[202:205], v[12:15]
	v_mfma_f32_16x16x32_bf16 v[8:11], v[148:151], v[206:209], v[8:11]
	v_mfma_f32_16x16x32_bf16 v[8:11], v[152:155], v[210:213], v[8:11]
	v_mfma_f32_16x16x32_bf16 v[2:5], v[156:159], v[206:209], v[4:7]
	v_mfma_f32_16x16x32_bf16 v[2:5], v[160:163], v[210:213], v[2:5]
	s_barrier
	s_setprio 0
	s_add_i32 s76, 0, 0x18000
	v_add_u32_e32 v1, s76, v235
	s_add_i32 s77, 0, 0x1c000
	ds_read_b128 v[132:135], v1
	ds_read_b128 v[136:139], v1 offset:1024
	ds_read_b128 v[140:143], v1 offset:2048
	ds_read_b128 v[144:147], v1 offset:3072
	v_add_u32_e32 v1, s77, v235
	ds_read_b128 v[148:151], v1
	ds_read_b128 v[152:155], v1 offset:1024
	ds_read_b128 v[156:159], v1 offset:2048
	ds_read_b128 v[160:163], v1 offset:3072
	s_add_u32 s18, s18, 0x80000
	s_addc_u32 s19, s19, 0
	s_mov_b32 m0, s34
	v_lshl_add_u64 v[6:7], s[18:19], 0, v[184:185]
	ds_read_b128 v[164:167], v237 offset:32768
	ds_read_b128 v[168:171], v237 offset:33792
	ds_read_b128 v[172:175], v237 offset:34816
	ds_read_b128 v[176:179], v237 offset:35840
	ds_read_b128 v[180:183], v237 offset:36864
	ds_read_b128 v[202:205], v237 offset:37888
	ds_read_b128 v[206:209], v237 offset:38912
	ds_read_b128 v[210:213], v237 offset:39936
	global_load_lds_dwordx4 v[6:7], off
	v_lshl_add_u64 v[6:7], s[18:19], 0, v[188:189]
	s_mov_b32 m0, s35
	s_nop 0
	global_load_lds_dwordx4 v[6:7], off
	s_waitcnt vmcnt(8)
	s_waitcnt lgkmcnt(0)
	s_setprio 1
	s_barrier
	v_mfma_f32_16x16x32_bf16 v[128:131], v[132:135], v[164:167], v[128:131]
	v_mfma_f32_16x16x32_bf16 v[128:131], v[136:139], v[168:171], v[128:131]
	v_mfma_f32_16x16x32_bf16 v[124:127], v[140:143], v[164:167], v[124:127]
	v_mfma_f32_16x16x32_bf16 v[124:127], v[144:147], v[168:171], v[124:127]
	v_mfma_f32_16x16x32_bf16 v[120:123], v[132:135], v[172:175], v[120:123]
	v_mfma_f32_16x16x32_bf16 v[120:123], v[136:139], v[176:179], v[120:123]
	v_mfma_f32_16x16x32_bf16 v[116:119], v[140:143], v[172:175], v[116:119]
	v_mfma_f32_16x16x32_bf16 v[116:119], v[144:147], v[176:179], v[116:119]
	v_mfma_f32_16x16x32_bf16 v[112:115], v[132:135], v[180:183], v[112:115]
	v_mfma_f32_16x16x32_bf16 v[112:115], v[136:139], v[202:205], v[112:115]
	v_mfma_f32_16x16x32_bf16 v[108:111], v[140:143], v[180:183], v[108:111]
	v_mfma_f32_16x16x32_bf16 v[108:111], v[144:147], v[202:205], v[108:111]
	v_mfma_f32_16x16x32_bf16 v[104:107], v[132:135], v[206:209], v[104:107]
	v_mfma_f32_16x16x32_bf16 v[104:107], v[136:139], v[210:213], v[104:107]
	v_mfma_f32_16x16x32_bf16 v[100:103], v[140:143], v[206:209], v[100:103]
	v_mfma_f32_16x16x32_bf16 v[100:103], v[144:147], v[210:213], v[100:103]
	s_setprio 0
	s_setprio 1
	v_mfma_f32_16x16x32_bf16 v[96:99], v[148:151], v[164:167], v[96:99]
	v_mfma_f32_16x16x32_bf16 v[96:99], v[152:155], v[168:171], v[96:99]
	v_mfma_f32_16x16x32_bf16 v[92:95], v[156:159], v[164:167], v[92:95]
	v_mfma_f32_16x16x32_bf16 v[92:95], v[160:163], v[168:171], v[92:95]
	v_mfma_f32_16x16x32_bf16 v[88:91], v[148:151], v[172:175], v[88:91]
	v_mfma_f32_16x16x32_bf16 v[88:91], v[152:155], v[176:179], v[88:91]
	v_mfma_f32_16x16x32_bf16 v[84:87], v[156:159], v[172:175], v[84:87]
	v_mfma_f32_16x16x32_bf16 v[84:87], v[160:163], v[176:179], v[84:87]
	v_mfma_f32_16x16x32_bf16 v[80:83], v[148:151], v[180:183], v[80:83]
	v_mfma_f32_16x16x32_bf16 v[80:83], v[152:155], v[202:205], v[80:83]
	v_mfma_f32_16x16x32_bf16 v[76:79], v[156:159], v[180:183], v[76:79]
	v_mfma_f32_16x16x32_bf16 v[76:79], v[160:163], v[202:205], v[76:79]
	v_mfma_f32_16x16x32_bf16 v[72:75], v[148:151], v[206:209], v[72:75]
	v_mfma_f32_16x16x32_bf16 v[72:75], v[152:155], v[210:213], v[72:75]
	v_mfma_f32_16x16x32_bf16 v[68:71], v[156:159], v[206:209], v[68:71]
	v_mfma_f32_16x16x32_bf16 v[68:71], v[160:163], v[210:213], v[68:71]
	s_barrier
; #define PG8_STAGE(bufoff, gbase, voff) do { _Pragma("unroll") for (int _i = 0; _i < 2; ++_i) \
;         __builtin_amdgcn_global_load_lds((const unsigned*)((const char*)(gbase) + (voff)[_i]), (PG8_LAS unsigned*)(lds + (bufoff) + ldsw + _i * 8192), 16, 0, 0); } while (0)
; #define PG8_LDA(dst, b, h) do { _Pragma("unroll") for (int m = 0; m < 4; ++m) _Pragma("unroll") for (int k = 0; k < 2; ++k) dst[m][k] = *(const PG8_LAS bf16x8*)(lds + PG8_SA(b, h) + aoff + m * 2048 + k * 1024); } while (0)
; #define PG8_MMA(ai, bj, At, Bt) do { __builtin_amdgcn_s_setprio(1); _Pragma("unroll") for (int m = 0; m < 4; ++m) _Pragma("unroll") for (int n = 0; n < 2; ++n) _Pragma("unroll") for (int k = 0; k < 2; ++k) \
;         acc[ai][bj][m][n] = __builtin_amdgcn_mfma_f32_16x16x32_bf16(Bt[n][k], At[m][k], acc[ai][bj][m][n], 0, 0, 0); __builtin_amdgcn_s_setprio(0); } while (0)
; #define PG8_WAIT_V(n) asm volatile("s_waitcnt vmcnt(" #n ")" ::: "memory")
; #define PG8_WAIT_L(n) asm volatile("s_waitcnt lgkmcnt(" #n ")" ::: "memory")
; #define PG8_BAR __builtin_amdgcn_s_barrier()
; #define PG8_SCHED __builtin_amdgcn_sched_barrier(0)
; template <class Epi, class Sched, bool ALIGN_EPI = false, bool SP2 = false, bool DUAL = false>
; __device__ __forceinline__ void gemm_phase(PG8_LAS unsigned char* lds, const Gemm g, const Sched& S, const Epi& E) {
;     ...
;         for (int t = 0; t < nt; t += 2) {
;     ...
;             PG8_LDA(At, 1, 1); PG8_STAGE(PG8_SB(1, 0), b3, voffB); PG8_STAGE(PG8_SB(1, 1), b3 + hstep, voffB); PG8_STAGE(PG8_SA(1, 0), a3, voffA);
;             PG8_WAIT_V(8); PG8_WAIT_L(0); PG8_BAR; PG8_MMA(1, 0, At, B0); PG8_MMA(1, 1, At, B1); PG8_BAR; PG8_SCHED;
	s_setprio 0
	s_add_i32 s18, s76, s27
	v_lshl_add_u64 v[6:7], v[214:215], 0, s[36:37]
	s_mov_b32 m0, s18
	ds_read_b128 v[164:167], v237 offset:49152
	ds_read_b128 v[168:171], v237 offset:50176
	ds_read_b128 v[172:175], v237 offset:51200
	ds_read_b128 v[176:179], v237 offset:52224
	ds_read_b128 v[180:183], v237 offset:53248
	ds_read_b128 v[202:205], v237 offset:54272
	ds_read_b128 v[206:209], v237 offset:55296
	ds_read_b128 v[210:213], v237 offset:56320
	global_load_lds_dwordx4 v[6:7], off
	s_add_i32 m0, s18, 0x2000
	s_add_u32 s16, s16, 0x80080
	v_lshl_add_u64 v[6:7], v[216:217], 0, s[36:37]
	s_addc_u32 s17, s17, 0
	s_add_i32 s18, s77, s27
	global_load_lds_dwordx4 v[6:7], off
	v_lshl_add_u64 v[6:7], s[16:17], 0, v[186:187]
	s_mov_b32 m0, s18
	s_nop 0
	global_load_lds_dwordx4 v[6:7], off
	v_lshl_add_u64 v[6:7], s[16:17], 0, v[190:191]
	s_add_i32 m0, s18, 0x2000
	s_nop 0
	global_load_lds_dwordx4 v[6:7], off
	v_lshl_add_u64 v[6:7], v[218:219], 0, s[36:37]
	s_mov_b32 m0, s42
	s_nop 0
	global_load_lds_dwordx4 v[6:7], off
	v_lshl_add_u64 v[6:7], v[220:221], 0, s[36:37]
	s_mov_b32 m0, s43
	s_nop 0
	global_load_lds_dwordx4 v[6:7], off
	s_waitcnt vmcnt(8)
	s_waitcnt lgkmcnt(0)
	s_setprio 1
	s_barrier
	v_mfma_f32_16x16x32_bf16 v[64:67], v[132:135], v[164:167], v[64:67]
	v_mfma_f32_16x16x32_bf16 v[64:67], v[136:139], v[168:171], v[64:67]
	v_mfma_f32_16x16x32_bf16 v[60:63], v[140:143], v[164:167], v[60:63]
	v_mfma_f32_16x16x32_bf16 v[60:63], v[144:147], v[168:171], v[60:63]
	v_mfma_f32_16x16x32_bf16 v[56:59], v[132:135], v[172:175], v[56:59]
	v_mfma_f32_16x16x32_bf16 v[56:59], v[136:139], v[176:179], v[56:59]
	v_mfma_f32_16x16x32_bf16 v[52:55], v[140:143], v[172:175], v[52:55]
	v_mfma_f32_16x16x32_bf16 v[52:55], v[144:147], v[176:179], v[52:55]
	v_mfma_f32_16x16x32_bf16 v[48:51], v[132:135], v[180:183], v[48:51]
	v_mfma_f32_16x16x32_bf16 v[48:51], v[136:139], v[202:205], v[48:51]
	v_mfma_f32_16x16x32_bf16 v[44:47], v[140:143], v[180:183], v[44:47]
	v_mfma_f32_16x16x32_bf16 v[44:47], v[144:147], v[202:205], v[44:47]
	v_mfma_f32_16x16x32_bf16 v[40:43], v[132:135], v[206:209], v[40:43]
	v_mfma_f32_16x16x32_bf16 v[40:43], v[136:139], v[210:213], v[40:43]
	v_mfma_f32_16x16x32_bf16 v[36:39], v[140:143], v[206:209], v[36:39]
	v_mfma_f32_16x16x32_bf16 v[36:39], v[144:147], v[210:213], v[36:39]
	s_setprio 0
	s_setprio 1
	v_mfma_f32_16x16x32_bf16 v[32:35], v[148:151], v[164:167], v[32:35]
	v_mfma_f32_16x16x32_bf16 v[28:31], v[156:159], v[164:167], v[28:31]
	v_mfma_f32_16x16x32_bf16 v[24:27], v[148:151], v[172:175], v[24:27]
	v_mfma_f32_16x16x32_bf16 v[20:23], v[156:159], v[172:175], v[20:23]
	v_mfma_f32_16x16x32_bf16 v[16:19], v[148:151], v[180:183], v[16:19]
	v_mfma_f32_16x16x32_bf16 v[12:15], v[156:159], v[180:183], v[12:15]
	v_mfma_f32_16x16x32_bf16 v[6:9], v[148:151], v[206:209], v[8:11]
	v_mfma_f32_16x16x32_bf16 v[2:5], v[156:159], v[206:209], v[2:5]
	v_mfma_f32_16x16x32_bf16 v[32:35], v[152:155], v[168:171], v[32:35]
	v_mfma_f32_16x16x32_bf16 v[28:31], v[160:163], v[168:171], v[28:31]
	v_mfma_f32_16x16x32_bf16 v[24:27], v[152:155], v[176:179], v[24:27]
	v_mfma_f32_16x16x32_bf16 v[20:23], v[160:163], v[176:179], v[20:23]
	v_mfma_f32_16x16x32_bf16 v[16:19], v[152:155], v[202:205], v[16:19]
	v_mfma_f32_16x16x32_bf16 v[12:15], v[160:163], v[202:205], v[12:15]
	v_mfma_f32_16x16x32_bf16 v[8:11], v[152:155], v[210:213], v[6:9]
	v_mfma_f32_16x16x32_bf16 v[4:7], v[160:163], v[210:213], v[2:5]
	s_barrier
	s_setprio 0
	s_add_i32 s75, s75, 2
	s_add_u32 s14, s14, 0x100
	s_addc_u32 s15, s15, 0
	s_add_u32 s72, s72, 0x100
	s_addc_u32 s73, s73, 0
	s_cmp_gt_u32 s75, 29
	s_cbranch_scc0 .LBB0_805
	s_and_b64 vcc, exec, s[38:39]
	s_cbranch_vccz .LBB0_808
	s_barrier

;     __device__ bool next(int i, Unit& u) const { if (!base.next(i >> 1, u)) return false; u.sub = i & 1; return true; }
; #define PG8_STAGE(bufoff, gbase, voff) do { _Pragma("unroll") for (int _i = 0; _i < 2; ++_i) \
;         __builtin_amdgcn_global_load_lds((const unsigned*)((const char*)(gbase) + (voff)[_i]), (PG8_LAS unsigned*)(lds + (bufoff) + ldsw + _i * 8192), 16, 0, 0); } while (0)
; #define PG8_LDA(dst, b, h) do { _Pragma("unroll") for (int m = 0; m < 4; ++m) _Pragma("unroll") for (int k = 0; k < 2; ++k) dst[m][k] = *(const PG8_LAS bf16x8*)(lds + PG8_SA(b, h) + aoff + m * 2048 + k * 1024); } while (0)
; template <class Epi, class Sched, bool ALIGN_EPI = false, bool SP2 = false, bool DUAL = false>
; __device__ __forceinline__ void gemm_phase(PG8_LAS unsigned char* lds, const Gemm g, const Sched& S, const Epi& E) {
;     ...
;     for (;;) {
;         const bool has_next = S.next(ui + 1, nxt);
;         const char* nA = has_next ? (const char*)((DUAL && nxt.sub) ? g.A2 : g.A) + (size_t)nxt.pm * tstep : cA; const char* nB = has_next ? (const char*)((DUAL && nxt.sub) ? g.Bt2 : g.Bt) + (size_t)nxt.pn * tstep : cB;
;         for (int t = 0; t < nt; t += 2) {
;             const bool last = (t == nt - 2);
;             const char* a1 = cA + (size_t)(t + 1) * kstep;
;             const char* a2 = last ? nA : cA + (size_t)(t + 2) * kstep; const char* b2 = last ? nB : cB + (size_t)(t + 2) * kstep;
;             const char* a3 = a2 + kstep; const char* b3 = b2 + kstep;
;             if (last && has_next) S.a_ready(nxt);
;             if constexpr (SP2) {
;             PG8_LDB(B0, 0, 0); PG8_LDB(B1, 0, 1); PG8_SCHED; PG8_LDA(At, 0, 0); PG8_STAGE(PG8_SA(1, 1), a1 + hstep, voffA);
;             PG8_WAIT_V(8); PG8_WAIT_L(0); PG8_BAR; PG8_MMA(0, 0, At, B0); PG8_MMA(0, 1, At, B1); PG8_BAR; PG8_SCHED;
;             PG8_LDA(At, 0, 1); PG8_STAGE(PG8_SB(0, 0), b2, voffB); PG8_STAGE(PG8_SB(0, 1), b2 + hstep, voffB); PG8_STAGE(PG8_SA(0, 0), a2, voffA);
;             PG8_WAIT_V(8); PG8_WAIT_L(0); PG8_BAR; PG8_MMA(1, 0, At, B0); PG8_MMA(1, 1, At, B1); PG8_BAR; PG8_SCHED;
;     ...
;         for (int a = 0; a < 2; ++a)
; #pragma unroll
;             for (int b = 0; b < 2; ++b)
; #pragma unroll
;                 for (int m = 0; m < 4; ++m)
; #pragma unroll
;                     for (int n = 0; n < 2; ++n) acc[a][b][m][n] = (f32x4){0.f, 0.f, 0.f, 0.f};
.LBB0_895:
	s_ashr_i32 s61, s60, 31
	s_lshl_b64 s[18:19], s[60:61], 20
	s_add_u32 s62, s10, s18
	s_addc_u32 s63, s11, s19
	s_and_b64 s[18:19], s[6:7], exec
	s_cselect_b32 s18, s63, s17
	s_cselect_b32 s19, s62, s16
	s_ashr_i32 s41, s40, 31
	s_lshl_b64 s[64:65], s[40:41], 20
	s_add_u32 s64, s12, s64
	s_addc_u32 s65, s13, s65
	s_and_b64 s[68:69], s[6:7], exec
	s_cselect_b32 s41, s65, s15
	s_cselect_b32 s61, s64, s14
	s_add_u32 s68, s16, 0x80080
	s_addc_u32 s69, s17, 0
	s_add_u32 s67, s14, 0x100
	s_addc_u32 s70, s15, 0
	s_mov_b32 s71, -2
	s_waitcnt lgkmcnt(0)
	s_add_u32 s14, s68, 0xfff80080
	s_addc_u32 s15, s69, -1
	s_cmp_eq_u32 s71, 28
	s_cselect_b32 s17, s18, s15
	s_cselect_b32 s16, s19, s14
	s_cselect_b32 s15, s41, s70
	s_cselect_b32 s14, s61, s67
	s_waitcnt vmcnt(8)
	s_waitcnt lgkmcnt(0)
	s_setprio 1
	s_barrier
	v_mfma_f32_16x16x32_bf16 v[124:127], v[128:131], v[160:163], 0
	v_mfma_f32_16x16x32_bf16 v[124:127], v[132:135], v[164:167], v[124:127]
	v_mfma_f32_16x16x32_bf16 v[120:123], v[136:139], v[160:163], 0
	v_mfma_f32_16x16x32_bf16 v[120:123], v[140:143], v[164:167], v[120:123]
	v_mfma_f32_16x16x32_bf16 v[108:111], v[128:131], v[168:171], 0
	v_mfma_f32_16x16x32_bf16 v[108:111], v[132:135], v[172:175], v[108:111]
	v_mfma_f32_16x16x32_bf16 v[104:107], v[136:139], v[168:171], 0
	v_mfma_f32_16x16x32_bf16 v[104:107], v[140:143], v[172:175], v[104:107]
	v_mfma_f32_16x16x32_bf16 v[92:95], v[128:131], v[196:199], 0
	v_mfma_f32_16x16x32_bf16 v[92:95], v[132:135], v[202:205], v[92:95]
	v_mfma_f32_16x16x32_bf16 v[88:91], v[136:139], v[196:199], 0
	v_mfma_f32_16x16x32_bf16 v[88:91], v[140:143], v[202:205], v[88:91]
	v_mfma_f32_16x16x32_bf16 v[76:79], v[128:131], v[206:209], 0
	v_mfma_f32_16x16x32_bf16 v[76:79], v[132:135], v[232:235], v[76:79]
	v_mfma_f32_16x16x32_bf16 v[72:75], v[136:139], v[206:209], 0
	v_mfma_f32_16x16x32_bf16 v[72:75], v[140:143], v[232:235], v[72:75]
	s_setprio 0
	s_setprio 1
	v_mfma_f32_16x16x32_bf16 v[116:119], v[144:147], v[160:163], 0
	v_mfma_f32_16x16x32_bf16 v[116:119], v[148:151], v[164:167], v[116:119]
	v_mfma_f32_16x16x32_bf16 v[112:115], v[152:155], v[160:163], 0
	v_mfma_f32_16x16x32_bf16 v[112:115], v[156:159], v[164:167], v[112:115]
	v_mfma_f32_16x16x32_bf16 v[100:103], v[144:147], v[168:171], 0
	v_mfma_f32_16x16x32_bf16 v[100:103], v[148:151], v[172:175], v[100:103]
	v_mfma_f32_16x16x32_bf16 v[96:99], v[152:155], v[168:171], 0
	v_mfma_f32_16x16x32_bf16 v[96:99], v[156:159], v[172:175], v[96:99]
	v_mfma_f32_16x16x32_bf16 v[84:87], v[144:147], v[196:199], 0
	v_mfma_f32_16x16x32_bf16 v[84:87], v[148:151], v[202:205], v[84:87]
	v_mfma_f32_16x16x32_bf16 v[80:83], v[152:155], v[196:199], 0
	v_mfma_f32_16x16x32_bf16 v[80:83], v[156:159], v[202:205], v[80:83]
	v_mfma_f32_16x16x32_bf16 v[68:71], v[144:147], v[206:209], 0
	v_mfma_f32_16x16x32_bf16 v[68:71], v[148:151], v[232:235], v[68:71]
	v_mfma_f32_16x16x32_bf16 v[64:67], v[152:155], v[206:209], 0
	v_mfma_f32_16x16x32_bf16 v[64:67], v[156:159], v[232:235], v[64:67]
	s_barrier
	s_setprio 0
	v_lshl_add_u64 v[222:223], s[68:69], 0, v[188:189]
	s_add_i32 m0, s27, 0xc000
	s_nop 0
	global_load_lds_dwordx4 v[222:223], off
	v_lshl_add_u64 v[222:223], s[68:69], 0, v[190:191]
	s_add_i32 m0, s27, 0xe000
	s_nop 0
	global_load_lds_dwordx4 v[222:223], off
	s_add_i32 s72, s48, s26
	v_lshl_add_u64 v[222:223], s[14:15], 0, v[182:183]
	s_mov_b32 m0, s72
	ds_read_b128 v[160:163], v220 offset:16384
	ds_read_b128 v[164:167], v220 offset:17408
	ds_read_b128 v[168:171], v220 offset:18432
	ds_read_b128 v[172:175], v220 offset:19456
	ds_read_b128 v[196:199], v220 offset:20480
	ds_read_b128 v[202:205], v220 offset:21504
	ds_read_b128 v[206:209], v220 offset:22528
	ds_read_b128 v[232:235], v220 offset:23552
	global_load_lds_dwordx4 v[222:223], off
	s_add_i32 m0, s72, 0x2000
	s_add_u32 s72, s14, 0x80000
	v_lshl_add_u64 v[228:229], s[14:15], 0, v[186:187]
	s_addc_u32 s73, s15, 0
	s_add_i32 s74, s49, s26
	global_load_lds_dwordx4 v[228:229], off
	v_lshl_add_u64 v[236:237], s[72:73], 0, v[182:183]
	s_mov_b32 m0, s74
	v_lshl_add_u64 v[238:239], s[16:17], 0, v[184:185]
	global_load_lds_dwordx4 v[236:237], off
	v_lshl_add_u64 v[236:237], s[72:73], 0, v[186:187]
	s_add_i32 m0, s74, 0x2000
	s_nop 0
	global_load_lds_dwordx4 v[236:237], off
	v_lshl_add_u64 v[236:237], s[16:17], 0, v[180:181]
	s_mov_b32 m0, s27
	s_nop 0
	global_load_lds_dwordx4 v[236:237], off
	s_mov_b32 m0, s28
	s_nop 0
	global_load_lds_dwordx4 v[238:239], off
	s_waitcnt vmcnt(8)
	s_waitcnt lgkmcnt(0)
	s_setprio 1
	s_barrier
	v_mfma_f32_16x16x32_bf16 v[60:63], v[128:131], v[160:163], 0
	v_mfma_f32_16x16x32_bf16 v[60:63], v[132:135], v[164:167], v[60:63]
	v_mfma_f32_16x16x32_bf16 v[56:59], v[136:139], v[160:163], 0
	v_mfma_f32_16x16x32_bf16 v[56:59], v[140:143], v[164:167], v[56:59]
	v_mfma_f32_16x16x32_bf16 v[44:47], v[128:131], v[168:171], 0
	v_mfma_f32_16x16x32_bf16 v[44:47], v[132:135], v[172:175], v[44:47]
	v_mfma_f32_16x16x32_bf16 v[40:43], v[136:139], v[168:171], 0
	v_mfma_f32_16x16x32_bf16 v[40:43], v[140:143], v[172:175], v[40:43]
	v_mfma_f32_16x16x32_bf16 v[28:31], v[128:131], v[196:199], 0
	v_mfma_f32_16x16x32_bf16 v[28:31], v[132:135], v[202:205], v[28:31]
	v_mfma_f32_16x16x32_bf16 v[24:27], v[136:139], v[196:199], 0
	v_mfma_f32_16x16x32_bf16 v[24:27], v[140:143], v[202:205], v[24:27]
	v_mfma_f32_16x16x32_bf16 v[12:15], v[128:131], v[206:209], 0
	v_mfma_f32_16x16x32_bf16 v[12:15], v[132:135], v[232:235], v[12:15]
	v_mfma_f32_16x16x32_bf16 v[8:11], v[136:139], v[206:209], 0
	v_mfma_f32_16x16x32_bf16 v[8:11], v[140:143], v[232:235], v[8:11]
	s_setprio 0
	s_setprio 1
	v_mfma_f32_16x16x32_bf16 v[52:55], v[144:147], v[160:163], 0
	v_mfma_f32_16x16x32_bf16 v[52:55], v[148:151], v[164:167], v[52:55]
	v_mfma_f32_16x16x32_bf16 v[48:51], v[152:155], v[160:163], 0
	v_mfma_f32_16x16x32_bf16 v[48:51], v[156:159], v[164:167], v[48:51]
	v_mfma_f32_16x16x32_bf16 v[36:39], v[144:147], v[168:171], 0
	v_mfma_f32_16x16x32_bf16 v[36:39], v[148:151], v[172:175], v[36:39]
	v_mfma_f32_16x16x32_bf16 v[32:35], v[152:155], v[168:171], 0
	v_mfma_f32_16x16x32_bf16 v[32:35], v[156:159], v[172:175], v[32:35]
	v_mfma_f32_16x16x32_bf16 v[20:23], v[144:147], v[196:199], 0
	v_mfma_f32_16x16x32_bf16 v[20:23], v[148:151], v[202:205], v[20:23]
	v_mfma_f32_16x16x32_bf16 v[16:19], v[152:155], v[196:199], 0
	v_mfma_f32_16x16x32_bf16 v[16:19], v[156:159], v[202:205], v[16:19]
	v_mfma_f32_16x16x32_bf16 v[4:7], v[144:147], v[206:209], 0
	v_mfma_f32_16x16x32_bf16 v[4:7], v[148:151], v[232:235], v[4:7]
	v_mfma_f32_16x16x32_bf16 v[0:3], v[152:155], v[206:209], 0
	v_mfma_f32_16x16x32_bf16 v[0:3], v[156:159], v[232:235], v[0:3]
	s_barrier
; #define PG8_STAGE(bufoff, gbase, voff) do { _Pragma("unroll") for (int _i = 0; _i < 2; ++_i) \
;         __builtin_amdgcn_global_load_lds((const unsigned*)((const char*)(gbase) + (voff)[_i]), (PG8_LAS unsigned*)(lds + (bufoff) + ldsw + _i * 8192), 16, 0, 0); } while (0)
; #define PG8_LDA(dst, b, h) do { _Pragma("unroll") for (int m = 0; m < 4; ++m) _Pragma("unroll") for (int k = 0; k < 2; ++k) dst[m][k] = *(const PG8_LAS bf16x8*)(lds + PG8_SA(b, h) + aoff + m * 2048 + k * 1024); } while (0)
; #define PG8_LDB(dst, b, h) do { _Pragma("unroll") for (int n = 0; n < 2; ++n) _Pragma("unroll") for (int k = 0; k < 2; ++k) dst[n][k] = *(const PG8_LAS bf16x8*)(lds + PG8_SB(b, h) + boff + n * 2048 + k * 1024); } while (0)
; #define PG8_MMA(ai, bj, At, Bt) do { __builtin_amdgcn_s_setprio(1); _Pragma("unroll") for (int m = 0; m < 4; ++m) _Pragma("unroll") for (int n = 0; n < 2; ++n) _Pragma("unroll") for (int k = 0; k < 2; ++k) \
;         acc[ai][bj][m][n] = __builtin_amdgcn_mfma_f32_16x16x32_bf16(Bt[n][k], At[m][k], acc[ai][bj][m][n], 0, 0, 0); __builtin_amdgcn_s_setprio(0); } while (0)
; #define PG8_WAIT_V(n) asm volatile("s_waitcnt vmcnt(" #n ")" ::: "memory")
; #define PG8_WAIT_L(n) asm volatile("s_waitcnt lgkmcnt(" #n ")" ::: "memory")
; #define PG8_BAR __builtin_amdgcn_s_barrier()
; #define PG8_SCHED __builtin_amdgcn_sched_barrier(0)
; template <class Epi, class Sched, bool ALIGN_EPI = false, bool SP2 = false, bool DUAL = false>
; __device__ __forceinline__ void gemm_phase(PG8_LAS unsigned char* lds, const Gemm g, const Sched& S, const Epi& E) {
;     ...
;             PG8_LDB(B0, 1, 0); PG8_LDB(B1, 1, 1); PG8_SCHED; PG8_LDA(At, 1, 0); PG8_STAGE(PG8_SA(0, 1), a2 + hstep, voffA);
;             PG8_WAIT_V(8); PG8_WAIT_L(0); PG8_BAR; PG8_MMA(0, 0, At, B0); PG8_MMA(0, 1, At, B1); PG8_BAR; PG8_SCHED;
;             PG8_LDA(At, 1, 1); PG8_STAGE(PG8_SB(1, 0), b3, voffB); PG8_STAGE(PG8_SB(1, 1), b3 + hstep, voffB); PG8_STAGE(PG8_SA(1, 0), a3, voffA);
	s_setprio 0
	s_add_i32 s72, 0, 0x18000
	s_add_i32 s73, 0, 0x1c000
	v_add_u32_e32 v140, s72, v216
	v_add_u32_e32 v156, s73, v216
	ds_read_b128 v[128:131], v140
	ds_read_b128 v[132:135], v140 offset:1024
	ds_read_b128 v[136:139], v140 offset:2048
	ds_read_b128 v[140:143], v140 offset:3072
	ds_read_b128 v[144:147], v156
	ds_read_b128 v[148:151], v156 offset:1024
	ds_read_b128 v[152:155], v156 offset:2048
	ds_read_b128 v[156:159], v156 offset:3072
	s_add_u32 s16, s16, 0x80000
	s_addc_u32 s17, s17, 0
	s_mov_b32 m0, s29
	v_lshl_add_u64 v[240:241], s[16:17], 0, v[180:181]
	ds_read_b128 v[160:163], v220 offset:32768
	ds_read_b128 v[164:167], v220 offset:33792
	ds_read_b128 v[168:171], v220 offset:34816
	ds_read_b128 v[172:175], v220 offset:35840
	ds_read_b128 v[196:199], v220 offset:36864
	ds_read_b128 v[202:205], v220 offset:37888
	ds_read_b128 v[206:209], v220 offset:38912
	ds_read_b128 v[232:235], v220 offset:39936
	global_load_lds_dwordx4 v[240:241], off
	v_lshl_add_u64 v[240:241], s[16:17], 0, v[184:185]
	s_mov_b32 m0, s34
	s_nop 0
	global_load_lds_dwordx4 v[240:241], off
	s_waitcnt vmcnt(8)
	s_waitcnt lgkmcnt(0)
	s_setprio 1
	s_barrier
	v_mfma_f32_16x16x32_bf16 v[124:127], v[128:131], v[160:163], v[124:127]
	v_mfma_f32_16x16x32_bf16 v[124:127], v[132:135], v[164:167], v[124:127]
	v_mfma_f32_16x16x32_bf16 v[120:123], v[136:139], v[160:163], v[120:123]
	v_mfma_f32_16x16x32_bf16 v[120:123], v[140:143], v[164:167], v[120:123]
	v_mfma_f32_16x16x32_bf16 v[108:111], v[128:131], v[168:171], v[108:111]
	v_mfma_f32_16x16x32_bf16 v[108:111], v[132:135], v[172:175], v[108:111]
	v_mfma_f32_16x16x32_bf16 v[104:107], v[136:139], v[168:171], v[104:107]
	v_mfma_f32_16x16x32_bf16 v[104:107], v[140:143], v[172:175], v[104:107]
	v_mfma_f32_16x16x32_bf16 v[92:95], v[128:131], v[196:199], v[92:95]
	v_mfma_f32_16x16x32_bf16 v[92:95], v[132:135], v[202:205], v[92:95]
	v_mfma_f32_16x16x32_bf16 v[88:91], v[136:139], v[196:199], v[88:91]
	v_mfma_f32_16x16x32_bf16 v[88:91], v[140:143], v[202:205], v[88:91]
	v_mfma_f32_16x16x32_bf16 v[76:79], v[128:131], v[206:209], v[76:79]
	v_mfma_f32_16x16x32_bf16 v[76:79], v[132:135], v[232:235], v[76:79]
	v_mfma_f32_16x16x32_bf16 v[72:75], v[136:139], v[206:209], v[72:75]
	v_mfma_f32_16x16x32_bf16 v[72:75], v[140:143], v[232:235], v[72:75]
	s_setprio 0
	s_setprio 1
	v_mfma_f32_16x16x32_bf16 v[116:119], v[144:147], v[160:163], v[116:119]
	v_mfma_f32_16x16x32_bf16 v[116:119], v[148:151], v[164:167], v[116:119]
	v_mfma_f32_16x16x32_bf16 v[112:115], v[152:155], v[160:163], v[112:115]
	v_mfma_f32_16x16x32_bf16 v[112:115], v[156:159], v[164:167], v[112:115]
	v_mfma_f32_16x16x32_bf16 v[100:103], v[144:147], v[168:171], v[100:103]
	v_mfma_f32_16x16x32_bf16 v[100:103], v[148:151], v[172:175], v[100:103]
	v_mfma_f32_16x16x32_bf16 v[96:99], v[152:155], v[168:171], v[96:99]
	v_mfma_f32_16x16x32_bf16 v[96:99], v[156:159], v[172:175], v[96:99]
	v_mfma_f32_16x16x32_bf16 v[84:87], v[144:147], v[196:199], v[84:87]
	v_mfma_f32_16x16x32_bf16 v[84:87], v[148:151], v[202:205], v[84:87]
	v_mfma_f32_16x16x32_bf16 v[80:83], v[152:155], v[196:199], v[80:83]
	v_mfma_f32_16x16x32_bf16 v[80:83], v[156:159], v[202:205], v[80:83]
	v_mfma_f32_16x16x32_bf16 v[68:71], v[144:147], v[206:209], v[68:71]
	v_mfma_f32_16x16x32_bf16 v[68:71], v[148:151], v[232:235], v[68:71]
	v_mfma_f32_16x16x32_bf16 v[64:67], v[152:155], v[206:209], v[64:67]
	v_mfma_f32_16x16x32_bf16 v[64:67], v[156:159], v[232:235], v[64:67]
	s_barrier
	s_setprio 0
	s_add_i32 s16, s72, s26
	v_lshl_add_u64 v[222:223], v[222:223], 0, s[36:37]
	s_mov_b32 m0, s16
	ds_read_b128 v[160:163], v220 offset:49152
	ds_read_b128 v[164:167], v220 offset:50176
	ds_read_b128 v[168:171], v220 offset:51200
	ds_read_b128 v[172:175], v220 offset:52224
	ds_read_b128 v[196:199], v220 offset:53248
	ds_read_b128 v[202:205], v220 offset:54272
	ds_read_b128 v[206:209], v220 offset:55296
	ds_read_b128 v[232:235], v220 offset:56320
	global_load_lds_dwordx4 v[222:223], off
	s_add_i32 m0, s16, 0x2000
	s_add_u32 s14, s14, 0x80080
	v_lshl_add_u64 v[222:223], v[228:229], 0, s[36:37]
	s_addc_u32 s15, s15, 0
	s_add_i32 s16, s73, s26
	global_load_lds_dwordx4 v[222:223], off
	v_lshl_add_u64 v[222:223], s[14:15], 0, v[182:183]
	s_mov_b32 m0, s16
	s_nop 0
	global_load_lds_dwordx4 v[222:223], off
	v_lshl_add_u64 v[222:223], s[14:15], 0, v[186:187]
	s_add_i32 m0, s16, 0x2000
	s_nop 0
	global_load_lds_dwordx4 v[222:223], off
	v_lshl_add_u64 v[222:223], v[236:237], 0, s[36:37]
	s_mov_b32 m0, s44
	s_nop 0
	global_load_lds_dwordx4 v[222:223], off
	v_lshl_add_u64 v[222:223], v[238:239], 0, s[36:37]
	s_mov_b32 m0, s45
	s_nop 0
	global_load_lds_dwordx4 v[222:223], off
	s_waitcnt vmcnt(8)
	s_waitcnt lgkmcnt(0)
	s_setprio 1
	s_barrier
; #define PG8_STAGE(bufoff, gbase, voff) do { _Pragma("unroll") for (int _i = 0; _i < 2; ++_i) \
;         __builtin_amdgcn_global_load_lds((const unsigned*)((const char*)(gbase) + (voff)[_i]), (PG8_LAS unsigned*)(lds + (bufoff) + ldsw + _i * 8192), 16, 0, 0); } while (0)
; #define PG8_LDA(dst, b, h) do { _Pragma("unroll") for (int m = 0; m < 4; ++m) _Pragma("unroll") for (int k = 0; k < 2; ++k) dst[m][k] = *(const PG8_LAS bf16x8*)(lds + PG8_SA(b, h) + aoff + m * 2048 + k * 1024); } while (0)
; #define PG8_LDB(dst, b, h) do { _Pragma("unroll") for (int n = 0; n < 2; ++n) _Pragma("unroll") for (int k = 0; k < 2; ++k) dst[n][k] = *(const PG8_LAS bf16x8*)(lds + PG8_SB(b, h) + boff + n * 2048 + k * 1024); } while (0)
; #define PG8_MMA(ai, bj, At, Bt) do { __builtin_amdgcn_s_setprio(1); _Pragma("unroll") for (int m = 0; m < 4; ++m) _Pragma("unroll") for (int n = 0; n < 2; ++n) _Pragma("unroll") for (int k = 0; k < 2; ++k) \
;         acc[ai][bj][m][n] = __builtin_amdgcn_mfma_f32_16x16x32_bf16(Bt[n][k], At[m][k], acc[ai][bj][m][n], 0, 0, 0); __builtin_amdgcn_s_setprio(0); } while (0)
; #define PG8_WAIT_V(n) asm volatile("s_waitcnt vmcnt(" #n ")" ::: "memory")
; #define PG8_BAR __builtin_amdgcn_s_barrier()
; template <class Epi, class Sched, bool ALIGN_EPI = false, bool SP2 = false, bool DUAL = false>
; __device__ __forceinline__ void gemm_phase(PG8_LAS unsigned char* lds, const Gemm g, const Sched& S, const Epi& E) {
;     ...
;         for (int t = 0; t < nt; t += 2) {
;             const bool last = (t == nt - 2);
;             const char* a1 = cA + (size_t)(t + 1) * kstep;
;             const char* a2 = last ? nA : cA + (size_t)(t + 2) * kstep; const char* b2 = last ? nB : cB + (size_t)(t + 2) * kstep;
;             const char* a3 = a2 + kstep; const char* b3 = b2 + kstep;
;             if (last && has_next) S.a_ready(nxt);
;             if constexpr (SP2) {
;             PG8_LDB(B0, 0, 0); PG8_LDB(B1, 0, 1); PG8_SCHED; PG8_LDA(At, 0, 0); PG8_STAGE(PG8_SA(1, 1), a1 + hstep, voffA);
;             PG8_WAIT_V(8); PG8_WAIT_L(0); PG8_BAR; PG8_MMA(0, 0, At, B0); PG8_MMA(0, 1, At, B1); PG8_BAR; PG8_SCHED;
;             PG8_LDA(At, 0, 1); PG8_STAGE(PG8_SB(0, 0), b2, voffB); PG8_STAGE(PG8_SB(0, 1), b2 + hstep, voffB); PG8_STAGE(PG8_SA(0, 0), a2, voffA);
;             PG8_WAIT_V(8); PG8_WAIT_L(0); PG8_BAR; PG8_MMA(1, 0, At, B0); PG8_MMA(1, 1, At, B1); PG8_BAR; PG8_SCHED;
	v_mfma_f32_16x16x32_bf16 v[60:63], v[128:131], v[160:163], v[60:63]
	v_mfma_f32_16x16x32_bf16 v[60:63], v[132:135], v[164:167], v[60:63]
	v_mfma_f32_16x16x32_bf16 v[56:59], v[136:139], v[160:163], v[56:59]
	v_mfma_f32_16x16x32_bf16 v[56:59], v[140:143], v[164:167], v[56:59]
	v_mfma_f32_16x16x32_bf16 v[44:47], v[128:131], v[168:171], v[44:47]
	v_mfma_f32_16x16x32_bf16 v[44:47], v[132:135], v[172:175], v[44:47]
	v_mfma_f32_16x16x32_bf16 v[40:43], v[136:139], v[168:171], v[40:43]
	v_mfma_f32_16x16x32_bf16 v[40:43], v[140:143], v[172:175], v[40:43]
	v_mfma_f32_16x16x32_bf16 v[28:31], v[128:131], v[196:199], v[28:31]
	v_mfma_f32_16x16x32_bf16 v[28:31], v[132:135], v[202:205], v[28:31]
	v_mfma_f32_16x16x32_bf16 v[24:27], v[136:139], v[196:199], v[24:27]
	v_mfma_f32_16x16x32_bf16 v[24:27], v[140:143], v[202:205], v[24:27]
	v_mfma_f32_16x16x32_bf16 v[12:15], v[128:131], v[206:209], v[12:15]
	v_mfma_f32_16x16x32_bf16 v[12:15], v[132:135], v[232:235], v[12:15]
	v_mfma_f32_16x16x32_bf16 v[8:11], v[136:139], v[206:209], v[8:11]
	v_mfma_f32_16x16x32_bf16 v[8:11], v[140:143], v[232:235], v[8:11]
	s_setprio 0
	s_setprio 1
	v_mfma_f32_16x16x32_bf16 v[52:55], v[144:147], v[160:163], v[52:55]
	v_mfma_f32_16x16x32_bf16 v[52:55], v[148:151], v[164:167], v[52:55]
	v_mfma_f32_16x16x32_bf16 v[48:51], v[152:155], v[160:163], v[48:51]
	v_mfma_f32_16x16x32_bf16 v[48:51], v[156:159], v[164:167], v[48:51]
	v_mfma_f32_16x16x32_bf16 v[36:39], v[144:147], v[168:171], v[36:39]
	v_mfma_f32_16x16x32_bf16 v[36:39], v[148:151], v[172:175], v[36:39]
	v_mfma_f32_16x16x32_bf16 v[32:35], v[152:155], v[168:171], v[32:35]
	v_mfma_f32_16x16x32_bf16 v[32:35], v[156:159], v[172:175], v[32:35]
	v_mfma_f32_16x16x32_bf16 v[20:23], v[144:147], v[196:199], v[20:23]
	v_mfma_f32_16x16x32_bf16 v[20:23], v[148:151], v[202:205], v[20:23]
	v_mfma_f32_16x16x32_bf16 v[16:19], v[152:155], v[196:199], v[16:19]
	v_mfma_f32_16x16x32_bf16 v[16:19], v[156:159], v[202:205], v[16:19]
	v_mfma_f32_16x16x32_bf16 v[4:7], v[144:147], v[206:209], v[4:7]
	v_mfma_f32_16x16x32_bf16 v[4:7], v[148:151], v[232:235], v[4:7]
	v_mfma_f32_16x16x32_bf16 v[0:3], v[152:155], v[206:209], v[0:3]
	v_mfma_f32_16x16x32_bf16 v[0:3], v[156:159], v[232:235], v[0:3]
	s_barrier
	s_setprio 0
	s_add_i32 s71, s71, 2
	s_add_u32 s68, s68, 0x100
	s_addc_u32 s69, s69, 0
	s_add_u32 s67, s67, 0x100
	s_addc_u32 s70, s70, 0
.LBB0_896:
	ds_read_b128 v[128:131], v218
	ds_read_b128 v[132:135], v218 offset:1024
	ds_read_b128 v[136:139], v218 offset:2048
	ds_read_b128 v[140:143], v218 offset:3072
	ds_read_b128 v[144:147], v219
	ds_read_b128 v[148:151], v219 offset:1024
	ds_read_b128 v[152:155], v219 offset:2048
	ds_read_b128 v[156:159], v219 offset:3072
	s_add_u32 s14, s68, 0xfff80080
	s_addc_u32 s15, s69, -1
	s_cmp_eq_u32 s71, 28
	s_cselect_b32 s17, s18, s15
	s_cselect_b32 s16, s19, s14
	s_cselect_b32 s15, s41, s70
	s_cselect_b32 s14, s61, s67
	v_lshl_add_u64 v[222:223], s[68:69], 0, v[188:189]
	s_add_i32 m0, s27, 0xc000
	ds_read_b128 v[160:163], v220
	ds_read_b128 v[164:167], v220 offset:1024
	ds_read_b128 v[168:171], v220 offset:2048
	ds_read_b128 v[172:175], v220 offset:3072
	ds_read_b128 v[196:199], v220 offset:4096
	ds_read_b128 v[202:205], v220 offset:5120
	ds_read_b128 v[206:209], v220 offset:6144
	ds_read_b128 v[232:235], v220 offset:7168
	global_load_lds_dwordx4 v[222:223], off
	v_lshl_add_u64 v[222:223], s[68:69], 0, v[190:191]
	s_add_i32 m0, s27, 0xe000
	s_nop 0
	global_load_lds_dwordx4 v[222:223], off
	s_waitcnt vmcnt(8)
	s_waitcnt lgkmcnt(0)
	s_setprio 1
	s_barrier
	v_mfma_f32_16x16x32_bf16 v[124:127], v[128:131], v[160:163], v[124:127]
	v_mfma_f32_16x16x32_bf16 v[124:127], v[132:135], v[164:167], v[124:127]
	v_mfma_f32_16x16x32_bf16 v[120:123], v[136:139], v[160:163], v[120:123]
	v_mfma_f32_16x16x32_bf16 v[120:123], v[140:143], v[164:167], v[120:123]
	v_mfma_f32_16x16x32_bf16 v[108:111], v[128:131], v[168:171], v[108:111]
	v_mfma_f32_16x16x32_bf16 v[108:111], v[132:135], v[172:175], v[108:111]
	v_mfma_f32_16x16x32_bf16 v[104:107], v[136:139], v[168:171], v[104:107]
	v_mfma_f32_16x16x32_bf16 v[104:107], v[140:143], v[172:175], v[104:107]
	v_mfma_f32_16x16x32_bf16 v[92:95], v[128:131], v[196:199], v[92:95]
	v_mfma_f32_16x16x32_bf16 v[92:95], v[132:135], v[202:205], v[92:95]
	v_mfma_f32_16x16x32_bf16 v[88:91], v[136:139], v[196:199], v[88:91]
	v_mfma_f32_16x16x32_bf16 v[88:91], v[140:143], v[202:205], v[88:91]
	v_mfma_f32_16x16x32_bf16 v[76:79], v[128:131], v[206:209], v[76:79]
	v_mfma_f32_16x16x32_bf16 v[76:79], v[132:135], v[232:235], v[76:79]
	v_mfma_f32_16x16x32_bf16 v[72:75], v[136:139], v[206:209], v[72:75]
	v_mfma_f32_16x16x32_bf16 v[72:75], v[140:143], v[232:235], v[72:75]
	s_setprio 0
	s_setprio 1
	v_mfma_f32_16x16x32_bf16 v[116:119], v[144:147], v[160:163], v[116:119]
	v_mfma_f32_16x16x32_bf16 v[116:119], v[148:151], v[164:167], v[116:119]
	v_mfma_f32_16x16x32_bf16 v[112:115], v[152:155], v[160:163], v[112:115]
	v_mfma_f32_16x16x32_bf16 v[112:115], v[156:159], v[164:167], v[112:115]
	v_mfma_f32_16x16x32_bf16 v[100:103], v[144:147], v[168:171], v[100:103]
	v_mfma_f32_16x16x32_bf16 v[100:103], v[148:151], v[172:175], v[100:103]
	v_mfma_f32_16x16x32_bf16 v[96:99], v[152:155], v[168:171], v[96:99]
	v_mfma_f32_16x16x32_bf16 v[96:99], v[156:159], v[172:175], v[96:99]
	v_mfma_f32_16x16x32_bf16 v[84:87], v[144:147], v[196:199], v[84:87]
	v_mfma_f32_16x16x32_bf16 v[84:87], v[148:151], v[202:205], v[84:87]
	v_mfma_f32_16x16x32_bf16 v[80:83], v[152:155], v[196:199], v[80:83]
	v_mfma_f32_16x16x32_bf16 v[80:83], v[156:159], v[202:205], v[80:83]
	v_mfma_f32_16x16x32_bf16 v[68:71], v[144:147], v[206:209], v[68:71]
	v_mfma_f32_16x16x32_bf16 v[68:71], v[148:151], v[232:235], v[68:71]
	v_mfma_f32_16x16x32_bf16 v[64:67], v[152:155], v[206:209], v[64:67]
	v_mfma_f32_16x16x32_bf16 v[64:67], v[156:159], v[232:235], v[64:67]
	s_barrier
; #define PG8_STAGE(bufoff, gbase, voff) do { _Pragma("unroll") for (int _i = 0; _i < 2; ++_i) \
;         __builtin_amdgcn_global_load_lds((const unsigned*)((const char*)(gbase) + (voff)[_i]), (PG8_LAS unsigned*)(lds + (bufoff) + ldsw + _i * 8192), 16, 0, 0); } while (0)
; #define PG8_LDA(dst, b, h) do { _Pragma("unroll") for (int m = 0; m < 4; ++m) _Pragma("unroll") for (int k = 0; k < 2; ++k) dst[m][k] = *(const PG8_LAS bf16x8*)(lds + PG8_SA(b, h) + aoff + m * 2048 + k * 1024); } while (0)
; #define PG8_LDB(dst, b, h) do { _Pragma("unroll") for (int n = 0; n < 2; ++n) _Pragma("unroll") for (int k = 0; k < 2; ++k) dst[n][k] = *(const PG8_LAS bf16x8*)(lds + PG8_SB(b, h) + boff + n * 2048 + k * 1024); } while (0)
; #define PG8_MMA(ai, bj, At, Bt) do { __builtin_amdgcn_s_setprio(1); _Pragma("unroll") for (int m = 0; m < 4; ++m) _Pragma("unroll") for (int n = 0; n < 2; ++n) _Pragma("unroll") for (int k = 0; k < 2; ++k) \
;         acc[ai][bj][m][n] = __builtin_amdgcn_mfma_f32_16x16x32_bf16(Bt[n][k], At[m][k], acc[ai][bj][m][n], 0, 0, 0); __builtin_amdgcn_s_setprio(0); } while (0)
; #define PG8_WAIT_V(n) asm volatile("s_waitcnt vmcnt(" #n ")" ::: "memory")
; #define PG8_WAIT_L(n) asm volatile("s_waitcnt lgkmcnt(" #n ")" ::: "memory")
; #define PG8_BAR __builtin_amdgcn_s_barrier()
; #define PG8_SCHED __builtin_amdgcn_sched_barrier(0)
; template <class Epi, class Sched, bool ALIGN_EPI = false, bool SP2 = false, bool DUAL = false>
; __device__ __forceinline__ void gemm_phase(PG8_LAS unsigned char* lds, const Gemm g, const Sched& S, const Epi& E) {
;     ...
;             PG8_LDA(At, 0, 1); PG8_STAGE(PG8_SB(0, 0), b2, voffB); PG8_STAGE(PG8_SB(0, 1), b2 + hstep, voffB); PG8_STAGE(PG8_SA(0, 0), a2, voffA);
;             PG8_WAIT_V(8); PG8_WAIT_L(0); PG8_BAR; PG8_MMA(1, 0, At, B0); PG8_MMA(1, 1, At, B1); PG8_BAR; PG8_SCHED;
;             PG8_LDB(B0, 1, 0); PG8_LDB(B1, 1, 1); PG8_SCHED; PG8_LDA(At, 1, 0); PG8_STAGE(PG8_SA(0, 1), a2 + hstep, voffA);
;             PG8_WAIT_V(8); PG8_WAIT_L(0); PG8_BAR; PG8_MMA(0, 0, At, B0); PG8_MMA(0, 1, At, B1); PG8_BAR; PG8_SCHED;
	s_setprio 0
	s_add_i32 s72, s48, s26
	v_lshl_add_u64 v[222:223], s[14:15], 0, v[182:183]
	s_mov_b32 m0, s72
	ds_read_b128 v[160:163], v220 offset:16384
	ds_read_b128 v[164:167], v220 offset:17408
	ds_read_b128 v[168:171], v220 offset:18432
	ds_read_b128 v[172:175], v220 offset:19456
	ds_read_b128 v[196:199], v220 offset:20480
	ds_read_b128 v[202:205], v220 offset:21504
	ds_read_b128 v[206:209], v220 offset:22528
	ds_read_b128 v[232:235], v220 offset:23552
	global_load_lds_dwordx4 v[222:223], off
	s_add_i32 m0, s72, 0x2000
	s_add_u32 s72, s14, 0x80000
	v_lshl_add_u64 v[228:229], s[14:15], 0, v[186:187]
	s_addc_u32 s73, s15, 0
	s_add_i32 s74, s49, s26
	global_load_lds_dwordx4 v[228:229], off
	v_lshl_add_u64 v[236:237], s[72:73], 0, v[182:183]
	s_mov_b32 m0, s74
	v_lshl_add_u64 v[238:239], s[16:17], 0, v[184:185]
	global_load_lds_dwordx4 v[236:237], off
	v_lshl_add_u64 v[236:237], s[72:73], 0, v[186:187]
	s_add_i32 m0, s74, 0x2000
	s_nop 0
	global_load_lds_dwordx4 v[236:237], off
	v_lshl_add_u64 v[236:237], s[16:17], 0, v[180:181]
	s_mov_b32 m0, s27
	s_nop 0
	global_load_lds_dwordx4 v[236:237], off
	s_mov_b32 m0, s28
	s_nop 0
	global_load_lds_dwordx4 v[238:239], off
	s_waitcnt vmcnt(8)
	s_waitcnt lgkmcnt(0)
	s_setprio 1
	s_barrier
	v_mfma_f32_16x16x32_bf16 v[60:63], v[128:131], v[160:163], v[60:63]
	v_mfma_f32_16x16x32_bf16 v[60:63], v[132:135], v[164:167], v[60:63]
	v_mfma_f32_16x16x32_bf16 v[56:59], v[136:139], v[160:163], v[56:59]
	v_mfma_f32_16x16x32_bf16 v[56:59], v[140:143], v[164:167], v[56:59]
	v_mfma_f32_16x16x32_bf16 v[44:47], v[128:131], v[168:171], v[44:47]
	v_mfma_f32_16x16x32_bf16 v[44:47], v[132:135], v[172:175], v[44:47]
	v_mfma_f32_16x16x32_bf16 v[40:43], v[136:139], v[168:171], v[40:43]
	v_mfma_f32_16x16x32_bf16 v[40:43], v[140:143], v[172:175], v[40:43]
	v_mfma_f32_16x16x32_bf16 v[28:31], v[128:131], v[196:199], v[28:31]
	v_mfma_f32_16x16x32_bf16 v[28:31], v[132:135], v[202:205], v[28:31]
	v_mfma_f32_16x16x32_bf16 v[24:27], v[136:139], v[196:199], v[24:27]
	v_mfma_f32_16x16x32_bf16 v[24:27], v[140:143], v[202:205], v[24:27]
	v_mfma_f32_16x16x32_bf16 v[12:15], v[128:131], v[206:209], v[12:15]
	v_mfma_f32_16x16x32_bf16 v[12:15], v[132:135], v[232:235], v[12:15]
	v_mfma_f32_16x16x32_bf16 v[8:11], v[136:139], v[206:209], v[8:11]
	v_mfma_f32_16x16x32_bf16 v[8:11], v[140:143], v[232:235], v[8:11]
	s_setprio 0
	s_setprio 1
	v_mfma_f32_16x16x32_bf16 v[52:55], v[144:147], v[160:163], v[52:55]
	v_mfma_f32_16x16x32_bf16 v[52:55], v[148:151], v[164:167], v[52:55]
	v_mfma_f32_16x16x32_bf16 v[48:51], v[152:155], v[160:163], v[48:51]
	v_mfma_f32_16x16x32_bf16 v[48:51], v[156:159], v[164:167], v[48:51]
	v_mfma_f32_16x16x32_bf16 v[36:39], v[144:147], v[168:171], v[36:39]
	v_mfma_f32_16x16x32_bf16 v[36:39], v[148:151], v[172:175], v[36:39]
	v_mfma_f32_16x16x32_bf16 v[32:35], v[152:155], v[168:171], v[32:35]
	v_mfma_f32_16x16x32_bf16 v[32:35], v[156:159], v[172:175], v[32:35]
	v_mfma_f32_16x16x32_bf16 v[20:23], v[144:147], v[196:199], v[20:23]
	v_mfma_f32_16x16x32_bf16 v[20:23], v[148:151], v[202:205], v[20:23]
	v_mfma_f32_16x16x32_bf16 v[16:19], v[152:155], v[196:199], v[16:19]
	v_mfma_f32_16x16x32_bf16 v[16:19], v[156:159], v[202:205], v[16:19]
	v_mfma_f32_16x16x32_bf16 v[4:7], v[144:147], v[206:209], v[4:7]
	v_mfma_f32_16x16x32_bf16 v[4:7], v[148:151], v[232:235], v[4:7]
	v_mfma_f32_16x16x32_bf16 v[0:3], v[152:155], v[206:209], v[0:3]
	v_mfma_f32_16x16x32_bf16 v[0:3], v[156:159], v[232:235], v[0:3]
	s_barrier
	s_setprio 0
	s_add_i32 s72, 0, 0x18000
	s_add_i32 s73, 0, 0x1c000
	v_add_u32_e32 v140, s72, v216
	v_add_u32_e32 v156, s73, v216
	ds_read_b128 v[128:131], v140
	ds_read_b128 v[132:135], v140 offset:1024
	ds_read_b128 v[136:139], v140 offset:2048
	ds_read_b128 v[140:143], v140 offset:3072
	ds_read_b128 v[144:147], v156
	ds_read_b128 v[148:151], v156 offset:1024
	ds_read_b128 v[152:155], v156 offset:2048
	ds_read_b128 v[156:159], v156 offset:3072
	s_add_u32 s16, s16, 0x80000
	s_addc_u32 s17, s17, 0
	s_mov_b32 m0, s29
	v_lshl_add_u64 v[240:241], s[16:17], 0, v[180:181]
	ds_read_b128 v[160:163], v220 offset:32768
	ds_read_b128 v[164:167], v220 offset:33792
	ds_read_b128 v[168:171], v220 offset:34816
	ds_read_b128 v[172:175], v220 offset:35840
	ds_read_b128 v[196:199], v220 offset:36864
	ds_read_b128 v[202:205], v220 offset:37888
	ds_read_b128 v[206:209], v220 offset:38912
	ds_read_b128 v[232:235], v220 offset:39936
	global_load_lds_dwordx4 v[240:241], off
	v_lshl_add_u64 v[240:241], s[16:17], 0, v[184:185]
	s_mov_b32 m0, s34
	s_nop 0
	global_load_lds_dwordx4 v[240:241], off
	s_waitcnt vmcnt(8)
	s_waitcnt lgkmcnt(0)
	s_setprio 1
	s_barrier
; #define PG8_STAGE(bufoff, gbase, voff) do { _Pragma("unroll") for (int _i = 0; _i < 2; ++_i) \
;         __builtin_amdgcn_global_load_lds((const unsigned*)((const char*)(gbase) + (voff)[_i]), (PG8_LAS unsigned*)(lds + (bufoff) + ldsw + _i * 8192), 16, 0, 0); } while (0)
; #define PG8_LDA(dst, b, h) do { _Pragma("unroll") for (int m = 0; m < 4; ++m) _Pragma("unroll") for (int k = 0; k < 2; ++k) dst[m][k] = *(const PG8_LAS bf16x8*)(lds + PG8_SA(b, h) + aoff + m * 2048 + k * 1024); } while (0)
; #define PG8_MMA(ai, bj, At, Bt) do { __builtin_amdgcn_s_setprio(1); _Pragma("unroll") for (int m = 0; m < 4; ++m) _Pragma("unroll") for (int n = 0; n < 2; ++n) _Pragma("unroll") for (int k = 0; k < 2; ++k) \
;         acc[ai][bj][m][n] = __builtin_amdgcn_mfma_f32_16x16x32_bf16(Bt[n][k], At[m][k], acc[ai][bj][m][n], 0, 0, 0); __builtin_amdgcn_s_setprio(0); } while (0)
; #define PG8_WAIT_V(n) asm volatile("s_waitcnt vmcnt(" #n ")" ::: "memory")
; #define PG8_WAIT_L(n) asm volatile("s_waitcnt lgkmcnt(" #n ")" ::: "memory")
; #define PG8_BAR __builtin_amdgcn_s_barrier()
; #define PG8_SCHED __builtin_amdgcn_sched_barrier(0)
; template <class Epi, class Sched, bool ALIGN_EPI = false, bool SP2 = false, bool DUAL = false>
; __device__ __forceinline__ void gemm_phase(PG8_LAS unsigned char* lds, const Gemm g, const Sched& S, const Epi& E) {
;     ...
;             PG8_WAIT_V(8); PG8_WAIT_L(0); PG8_BAR; PG8_MMA(0, 0, At, B0); PG8_MMA(0, 1, At, B1); PG8_BAR; PG8_SCHED;
;             PG8_LDA(At, 1, 1); PG8_STAGE(PG8_SB(1, 0), b3, voffB); PG8_STAGE(PG8_SB(1, 1), b3 + hstep, voffB); PG8_STAGE(PG8_SA(1, 0), a3, voffA);
;             PG8_WAIT_V(8); PG8_WAIT_L(0); PG8_BAR; PG8_MMA(1, 0, At, B0); PG8_MMA(1, 1, At, B1); PG8_BAR; PG8_SCHED;
	v_mfma_f32_16x16x32_bf16 v[124:127], v[128:131], v[160:163], v[124:127]
	v_mfma_f32_16x16x32_bf16 v[124:127], v[132:135], v[164:167], v[124:127]
	v_mfma_f32_16x16x32_bf16 v[120:123], v[136:139], v[160:163], v[120:123]
	v_mfma_f32_16x16x32_bf16 v[120:123], v[140:143], v[164:167], v[120:123]
	v_mfma_f32_16x16x32_bf16 v[108:111], v[128:131], v[168:171], v[108:111]
	v_mfma_f32_16x16x32_bf16 v[108:111], v[132:135], v[172:175], v[108:111]
	v_mfma_f32_16x16x32_bf16 v[104:107], v[136:139], v[168:171], v[104:107]
	v_mfma_f32_16x16x32_bf16 v[104:107], v[140:143], v[172:175], v[104:107]
	v_mfma_f32_16x16x32_bf16 v[92:95], v[128:131], v[196:199], v[92:95]
	v_mfma_f32_16x16x32_bf16 v[92:95], v[132:135], v[202:205], v[92:95]
	v_mfma_f32_16x16x32_bf16 v[88:91], v[136:139], v[196:199], v[88:91]
	v_mfma_f32_16x16x32_bf16 v[88:91], v[140:143], v[202:205], v[88:91]
	v_mfma_f32_16x16x32_bf16 v[76:79], v[128:131], v[206:209], v[76:79]
	v_mfma_f32_16x16x32_bf16 v[76:79], v[132:135], v[232:235], v[76:79]
	v_mfma_f32_16x16x32_bf16 v[72:75], v[136:139], v[206:209], v[72:75]
	v_mfma_f32_16x16x32_bf16 v[72:75], v[140:143], v[232:235], v[72:75]
	s_setprio 0
	s_setprio 1
	v_mfma_f32_16x16x32_bf16 v[116:119], v[144:147], v[160:163], v[116:119]
	v_mfma_f32_16x16x32_bf16 v[116:119], v[148:151], v[164:167], v[116:119]
	v_mfma_f32_16x16x32_bf16 v[112:115], v[152:155], v[160:163], v[112:115]
	v_mfma_f32_16x16x32_bf16 v[112:115], v[156:159], v[164:167], v[112:115]
	v_mfma_f32_16x16x32_bf16 v[100:103], v[144:147], v[168:171], v[100:103]
	v_mfma_f32_16x16x32_bf16 v[100:103], v[148:151], v[172:175], v[100:103]
	v_mfma_f32_16x16x32_bf16 v[96:99], v[152:155], v[168:171], v[96:99]
	v_mfma_f32_16x16x32_bf16 v[96:99], v[156:159], v[172:175], v[96:99]
	v_mfma_f32_16x16x32_bf16 v[84:87], v[144:147], v[196:199], v[84:87]
	v_mfma_f32_16x16x32_bf16 v[84:87], v[148:151], v[202:205], v[84:87]
	v_mfma_f32_16x16x32_bf16 v[80:83], v[152:155], v[196:199], v[80:83]
	v_mfma_f32_16x16x32_bf16 v[80:83], v[156:159], v[202:205], v[80:83]
	v_mfma_f32_16x16x32_bf16 v[68:71], v[144:147], v[206:209], v[68:71]
	v_mfma_f32_16x16x32_bf16 v[68:71], v[148:151], v[232:235], v[68:71]
	v_mfma_f32_16x16x32_bf16 v[64:67], v[152:155], v[206:209], v[64:67]
	v_mfma_f32_16x16x32_bf16 v[64:67], v[156:159], v[232:235], v[64:67]
	s_barrier
	s_setprio 0
	s_add_i32 s16, s72, s26
	v_lshl_add_u64 v[222:223], v[222:223], 0, s[36:37]
	s_mov_b32 m0, s16
	ds_read_b128 v[160:163], v220 offset:49152
	ds_read_b128 v[164:167], v220 offset:50176
	ds_read_b128 v[168:171], v220 offset:51200
	ds_read_b128 v[172:175], v220 offset:52224
	ds_read_b128 v[196:199], v220 offset:53248
	ds_read_b128 v[202:205], v220 offset:54272
	ds_read_b128 v[206:209], v220 offset:55296
	ds_read_b128 v[232:235], v220 offset:56320
	global_load_lds_dwordx4 v[222:223], off
	s_add_i32 m0, s16, 0x2000
	s_add_u32 s14, s14, 0x80080
	v_lshl_add_u64 v[222:223], v[228:229], 0, s[36:37]
	s_addc_u32 s15, s15, 0
	s_add_i32 s16, s73, s26
	global_load_lds_dwordx4 v[222:223], off
	v_lshl_add_u64 v[222:223], s[14:15], 0, v[182:183]
	s_mov_b32 m0, s16
	s_nop 0
	global_load_lds_dwordx4 v[222:223], off
	v_lshl_add_u64 v[222:223], s[14:15], 0, v[186:187]
	s_add_i32 m0, s16, 0x2000
	s_nop 0
	global_load_lds_dwordx4 v[222:223], off
	v_lshl_add_u64 v[222:223], v[236:237], 0, s[36:37]
	s_mov_b32 m0, s44
	s_nop 0
	global_load_lds_dwordx4 v[222:223], off
	v_lshl_add_u64 v[222:223], v[238:239], 0, s[36:37]
	s_mov_b32 m0, s45
	s_nop 0
	global_load_lds_dwordx4 v[222:223], off
	s_waitcnt vmcnt(8)
	s_waitcnt lgkmcnt(0)
	s_setprio 1
	s_barrier
	v_mfma_f32_16x16x32_bf16 v[60:63], v[128:131], v[160:163], v[60:63]
	v_mfma_f32_16x16x32_bf16 v[60:63], v[132:135], v[164:167], v[60:63]
	v_mfma_f32_16x16x32_bf16 v[56:59], v[136:139], v[160:163], v[56:59]
	v_mfma_f32_16x16x32_bf16 v[56:59], v[140:143], v[164:167], v[56:59]
	v_mfma_f32_16x16x32_bf16 v[44:47], v[128:131], v[168:171], v[44:47]
	v_mfma_f32_16x16x32_bf16 v[44:47], v[132:135], v[172:175], v[44:47]
	v_mfma_f32_16x16x32_bf16 v[40:43], v[136:139], v[168:171], v[40:43]
	v_mfma_f32_16x16x32_bf16 v[40:43], v[140:143], v[172:175], v[40:43]
	v_mfma_f32_16x16x32_bf16 v[28:31], v[128:131], v[196:199], v[28:31]
	v_mfma_f32_16x16x32_bf16 v[28:31], v[132:135], v[202:205], v[28:31]
	v_mfma_f32_16x16x32_bf16 v[24:27], v[136:139], v[196:199], v[24:27]
	v_mfma_f32_16x16x32_bf16 v[24:27], v[140:143], v[202:205], v[24:27]
	v_mfma_f32_16x16x32_bf16 v[12:15], v[128:131], v[206:209], v[12:15]
	v_mfma_f32_16x16x32_bf16 v[12:15], v[132:135], v[232:235], v[12:15]
	v_mfma_f32_16x16x32_bf16 v[8:11], v[136:139], v[206:209], v[8:11]
	v_mfma_f32_16x16x32_bf16 v[8:11], v[140:143], v[232:235], v[8:11]
	s_setprio 0
	s_setprio 1
	v_mfma_f32_16x16x32_bf16 v[52:55], v[144:147], v[160:163], v[52:55]
	v_mfma_f32_16x16x32_bf16 v[52:55], v[148:151], v[164:167], v[52:55]
	v_mfma_f32_16x16x32_bf16 v[48:51], v[152:155], v[160:163], v[48:51]
	v_mfma_f32_16x16x32_bf16 v[48:51], v[156:159], v[164:167], v[48:51]
	v_mfma_f32_16x16x32_bf16 v[36:39], v[144:147], v[168:171], v[36:39]
	v_mfma_f32_16x16x32_bf16 v[36:39], v[148:151], v[172:175], v[36:39]
	v_mfma_f32_16x16x32_bf16 v[32:35], v[152:155], v[168:171], v[32:35]
	v_mfma_f32_16x16x32_bf16 v[32:35], v[156:159], v[172:175], v[32:35]
	v_mfma_f32_16x16x32_bf16 v[20:23], v[144:147], v[196:199], v[20:23]
	v_mfma_f32_16x16x32_bf16 v[20:23], v[148:151], v[202:205], v[20:23]
	v_mfma_f32_16x16x32_bf16 v[16:19], v[152:155], v[196:199], v[16:19]
	v_mfma_f32_16x16x32_bf16 v[16:19], v[156:159], v[202:205], v[16:19]
	v_mfma_f32_16x16x32_bf16 v[4:7], v[144:147], v[206:209], v[4:7]
	v_mfma_f32_16x16x32_bf16 v[4:7], v[148:151], v[232:235], v[4:7]
	v_mfma_f32_16x16x32_bf16 v[0:3], v[152:155], v[206:209], v[0:3]
	v_mfma_f32_16x16x32_bf16 v[0:3], v[156:159], v[232:235], v[0:3]
	s_barrier
	s_setprio 0
	s_add_i32 s71, s71, 2
	s_add_u32 s68, s68, 0x100
	s_addc_u32 s69, s69, 0
	s_add_u32 s67, s67, 0x100
	s_addc_u32 s70, s70, 0
	s_cmp_gt_u32 s71, 29
	s_cbranch_scc0 .LBB0_896
	s_and_b64 vcc, exec, s[38:39]
	s_cbranch_vccz .LBB0_899
	s_barrier

;     __device__ bool next(int i, Unit& u) const { if (!base.next(i >> 1, u)) return false; u.sub = i & 1; return true; }
; #define PG8_STAGE(bufoff, gbase, voff) do { _Pragma("unroll") for (int _i = 0; _i < 2; ++_i) \
;         __builtin_amdgcn_global_load_lds((const unsigned*)((const char*)(gbase) + (voff)[_i]), (PG8_LAS unsigned*)(lds + (bufoff) + ldsw + _i * 8192), 16, 0, 0); } while (0)
; #define PG8_LDA(dst, b, h) do { _Pragma("unroll") for (int m = 0; m < 4; ++m) _Pragma("unroll") for (int k = 0; k < 2; ++k) dst[m][k] = *(const PG8_LAS bf16x8*)(lds + PG8_SA(b, h) + aoff + m * 2048 + k * 1024); } while (0)
; template <class Epi, class Sched, bool ALIGN_EPI = false, bool SP2 = false, bool DUAL = false>
; __device__ __forceinline__ void gemm_phase(PG8_LAS unsigned char* lds, const Gemm g, const Sched& S, const Epi& E) {
;     ...
;     for (;;) {
;         const bool has_next = S.next(ui + 1, nxt);
;         const char* nA = has_next ? (const char*)((DUAL && nxt.sub) ? g.A2 : g.A) + (size_t)nxt.pm * tstep : cA; const char* nB = has_next ? (const char*)((DUAL && nxt.sub) ? g.Bt2 : g.Bt) + (size_t)nxt.pn * tstep : cB;
;         for (int t = 0; t < nt; t += 2) {
;             const bool last = (t == nt - 2);
;             const char* a1 = cA + (size_t)(t + 1) * kstep;
;             const char* a2 = last ? nA : cA + (size_t)(t + 2) * kstep; const char* b2 = last ? nB : cB + (size_t)(t + 2) * kstep;
;             const char* a3 = a2 + kstep; const char* b3 = b2 + kstep;
;             if (last && has_next) S.a_ready(nxt);
;             if constexpr (SP2) {
;             PG8_LDB(B0, 0, 0); PG8_LDB(B1, 0, 1); PG8_SCHED; PG8_LDA(At, 0, 0); PG8_STAGE(PG8_SA(1, 1), a1 + hstep, voffA);
;             PG8_WAIT_V(8); PG8_WAIT_L(0); PG8_BAR; PG8_MMA(0, 0, At, B0); PG8_MMA(0, 1, At, B1); PG8_BAR; PG8_SCHED;
;             PG8_LDA(At, 0, 1); PG8_STAGE(PG8_SB(0, 0), b2, voffB); PG8_STAGE(PG8_SB(0, 1), b2 + hstep, voffB); PG8_STAGE(PG8_SA(0, 0), a2, voffA);
;             PG8_WAIT_V(8); PG8_WAIT_L(0); PG8_BAR; PG8_MMA(1, 0, At, B0); PG8_MMA(1, 1, At, B1); PG8_BAR; PG8_SCHED;
;     ...
;         for (int a = 0; a < 2; ++a)
; #pragma unroll
;             for (int b = 0; b < 2; ++b)
; #pragma unroll
;                 for (int m = 0; m < 4; ++m)
; #pragma unroll
;                     for (int n = 0; n < 2; ++n) acc[a][b][m][n] = (f32x4){0.f, 0.f, 0.f, 0.f};
.LBB0_991:
	s_ashr_i32 s25, s24, 31
	s_lshl_b64 s[28:29], s[24:25], 20
	s_add_u32 s30, s19, s28
	s_addc_u32 s31, s21, s29
	s_and_b64 s[28:29], s[4:5], exec
	s_cselect_b32 s25, s31, s27
	s_cselect_b32 s28, s30, s26
	s_ashr_i32 s23, s22, 31
	s_lshl_b64 s[36:37], s[22:23], 20
	s_add_u32 s36, s8, s36
	s_addc_u32 s37, s9, s37
	s_and_b64 s[40:41], s[4:5], exec
	s_cselect_b32 s23, s37, s15
	s_cselect_b32 s29, s36, s14
	s_add_u32 s40, s26, 0x80080
	s_addc_u32 s41, s27, 0
	s_add_u32 s63, s14, 0x100
	s_addc_u32 s64, s15, 0
	s_mov_b32 s65, -2
	s_add_u32 s14, s40, 0xfff80080
	s_addc_u32 s15, s41, -1
	s_cmp_eq_u32 s65, 28
	s_cselect_b32 s27, s25, s15
	s_cselect_b32 s26, s28, s14
	s_cselect_b32 s15, s23, s64
	s_cselect_b32 s14, s29, s63
	s_waitcnt vmcnt(8)
	s_waitcnt lgkmcnt(0)
	s_setprio 1
	s_barrier
	v_mfma_f32_16x16x32_bf16 v[124:127], v[128:131], v[160:163], 0
	v_mfma_f32_16x16x32_bf16 v[124:127], v[132:135], v[164:167], v[124:127]
	v_mfma_f32_16x16x32_bf16 v[120:123], v[136:139], v[160:163], 0
	v_mfma_f32_16x16x32_bf16 v[120:123], v[140:143], v[164:167], v[120:123]
	v_mfma_f32_16x16x32_bf16 v[108:111], v[128:131], v[188:191], 0
	v_mfma_f32_16x16x32_bf16 v[108:111], v[132:135], v[192:195], v[108:111]
	v_mfma_f32_16x16x32_bf16 v[104:107], v[136:139], v[188:191], 0
	v_mfma_f32_16x16x32_bf16 v[104:107], v[140:143], v[192:195], v[104:107]
	v_mfma_f32_16x16x32_bf16 v[92:95], v[128:131], v[196:199], 0
	v_mfma_f32_16x16x32_bf16 v[92:95], v[132:135], v[202:205], v[92:95]
	v_mfma_f32_16x16x32_bf16 v[88:91], v[136:139], v[196:199], 0
	v_mfma_f32_16x16x32_bf16 v[88:91], v[140:143], v[202:205], v[88:91]
	v_mfma_f32_16x16x32_bf16 v[76:79], v[128:131], v[206:209], 0
	v_mfma_f32_16x16x32_bf16 v[76:79], v[132:135], v[220:223], v[76:79]
	v_mfma_f32_16x16x32_bf16 v[72:75], v[136:139], v[206:209], 0
	v_mfma_f32_16x16x32_bf16 v[72:75], v[140:143], v[220:223], v[72:75]
	s_setprio 0
	s_setprio 1
	v_mfma_f32_16x16x32_bf16 v[116:119], v[144:147], v[160:163], 0
	v_mfma_f32_16x16x32_bf16 v[116:119], v[148:151], v[164:167], v[116:119]
	v_mfma_f32_16x16x32_bf16 v[112:115], v[152:155], v[160:163], 0
	v_mfma_f32_16x16x32_bf16 v[112:115], v[156:159], v[164:167], v[112:115]
	v_mfma_f32_16x16x32_bf16 v[100:103], v[144:147], v[188:191], 0
	v_mfma_f32_16x16x32_bf16 v[100:103], v[148:151], v[192:195], v[100:103]
	v_mfma_f32_16x16x32_bf16 v[96:99], v[152:155], v[188:191], 0
	v_mfma_f32_16x16x32_bf16 v[96:99], v[156:159], v[192:195], v[96:99]
	v_mfma_f32_16x16x32_bf16 v[84:87], v[144:147], v[196:199], 0
	v_mfma_f32_16x16x32_bf16 v[84:87], v[148:151], v[202:205], v[84:87]
	v_mfma_f32_16x16x32_bf16 v[80:83], v[152:155], v[196:199], 0
	v_mfma_f32_16x16x32_bf16 v[80:83], v[156:159], v[202:205], v[80:83]
	v_mfma_f32_16x16x32_bf16 v[68:71], v[144:147], v[206:209], 0
	v_mfma_f32_16x16x32_bf16 v[68:71], v[148:151], v[220:223], v[68:71]
	v_mfma_f32_16x16x32_bf16 v[64:67], v[152:155], v[206:209], 0
	v_mfma_f32_16x16x32_bf16 v[64:67], v[156:159], v[220:223], v[64:67]
	s_barrier
	s_setprio 0
	v_lshl_add_u64 v[228:229], s[40:41], 0, v[180:181]
	s_add_i32 m0, s39, 0xc000
	s_nop 0
	global_load_lds_dwordx4 v[228:229], off
	v_lshl_add_u64 v[228:229], s[40:41], 0, v[182:183]
	s_add_i32 m0, s39, 0xe000
	s_nop 0
	global_load_lds_dwordx4 v[228:229], off
	s_add_i32 s66, s50, s34
	v_lshl_add_u64 v[228:229], s[14:15], 0, v[170:171]
	s_mov_b32 m0, s66
	ds_read_b128 v[160:163], v217 offset:16384
	ds_read_b128 v[164:167], v217 offset:17408
	ds_read_b128 v[188:191], v217 offset:18432
	ds_read_b128 v[192:195], v217 offset:19456
	ds_read_b128 v[196:199], v217 offset:20480
	ds_read_b128 v[202:205], v217 offset:21504
	ds_read_b128 v[206:209], v217 offset:22528
	ds_read_b128 v[220:223], v217 offset:23552
	global_load_lds_dwordx4 v[228:229], off
	s_add_i32 m0, s66, 0x2000
	s_add_u32 s66, s14, 0x80000
	v_lshl_add_u64 v[232:233], s[14:15], 0, v[174:175]
	s_addc_u32 s67, s15, 0
	s_add_i32 s68, s51, s34
	global_load_lds_dwordx4 v[232:233], off
	v_lshl_add_u64 v[234:235], s[66:67], 0, v[170:171]
	s_mov_b32 m0, s68
	v_lshl_add_u64 v[236:237], s[26:27], 0, v[172:173]
	global_load_lds_dwordx4 v[234:235], off
	v_lshl_add_u64 v[234:235], s[66:67], 0, v[174:175]
	s_add_i32 m0, s68, 0x2000
	s_nop 0
	global_load_lds_dwordx4 v[234:235], off
	v_lshl_add_u64 v[234:235], s[26:27], 0, v[168:169]
	s_mov_b32 m0, s39
	s_nop 0
	global_load_lds_dwordx4 v[234:235], off
	s_mov_b32 m0, s42
	s_nop 0
	global_load_lds_dwordx4 v[236:237], off
	s_waitcnt vmcnt(8)
	s_waitcnt lgkmcnt(0)
	s_setprio 1
	s_barrier
	v_mfma_f32_16x16x32_bf16 v[60:63], v[128:131], v[160:163], 0
	v_mfma_f32_16x16x32_bf16 v[60:63], v[132:135], v[164:167], v[60:63]
	v_mfma_f32_16x16x32_bf16 v[56:59], v[136:139], v[160:163], 0
	v_mfma_f32_16x16x32_bf16 v[56:59], v[140:143], v[164:167], v[56:59]
	v_mfma_f32_16x16x32_bf16 v[44:47], v[128:131], v[188:191], 0
	v_mfma_f32_16x16x32_bf16 v[44:47], v[132:135], v[192:195], v[44:47]
	v_mfma_f32_16x16x32_bf16 v[40:43], v[136:139], v[188:191], 0
	v_mfma_f32_16x16x32_bf16 v[40:43], v[140:143], v[192:195], v[40:43]
	v_mfma_f32_16x16x32_bf16 v[28:31], v[128:131], v[196:199], 0
	v_mfma_f32_16x16x32_bf16 v[28:31], v[132:135], v[202:205], v[28:31]
	v_mfma_f32_16x16x32_bf16 v[24:27], v[136:139], v[196:199], 0
	v_mfma_f32_16x16x32_bf16 v[24:27], v[140:143], v[202:205], v[24:27]
	v_mfma_f32_16x16x32_bf16 v[12:15], v[128:131], v[206:209], 0
	v_mfma_f32_16x16x32_bf16 v[12:15], v[132:135], v[220:223], v[12:15]
	v_mfma_f32_16x16x32_bf16 v[8:11], v[136:139], v[206:209], 0
	v_mfma_f32_16x16x32_bf16 v[8:11], v[140:143], v[220:223], v[8:11]
	s_setprio 0
	s_setprio 1
	v_mfma_f32_16x16x32_bf16 v[52:55], v[144:147], v[160:163], 0
	v_mfma_f32_16x16x32_bf16 v[52:55], v[148:151], v[164:167], v[52:55]
	v_mfma_f32_16x16x32_bf16 v[48:51], v[152:155], v[160:163], 0
	v_mfma_f32_16x16x32_bf16 v[48:51], v[156:159], v[164:167], v[48:51]
	v_mfma_f32_16x16x32_bf16 v[36:39], v[144:147], v[188:191], 0
	v_mfma_f32_16x16x32_bf16 v[36:39], v[148:151], v[192:195], v[36:39]
	v_mfma_f32_16x16x32_bf16 v[32:35], v[152:155], v[188:191], 0
	v_mfma_f32_16x16x32_bf16 v[32:35], v[156:159], v[192:195], v[32:35]
	v_mfma_f32_16x16x32_bf16 v[20:23], v[144:147], v[196:199], 0
	v_mfma_f32_16x16x32_bf16 v[20:23], v[148:151], v[202:205], v[20:23]
	v_mfma_f32_16x16x32_bf16 v[16:19], v[152:155], v[196:199], 0
	v_mfma_f32_16x16x32_bf16 v[16:19], v[156:159], v[202:205], v[16:19]
	v_mfma_f32_16x16x32_bf16 v[4:7], v[144:147], v[206:209], 0
	v_mfma_f32_16x16x32_bf16 v[4:7], v[148:151], v[220:223], v[4:7]
	v_mfma_f32_16x16x32_bf16 v[0:3], v[152:155], v[206:209], 0
	v_mfma_f32_16x16x32_bf16 v[0:3], v[156:159], v[220:223], v[0:3]
	s_barrier
; #define PG8_STAGE(bufoff, gbase, voff) do { _Pragma("unroll") for (int _i = 0; _i < 2; ++_i) \
;         __builtin_amdgcn_global_load_lds((const unsigned*)((const char*)(gbase) + (voff)[_i]), (PG8_LAS unsigned*)(lds + (bufoff) + ldsw + _i * 8192), 16, 0, 0); } while (0)
; #define PG8_LDA(dst, b, h) do { _Pragma("unroll") for (int m = 0; m < 4; ++m) _Pragma("unroll") for (int k = 0; k < 2; ++k) dst[m][k] = *(const PG8_LAS bf16x8*)(lds + PG8_SA(b, h) + aoff + m * 2048 + k * 1024); } while (0)
; #define PG8_LDB(dst, b, h) do { _Pragma("unroll") for (int n = 0; n < 2; ++n) _Pragma("unroll") for (int k = 0; k < 2; ++k) dst[n][k] = *(const PG8_LAS bf16x8*)(lds + PG8_SB(b, h) + boff + n * 2048 + k * 1024); } while (0)
; #define PG8_MMA(ai, bj, At, Bt) do { __builtin_amdgcn_s_setprio(1); _Pragma("unroll") for (int m = 0; m < 4; ++m) _Pragma("unroll") for (int n = 0; n < 2; ++n) _Pragma("unroll") for (int k = 0; k < 2; ++k) \
;         acc[ai][bj][m][n] = __builtin_amdgcn_mfma_f32_16x16x32_bf16(Bt[n][k], At[m][k], acc[ai][bj][m][n], 0, 0, 0); __builtin_amdgcn_s_setprio(0); } while (0)
; #define PG8_WAIT_V(n) asm volatile("s_waitcnt vmcnt(" #n ")" ::: "memory")
; #define PG8_WAIT_L(n) asm volatile("s_waitcnt lgkmcnt(" #n ")" ::: "memory")
; #define PG8_BAR __builtin_amdgcn_s_barrier()
; #define PG8_SCHED __builtin_amdgcn_sched_barrier(0)
; template <class Epi, class Sched, bool ALIGN_EPI = false, bool SP2 = false, bool DUAL = false>
; __device__ __forceinline__ void gemm_phase(PG8_LAS unsigned char* lds, const Gemm g, const Sched& S, const Epi& E) {
;     ...
;             PG8_LDB(B0, 1, 0); PG8_LDB(B1, 1, 1); PG8_SCHED; PG8_LDA(At, 1, 0); PG8_STAGE(PG8_SA(0, 1), a2 + hstep, voffA);
;             PG8_WAIT_V(8); PG8_WAIT_L(0); PG8_BAR; PG8_MMA(0, 0, At, B0); PG8_MMA(0, 1, At, B1); PG8_BAR; PG8_SCHED;
;             PG8_LDA(At, 1, 1); PG8_STAGE(PG8_SB(1, 0), b3, voffB); PG8_STAGE(PG8_SB(1, 1), b3 + hstep, voffB); PG8_STAGE(PG8_SA(1, 0), a3, voffA);
	s_setprio 0
	s_add_i32 s66, 0, 0x18000
	s_add_i32 s67, 0, 0x1c000
	v_add_u32_e32 v140, s66, v213
	v_add_u32_e32 v156, s67, v213
	ds_read_b128 v[128:131], v140
	ds_read_b128 v[132:135], v140 offset:1024
	ds_read_b128 v[136:139], v140 offset:2048
	ds_read_b128 v[140:143], v140 offset:3072
	ds_read_b128 v[144:147], v156
	ds_read_b128 v[148:151], v156 offset:1024
	ds_read_b128 v[152:155], v156 offset:2048
	ds_read_b128 v[156:159], v156 offset:3072
	s_add_u32 s26, s26, 0x80000
	s_addc_u32 s27, s27, 0
	s_mov_b32 m0, s43
	v_lshl_add_u64 v[238:239], s[26:27], 0, v[168:169]
	ds_read_b128 v[160:163], v217 offset:32768
	ds_read_b128 v[164:167], v217 offset:33792
	ds_read_b128 v[188:191], v217 offset:34816
	ds_read_b128 v[192:195], v217 offset:35840
	ds_read_b128 v[196:199], v217 offset:36864
	ds_read_b128 v[202:205], v217 offset:37888
	ds_read_b128 v[206:209], v217 offset:38912
	ds_read_b128 v[220:223], v217 offset:39936
	global_load_lds_dwordx4 v[238:239], off
	v_lshl_add_u64 v[238:239], s[26:27], 0, v[172:173]
	s_mov_b32 m0, s44
	s_nop 0
	global_load_lds_dwordx4 v[238:239], off
	s_waitcnt vmcnt(8)
	s_waitcnt lgkmcnt(0)
	s_setprio 1
	s_barrier
	v_mfma_f32_16x16x32_bf16 v[124:127], v[128:131], v[160:163], v[124:127]
	v_mfma_f32_16x16x32_bf16 v[124:127], v[132:135], v[164:167], v[124:127]
	v_mfma_f32_16x16x32_bf16 v[120:123], v[136:139], v[160:163], v[120:123]
	v_mfma_f32_16x16x32_bf16 v[120:123], v[140:143], v[164:167], v[120:123]
	v_mfma_f32_16x16x32_bf16 v[108:111], v[128:131], v[188:191], v[108:111]
	v_mfma_f32_16x16x32_bf16 v[108:111], v[132:135], v[192:195], v[108:111]
	v_mfma_f32_16x16x32_bf16 v[104:107], v[136:139], v[188:191], v[104:107]
	v_mfma_f32_16x16x32_bf16 v[104:107], v[140:143], v[192:195], v[104:107]
	v_mfma_f32_16x16x32_bf16 v[92:95], v[128:131], v[196:199], v[92:95]
	v_mfma_f32_16x16x32_bf16 v[92:95], v[132:135], v[202:205], v[92:95]
	v_mfma_f32_16x16x32_bf16 v[88:91], v[136:139], v[196:199], v[88:91]
	v_mfma_f32_16x16x32_bf16 v[88:91], v[140:143], v[202:205], v[88:91]
	v_mfma_f32_16x16x32_bf16 v[76:79], v[128:131], v[206:209], v[76:79]
	v_mfma_f32_16x16x32_bf16 v[76:79], v[132:135], v[220:223], v[76:79]
	v_mfma_f32_16x16x32_bf16 v[72:75], v[136:139], v[206:209], v[72:75]
	v_mfma_f32_16x16x32_bf16 v[72:75], v[140:143], v[220:223], v[72:75]
	s_setprio 0
	s_setprio 1
	v_mfma_f32_16x16x32_bf16 v[116:119], v[144:147], v[160:163], v[116:119]
	v_mfma_f32_16x16x32_bf16 v[116:119], v[148:151], v[164:167], v[116:119]
	v_mfma_f32_16x16x32_bf16 v[112:115], v[152:155], v[160:163], v[112:115]
	v_mfma_f32_16x16x32_bf16 v[112:115], v[156:159], v[164:167], v[112:115]
	v_mfma_f32_16x16x32_bf16 v[100:103], v[144:147], v[188:191], v[100:103]
	v_mfma_f32_16x16x32_bf16 v[100:103], v[148:151], v[192:195], v[100:103]
	v_mfma_f32_16x16x32_bf16 v[96:99], v[152:155], v[188:191], v[96:99]
	v_mfma_f32_16x16x32_bf16 v[96:99], v[156:159], v[192:195], v[96:99]
	v_mfma_f32_16x16x32_bf16 v[84:87], v[144:147], v[196:199], v[84:87]
	v_mfma_f32_16x16x32_bf16 v[84:87], v[148:151], v[202:205], v[84:87]
	v_mfma_f32_16x16x32_bf16 v[80:83], v[152:155], v[196:199], v[80:83]
	v_mfma_f32_16x16x32_bf16 v[80:83], v[156:159], v[202:205], v[80:83]
	v_mfma_f32_16x16x32_bf16 v[68:71], v[144:147], v[206:209], v[68:71]
	v_mfma_f32_16x16x32_bf16 v[68:71], v[148:151], v[220:223], v[68:71]
	v_mfma_f32_16x16x32_bf16 v[64:67], v[152:155], v[206:209], v[64:67]
	v_mfma_f32_16x16x32_bf16 v[64:67], v[156:159], v[220:223], v[64:67]
	s_barrier
	s_setprio 0
	s_add_i32 s26, s66, s34
	v_lshl_add_u64 v[228:229], v[228:229], 0, s[12:13]
	s_mov_b32 m0, s26
	ds_read_b128 v[160:163], v217 offset:49152
	ds_read_b128 v[164:167], v217 offset:50176
	ds_read_b128 v[188:191], v217 offset:51200
	ds_read_b128 v[192:195], v217 offset:52224
	ds_read_b128 v[196:199], v217 offset:53248
	ds_read_b128 v[202:205], v217 offset:54272
	ds_read_b128 v[206:209], v217 offset:55296
	ds_read_b128 v[220:223], v217 offset:56320
	global_load_lds_dwordx4 v[228:229], off
	s_add_i32 m0, s26, 0x2000
	s_add_u32 s14, s14, 0x80080
	v_lshl_add_u64 v[228:229], v[232:233], 0, s[12:13]
	s_addc_u32 s15, s15, 0
	s_add_i32 s26, s67, s34
	global_load_lds_dwordx4 v[228:229], off
	v_lshl_add_u64 v[228:229], s[14:15], 0, v[170:171]
	s_mov_b32 m0, s26
	s_nop 0
	global_load_lds_dwordx4 v[228:229], off
	v_lshl_add_u64 v[228:229], s[14:15], 0, v[174:175]
	s_add_i32 m0, s26, 0x2000
	s_nop 0
	global_load_lds_dwordx4 v[228:229], off
	v_lshl_add_u64 v[228:229], v[234:235], 0, s[12:13]
	s_mov_b32 m0, s47
	s_nop 0
	global_load_lds_dwordx4 v[228:229], off
	v_lshl_add_u64 v[228:229], v[236:237], 0, s[12:13]
	s_mov_b32 m0, s48
	s_nop 0
	global_load_lds_dwordx4 v[228:229], off
	s_waitcnt vmcnt(8)
	s_waitcnt lgkmcnt(0)
	s_setprio 1
	s_barrier
; #define PG8_STAGE(bufoff, gbase, voff) do { _Pragma("unroll") for (int _i = 0; _i < 2; ++_i) \
;         __builtin_amdgcn_global_load_lds((const unsigned*)((const char*)(gbase) + (voff)[_i]), (PG8_LAS unsigned*)(lds + (bufoff) + ldsw + _i * 8192), 16, 0, 0); } while (0)
; #define PG8_LDA(dst, b, h) do { _Pragma("unroll") for (int m = 0; m < 4; ++m) _Pragma("unroll") for (int k = 0; k < 2; ++k) dst[m][k] = *(const PG8_LAS bf16x8*)(lds + PG8_SA(b, h) + aoff + m * 2048 + k * 1024); } while (0)
; #define PG8_LDB(dst, b, h) do { _Pragma("unroll") for (int n = 0; n < 2; ++n) _Pragma("unroll") for (int k = 0; k < 2; ++k) dst[n][k] = *(const PG8_LAS bf16x8*)(lds + PG8_SB(b, h) + boff + n * 2048 + k * 1024); } while (0)
; #define PG8_MMA(ai, bj, At, Bt) do { __builtin_amdgcn_s_setprio(1); _Pragma("unroll") for (int m = 0; m < 4; ++m) _Pragma("unroll") for (int n = 0; n < 2; ++n) _Pragma("unroll") for (int k = 0; k < 2; ++k) \
;         acc[ai][bj][m][n] = __builtin_amdgcn_mfma_f32_16x16x32_bf16(Bt[n][k], At[m][k], acc[ai][bj][m][n], 0, 0, 0); __builtin_amdgcn_s_setprio(0); } while (0)
; #define PG8_WAIT_V(n) asm volatile("s_waitcnt vmcnt(" #n ")" ::: "memory")
; #define PG8_BAR __builtin_amdgcn_s_barrier()
; template <class Epi, class Sched, bool ALIGN_EPI = false, bool SP2 = false, bool DUAL = false>
; __device__ __forceinline__ void gemm_phase(PG8_LAS unsigned char* lds, const Gemm g, const Sched& S, const Epi& E) {
;     ...
;         for (int t = 0; t < nt; t += 2) {
;             const bool last = (t == nt - 2);
;             const char* a1 = cA + (size_t)(t + 1) * kstep;
;             const char* a2 = last ? nA : cA + (size_t)(t + 2) * kstep; const char* b2 = last ? nB : cB + (size_t)(t + 2) * kstep;
;             const char* a3 = a2 + kstep; const char* b3 = b2 + kstep;
;             if (last && has_next) S.a_ready(nxt);
;             if constexpr (SP2) {
;             PG8_LDB(B0, 0, 0); PG8_LDB(B1, 0, 1); PG8_SCHED; PG8_LDA(At, 0, 0); PG8_STAGE(PG8_SA(1, 1), a1 + hstep, voffA);
;             PG8_WAIT_V(8); PG8_WAIT_L(0); PG8_BAR; PG8_MMA(0, 0, At, B0); PG8_MMA(0, 1, At, B1); PG8_BAR; PG8_SCHED;
;             PG8_LDA(At, 0, 1); PG8_STAGE(PG8_SB(0, 0), b2, voffB); PG8_STAGE(PG8_SB(0, 1), b2 + hstep, voffB); PG8_STAGE(PG8_SA(0, 0), a2, voffA);
;             PG8_WAIT_V(8); PG8_WAIT_L(0); PG8_BAR; PG8_MMA(1, 0, At, B0); PG8_MMA(1, 1, At, B1); PG8_BAR; PG8_SCHED;
	v_mfma_f32_16x16x32_bf16 v[60:63], v[128:131], v[160:163], v[60:63]
	v_mfma_f32_16x16x32_bf16 v[60:63], v[132:135], v[164:167], v[60:63]
	v_mfma_f32_16x16x32_bf16 v[56:59], v[136:139], v[160:163], v[56:59]
	v_mfma_f32_16x16x32_bf16 v[56:59], v[140:143], v[164:167], v[56:59]
	v_mfma_f32_16x16x32_bf16 v[44:47], v[128:131], v[188:191], v[44:47]
	v_mfma_f32_16x16x32_bf16 v[44:47], v[132:135], v[192:195], v[44:47]
	v_mfma_f32_16x16x32_bf16 v[40:43], v[136:139], v[188:191], v[40:43]
	v_mfma_f32_16x16x32_bf16 v[40:43], v[140:143], v[192:195], v[40:43]
	v_mfma_f32_16x16x32_bf16 v[28:31], v[128:131], v[196:199], v[28:31]
	v_mfma_f32_16x16x32_bf16 v[28:31], v[132:135], v[202:205], v[28:31]
	v_mfma_f32_16x16x32_bf16 v[24:27], v[136:139], v[196:199], v[24:27]
	v_mfma_f32_16x16x32_bf16 v[24:27], v[140:143], v[202:205], v[24:27]
	v_mfma_f32_16x16x32_bf16 v[12:15], v[128:131], v[206:209], v[12:15]
	v_mfma_f32_16x16x32_bf16 v[12:15], v[132:135], v[220:223], v[12:15]
	v_mfma_f32_16x16x32_bf16 v[8:11], v[136:139], v[206:209], v[8:11]
	v_mfma_f32_16x16x32_bf16 v[8:11], v[140:143], v[220:223], v[8:11]
	s_setprio 0
	s_setprio 1
	v_mfma_f32_16x16x32_bf16 v[52:55], v[144:147], v[160:163], v[52:55]
	v_mfma_f32_16x16x32_bf16 v[52:55], v[148:151], v[164:167], v[52:55]
	v_mfma_f32_16x16x32_bf16 v[48:51], v[152:155], v[160:163], v[48:51]
	v_mfma_f32_16x16x32_bf16 v[48:51], v[156:159], v[164:167], v[48:51]
	v_mfma_f32_16x16x32_bf16 v[36:39], v[144:147], v[188:191], v[36:39]
	v_mfma_f32_16x16x32_bf16 v[36:39], v[148:151], v[192:195], v[36:39]
	v_mfma_f32_16x16x32_bf16 v[32:35], v[152:155], v[188:191], v[32:35]
	v_mfma_f32_16x16x32_bf16 v[32:35], v[156:159], v[192:195], v[32:35]
	v_mfma_f32_16x16x32_bf16 v[20:23], v[144:147], v[196:199], v[20:23]
	v_mfma_f32_16x16x32_bf16 v[20:23], v[148:151], v[202:205], v[20:23]
	v_mfma_f32_16x16x32_bf16 v[16:19], v[152:155], v[196:199], v[16:19]
	v_mfma_f32_16x16x32_bf16 v[16:19], v[156:159], v[202:205], v[16:19]
	v_mfma_f32_16x16x32_bf16 v[4:7], v[144:147], v[206:209], v[4:7]
	v_mfma_f32_16x16x32_bf16 v[4:7], v[148:151], v[220:223], v[4:7]
	v_mfma_f32_16x16x32_bf16 v[0:3], v[152:155], v[206:209], v[0:3]
	v_mfma_f32_16x16x32_bf16 v[0:3], v[156:159], v[220:223], v[0:3]
	s_barrier
	s_setprio 0
	s_add_i32 s65, s65, 2
	s_add_u32 s40, s40, 0x100
	s_addc_u32 s41, s41, 0
	s_add_u32 s63, s63, 0x100
	s_addc_u32 s64, s64, 0
.LBB0_992:
	ds_read_b128 v[128:131], v215
	ds_read_b128 v[132:135], v215 offset:1024
	ds_read_b128 v[136:139], v215 offset:2048
	ds_read_b128 v[140:143], v215 offset:3072
	ds_read_b128 v[144:147], v216
	ds_read_b128 v[148:151], v216 offset:1024
	ds_read_b128 v[152:155], v216 offset:2048
	ds_read_b128 v[156:159], v216 offset:3072
	s_add_u32 s14, s40, 0xfff80080
	s_addc_u32 s15, s41, -1
	s_cmp_eq_u32 s65, 28
	s_cselect_b32 s27, s25, s15
	s_cselect_b32 s26, s28, s14
	s_cselect_b32 s15, s23, s64
	s_cselect_b32 s14, s29, s63
	v_lshl_add_u64 v[228:229], s[40:41], 0, v[180:181]
	s_add_i32 m0, s39, 0xc000
	ds_read_b128 v[160:163], v217
	ds_read_b128 v[164:167], v217 offset:1024
	ds_read_b128 v[188:191], v217 offset:2048
	ds_read_b128 v[192:195], v217 offset:3072
	ds_read_b128 v[196:199], v217 offset:4096
	ds_read_b128 v[202:205], v217 offset:5120
	ds_read_b128 v[206:209], v217 offset:6144
	ds_read_b128 v[220:223], v217 offset:7168
	global_load_lds_dwordx4 v[228:229], off
	v_lshl_add_u64 v[228:229], s[40:41], 0, v[182:183]
	s_add_i32 m0, s39, 0xe000
	s_nop 0
	global_load_lds_dwordx4 v[228:229], off
	s_waitcnt vmcnt(8)
	s_waitcnt lgkmcnt(0)
	s_setprio 1
	s_barrier
	v_mfma_f32_16x16x32_bf16 v[124:127], v[128:131], v[160:163], v[124:127]
	v_mfma_f32_16x16x32_bf16 v[124:127], v[132:135], v[164:167], v[124:127]
	v_mfma_f32_16x16x32_bf16 v[120:123], v[136:139], v[160:163], v[120:123]
	v_mfma_f32_16x16x32_bf16 v[120:123], v[140:143], v[164:167], v[120:123]
	v_mfma_f32_16x16x32_bf16 v[108:111], v[128:131], v[188:191], v[108:111]
	v_mfma_f32_16x16x32_bf16 v[108:111], v[132:135], v[192:195], v[108:111]
	v_mfma_f32_16x16x32_bf16 v[104:107], v[136:139], v[188:191], v[104:107]
	v_mfma_f32_16x16x32_bf16 v[104:107], v[140:143], v[192:195], v[104:107]
	v_mfma_f32_16x16x32_bf16 v[92:95], v[128:131], v[196:199], v[92:95]
	v_mfma_f32_16x16x32_bf16 v[92:95], v[132:135], v[202:205], v[92:95]
	v_mfma_f32_16x16x32_bf16 v[88:91], v[136:139], v[196:199], v[88:91]
	v_mfma_f32_16x16x32_bf16 v[88:91], v[140:143], v[202:205], v[88:91]
	v_mfma_f32_16x16x32_bf16 v[76:79], v[128:131], v[206:209], v[76:79]
	v_mfma_f32_16x16x32_bf16 v[76:79], v[132:135], v[220:223], v[76:79]
	v_mfma_f32_16x16x32_bf16 v[72:75], v[136:139], v[206:209], v[72:75]
	v_mfma_f32_16x16x32_bf16 v[72:75], v[140:143], v[220:223], v[72:75]
	s_setprio 0
	s_setprio 1
	v_mfma_f32_16x16x32_bf16 v[116:119], v[144:147], v[160:163], v[116:119]
	v_mfma_f32_16x16x32_bf16 v[116:119], v[148:151], v[164:167], v[116:119]
	v_mfma_f32_16x16x32_bf16 v[112:115], v[152:155], v[160:163], v[112:115]
	v_mfma_f32_16x16x32_bf16 v[112:115], v[156:159], v[164:167], v[112:115]
	v_mfma_f32_16x16x32_bf16 v[100:103], v[144:147], v[188:191], v[100:103]
	v_mfma_f32_16x16x32_bf16 v[100:103], v[148:151], v[192:195], v[100:103]
	v_mfma_f32_16x16x32_bf16 v[96:99], v[152:155], v[188:191], v[96:99]
	v_mfma_f32_16x16x32_bf16 v[96:99], v[156:159], v[192:195], v[96:99]
	v_mfma_f32_16x16x32_bf16 v[84:87], v[144:147], v[196:199], v[84:87]
	v_mfma_f32_16x16x32_bf16 v[84:87], v[148:151], v[202:205], v[84:87]
	v_mfma_f32_16x16x32_bf16 v[80:83], v[152:155], v[196:199], v[80:83]
	v_mfma_f32_16x16x32_bf16 v[80:83], v[156:159], v[202:205], v[80:83]
	v_mfma_f32_16x16x32_bf16 v[68:71], v[144:147], v[206:209], v[68:71]
	v_mfma_f32_16x16x32_bf16 v[68:71], v[148:151], v[220:223], v[68:71]
	v_mfma_f32_16x16x32_bf16 v[64:67], v[152:155], v[206:209], v[64:67]
	v_mfma_f32_16x16x32_bf16 v[64:67], v[156:159], v[220:223], v[64:67]
	s_barrier
; #define PG8_STAGE(bufoff, gbase, voff) do { _Pragma("unroll") for (int _i = 0; _i < 2; ++_i) \
;         __builtin_amdgcn_global_load_lds((const unsigned*)((const char*)(gbase) + (voff)[_i]), (PG8_LAS unsigned*)(lds + (bufoff) + ldsw + _i * 8192), 16, 0, 0); } while (0)
; #define PG8_LDA(dst, b, h) do { _Pragma("unroll") for (int m = 0; m < 4; ++m) _Pragma("unroll") for (int k = 0; k < 2; ++k) dst[m][k] = *(const PG8_LAS bf16x8*)(lds + PG8_SA(b, h) + aoff + m * 2048 + k * 1024); } while (0)
; #define PG8_LDB(dst, b, h) do { _Pragma("unroll") for (int n = 0; n < 2; ++n) _Pragma("unroll") for (int k = 0; k < 2; ++k) dst[n][k] = *(const PG8_LAS bf16x8*)(lds + PG8_SB(b, h) + boff + n * 2048 + k * 1024); } while (0)
; #define PG8_MMA(ai, bj, At, Bt) do { __builtin_amdgcn_s_setprio(1); _Pragma("unroll") for (int m = 0; m < 4; ++m) _Pragma("unroll") for (int n = 0; n < 2; ++n) _Pragma("unroll") for (int k = 0; k < 2; ++k) \
;         acc[ai][bj][m][n] = __builtin_amdgcn_mfma_f32_16x16x32_bf16(Bt[n][k], At[m][k], acc[ai][bj][m][n], 0, 0, 0); __builtin_amdgcn_s_setprio(0); } while (0)
; #define PG8_WAIT_V(n) asm volatile("s_waitcnt vmcnt(" #n ")" ::: "memory")
; #define PG8_WAIT_L(n) asm volatile("s_waitcnt lgkmcnt(" #n ")" ::: "memory")
; #define PG8_BAR __builtin_amdgcn_s_barrier()
; #define PG8_SCHED __builtin_amdgcn_sched_barrier(0)
; template <class Epi, class Sched, bool ALIGN_EPI = false, bool SP2 = false, bool DUAL = false>
; __device__ __forceinline__ void gemm_phase(PG8_LAS unsigned char* lds, const Gemm g, const Sched& S, const Epi& E) {
;     ...
;             PG8_LDA(At, 0, 1); PG8_STAGE(PG8_SB(0, 0), b2, voffB); PG8_STAGE(PG8_SB(0, 1), b2 + hstep, voffB); PG8_STAGE(PG8_SA(0, 0), a2, voffA);
;             PG8_WAIT_V(8); PG8_WAIT_L(0); PG8_BAR; PG8_MMA(1, 0, At, B0); PG8_MMA(1, 1, At, B1); PG8_BAR; PG8_SCHED;
;             PG8_LDB(B0, 1, 0); PG8_LDB(B1, 1, 1); PG8_SCHED; PG8_LDA(At, 1, 0); PG8_STAGE(PG8_SA(0, 1), a2 + hstep, voffA);
;             PG8_WAIT_V(8); PG8_WAIT_L(0); PG8_BAR; PG8_MMA(0, 0, At, B0); PG8_MMA(0, 1, At, B1); PG8_BAR; PG8_SCHED;
	s_setprio 0
	s_add_i32 s66, s50, s34
	v_lshl_add_u64 v[228:229], s[14:15], 0, v[170:171]
	s_mov_b32 m0, s66
	ds_read_b128 v[160:163], v217 offset:16384
	ds_read_b128 v[164:167], v217 offset:17408
	ds_read_b128 v[188:191], v217 offset:18432
	ds_read_b128 v[192:195], v217 offset:19456
	ds_read_b128 v[196:199], v217 offset:20480
	ds_read_b128 v[202:205], v217 offset:21504
	ds_read_b128 v[206:209], v217 offset:22528
	ds_read_b128 v[220:223], v217 offset:23552
	global_load_lds_dwordx4 v[228:229], off
	s_add_i32 m0, s66, 0x2000
	s_add_u32 s66, s14, 0x80000
	v_lshl_add_u64 v[232:233], s[14:15], 0, v[174:175]
	s_addc_u32 s67, s15, 0
	s_add_i32 s68, s51, s34
	global_load_lds_dwordx4 v[232:233], off
	v_lshl_add_u64 v[234:235], s[66:67], 0, v[170:171]
	s_mov_b32 m0, s68
	v_lshl_add_u64 v[236:237], s[26:27], 0, v[172:173]
	global_load_lds_dwordx4 v[234:235], off
	v_lshl_add_u64 v[234:235], s[66:67], 0, v[174:175]
	s_add_i32 m0, s68, 0x2000
	s_nop 0
	global_load_lds_dwordx4 v[234:235], off
	v_lshl_add_u64 v[234:235], s[26:27], 0, v[168:169]
	s_mov_b32 m0, s39
	s_nop 0
	global_load_lds_dwordx4 v[234:235], off
	s_mov_b32 m0, s42
	s_nop 0
	global_load_lds_dwordx4 v[236:237], off
	s_waitcnt vmcnt(8)
	s_waitcnt lgkmcnt(0)
	s_setprio 1
	s_barrier
	v_mfma_f32_16x16x32_bf16 v[60:63], v[128:131], v[160:163], v[60:63]
	v_mfma_f32_16x16x32_bf16 v[60:63], v[132:135], v[164:167], v[60:63]
	v_mfma_f32_16x16x32_bf16 v[56:59], v[136:139], v[160:163], v[56:59]
	v_mfma_f32_16x16x32_bf16 v[56:59], v[140:143], v[164:167], v[56:59]
	v_mfma_f32_16x16x32_bf16 v[44:47], v[128:131], v[188:191], v[44:47]
	v_mfma_f32_16x16x32_bf16 v[44:47], v[132:135], v[192:195], v[44:47]
	v_mfma_f32_16x16x32_bf16 v[40:43], v[136:139], v[188:191], v[40:43]
	v_mfma_f32_16x16x32_bf16 v[40:43], v[140:143], v[192:195], v[40:43]
	v_mfma_f32_16x16x32_bf16 v[28:31], v[128:131], v[196:199], v[28:31]
	v_mfma_f32_16x16x32_bf16 v[28:31], v[132:135], v[202:205], v[28:31]
	v_mfma_f32_16x16x32_bf16 v[24:27], v[136:139], v[196:199], v[24:27]
	v_mfma_f32_16x16x32_bf16 v[24:27], v[140:143], v[202:205], v[24:27]
	v_mfma_f32_16x16x32_bf16 v[12:15], v[128:131], v[206:209], v[12:15]
	v_mfma_f32_16x16x32_bf16 v[12:15], v[132:135], v[220:223], v[12:15]
	v_mfma_f32_16x16x32_bf16 v[8:11], v[136:139], v[206:209], v[8:11]
	v_mfma_f32_16x16x32_bf16 v[8:11], v[140:143], v[220:223], v[8:11]
	s_setprio 0
	s_setprio 1
	v_mfma_f32_16x16x32_bf16 v[52:55], v[144:147], v[160:163], v[52:55]
	v_mfma_f32_16x16x32_bf16 v[52:55], v[148:151], v[164:167], v[52:55]
	v_mfma_f32_16x16x32_bf16 v[48:51], v[152:155], v[160:163], v[48:51]
	v_mfma_f32_16x16x32_bf16 v[48:51], v[156:159], v[164:167], v[48:51]
	v_mfma_f32_16x16x32_bf16 v[36:39], v[144:147], v[188:191], v[36:39]
	v_mfma_f32_16x16x32_bf16 v[36:39], v[148:151], v[192:195], v[36:39]
	v_mfma_f32_16x16x32_bf16 v[32:35], v[152:155], v[188:191], v[32:35]
	v_mfma_f32_16x16x32_bf16 v[32:35], v[156:159], v[192:195], v[32:35]
	v_mfma_f32_16x16x32_bf16 v[20:23], v[144:147], v[196:199], v[20:23]
	v_mfma_f32_16x16x32_bf16 v[20:23], v[148:151], v[202:205], v[20:23]
	v_mfma_f32_16x16x32_bf16 v[16:19], v[152:155], v[196:199], v[16:19]
	v_mfma_f32_16x16x32_bf16 v[16:19], v[156:159], v[202:205], v[16:19]
	v_mfma_f32_16x16x32_bf16 v[4:7], v[144:147], v[206:209], v[4:7]
	v_mfma_f32_16x16x32_bf16 v[4:7], v[148:151], v[220:223], v[4:7]
	v_mfma_f32_16x16x32_bf16 v[0:3], v[152:155], v[206:209], v[0:3]
	v_mfma_f32_16x16x32_bf16 v[0:3], v[156:159], v[220:223], v[0:3]
	s_barrier
	s_setprio 0
	s_add_i32 s66, 0, 0x18000
	s_add_i32 s67, 0, 0x1c000
	v_add_u32_e32 v140, s66, v213
	v_add_u32_e32 v156, s67, v213
	ds_read_b128 v[128:131], v140
	ds_read_b128 v[132:135], v140 offset:1024
	ds_read_b128 v[136:139], v140 offset:2048
	ds_read_b128 v[140:143], v140 offset:3072
	ds_read_b128 v[144:147], v156
	ds_read_b128 v[148:151], v156 offset:1024
	ds_read_b128 v[152:155], v156 offset:2048
	ds_read_b128 v[156:159], v156 offset:3072
	s_add_u32 s26, s26, 0x80000
	s_addc_u32 s27, s27, 0
	s_mov_b32 m0, s43
	v_lshl_add_u64 v[238:239], s[26:27], 0, v[168:169]
	ds_read_b128 v[160:163], v217 offset:32768
	ds_read_b128 v[164:167], v217 offset:33792
	ds_read_b128 v[188:191], v217 offset:34816
	ds_read_b128 v[192:195], v217 offset:35840
	ds_read_b128 v[196:199], v217 offset:36864
	ds_read_b128 v[202:205], v217 offset:37888
	ds_read_b128 v[206:209], v217 offset:38912
	ds_read_b128 v[220:223], v217 offset:39936
	global_load_lds_dwordx4 v[238:239], off
	v_lshl_add_u64 v[238:239], s[26:27], 0, v[172:173]
	s_mov_b32 m0, s44
	s_nop 0
	global_load_lds_dwordx4 v[238:239], off
	s_waitcnt vmcnt(8)
	s_waitcnt lgkmcnt(0)
	s_setprio 1
	s_barrier
; #define PG8_STAGE(bufoff, gbase, voff) do { _Pragma("unroll") for (int _i = 0; _i < 2; ++_i) \
;         __builtin_amdgcn_global_load_lds((const unsigned*)((const char*)(gbase) + (voff)[_i]), (PG8_LAS unsigned*)(lds + (bufoff) + ldsw + _i * 8192), 16, 0, 0); } while (0)
; #define PG8_LDA(dst, b, h) do { _Pragma("unroll") for (int m = 0; m < 4; ++m) _Pragma("unroll") for (int k = 0; k < 2; ++k) dst[m][k] = *(const PG8_LAS bf16x8*)(lds + PG8_SA(b, h) + aoff + m * 2048 + k * 1024); } while (0)
; #define PG8_MMA(ai, bj, At, Bt) do { __builtin_amdgcn_s_setprio(1); _Pragma("unroll") for (int m = 0; m < 4; ++m) _Pragma("unroll") for (int n = 0; n < 2; ++n) _Pragma("unroll") for (int k = 0; k < 2; ++k) \
;         acc[ai][bj][m][n] = __builtin_amdgcn_mfma_f32_16x16x32_bf16(Bt[n][k], At[m][k], acc[ai][bj][m][n], 0, 0, 0); __builtin_amdgcn_s_setprio(0); } while (0)
; #define PG8_WAIT_V(n) asm volatile("s_waitcnt vmcnt(" #n ")" ::: "memory")
; #define PG8_WAIT_L(n) asm volatile("s_waitcnt lgkmcnt(" #n ")" ::: "memory")
; #define PG8_BAR __builtin_amdgcn_s_barrier()
; #define PG8_SCHED __builtin_amdgcn_sched_barrier(0)
; template <class Epi, class Sched, bool ALIGN_EPI = false, bool SP2 = false, bool DUAL = false>
; __device__ __forceinline__ void gemm_phase(PG8_LAS unsigned char* lds, const Gemm g, const Sched& S, const Epi& E) {
;     ...
;             PG8_WAIT_V(8); PG8_WAIT_L(0); PG8_BAR; PG8_MMA(0, 0, At, B0); PG8_MMA(0, 1, At, B1); PG8_BAR; PG8_SCHED;
;             PG8_LDA(At, 1, 1); PG8_STAGE(PG8_SB(1, 0), b3, voffB); PG8_STAGE(PG8_SB(1, 1), b3 + hstep, voffB); PG8_STAGE(PG8_SA(1, 0), a3, voffA);
	v_mfma_f32_16x16x32_bf16 v[124:127], v[128:131], v[160:163], v[124:127]
	v_mfma_f32_16x16x32_bf16 v[124:127], v[132:135], v[164:167], v[124:127]
	v_mfma_f32_16x16x32_bf16 v[120:123], v[136:139], v[160:163], v[120:123]
	v_mfma_f32_16x16x32_bf16 v[120:123], v[140:143], v[164:167], v[120:123]
	v_mfma_f32_16x16x32_bf16 v[108:111], v[128:131], v[188:191], v[108:111]
	v_mfma_f32_16x16x32_bf16 v[108:111], v[132:135], v[192:195], v[108:111]
	v_mfma_f32_16x16x32_bf16 v[104:107], v[136:139], v[188:191], v[104:107]
	v_mfma_f32_16x16x32_bf16 v[104:107], v[140:143], v[192:195], v[104:107]
	v_mfma_f32_16x16x32_bf16 v[92:95], v[128:131], v[196:199], v[92:95]
	v_mfma_f32_16x16x32_bf16 v[92:95], v[132:135], v[202:205], v[92:95]
	v_mfma_f32_16x16x32_bf16 v[88:91], v[136:139], v[196:199], v[88:91]
	v_mfma_f32_16x16x32_bf16 v[88:91], v[140:143], v[202:205], v[88:91]
	v_mfma_f32_16x16x32_bf16 v[76:79], v[128:131], v[206:209], v[76:79]
	v_mfma_f32_16x16x32_bf16 v[76:79], v[132:135], v[220:223], v[76:79]
	v_mfma_f32_16x16x32_bf16 v[72:75], v[136:139], v[206:209], v[72:75]
	v_mfma_f32_16x16x32_bf16 v[72:75], v[140:143], v[220:223], v[72:75]
	s_setprio 0
	s_setprio 1
	v_mfma_f32_16x16x32_bf16 v[116:119], v[144:147], v[160:163], v[116:119]
	v_mfma_f32_16x16x32_bf16 v[116:119], v[148:151], v[164:167], v[116:119]
	v_mfma_f32_16x16x32_bf16 v[112:115], v[152:155], v[160:163], v[112:115]
	v_mfma_f32_16x16x32_bf16 v[112:115], v[156:159], v[164:167], v[112:115]
	v_mfma_f32_16x16x32_bf16 v[100:103], v[144:147], v[188:191], v[100:103]
	v_mfma_f32_16x16x32_bf16 v[100:103], v[148:151], v[192:195], v[100:103]
	v_mfma_f32_16x16x32_bf16 v[96:99], v[152:155], v[188:191], v[96:99]
	v_mfma_f32_16x16x32_bf16 v[96:99], v[156:159], v[192:195], v[96:99]
	v_mfma_f32_16x16x32_bf16 v[84:87], v[144:147], v[196:199], v[84:87]
	v_mfma_f32_16x16x32_bf16 v[84:87], v[148:151], v[202:205], v[84:87]
	v_mfma_f32_16x16x32_bf16 v[80:83], v[152:155], v[196:199], v[80:83]
	v_mfma_f32_16x16x32_bf16 v[80:83], v[156:159], v[202:205], v[80:83]
	v_mfma_f32_16x16x32_bf16 v[68:71], v[144:147], v[206:209], v[68:71]
	v_mfma_f32_16x16x32_bf16 v[68:71], v[148:151], v[220:223], v[68:71]
	v_mfma_f32_16x16x32_bf16 v[64:67], v[152:155], v[206:209], v[64:67]
	v_mfma_f32_16x16x32_bf16 v[64:67], v[156:159], v[220:223], v[64:67]
	s_barrier
	s_setprio 0
	s_add_i32 s26, s66, s34
	v_lshl_add_u64 v[228:229], v[228:229], 0, s[12:13]
	s_mov_b32 m0, s26
	ds_read_b128 v[160:163], v217 offset:49152
	ds_read_b128 v[164:167], v217 offset:50176
	ds_read_b128 v[188:191], v217 offset:51200
	ds_read_b128 v[192:195], v217 offset:52224
	ds_read_b128 v[196:199], v217 offset:53248
	ds_read_b128 v[202:205], v217 offset:54272
	ds_read_b128 v[206:209], v217 offset:55296
	ds_read_b128 v[220:223], v217 offset:56320
	global_load_lds_dwordx4 v[228:229], off
	s_add_i32 m0, s26, 0x2000
	s_add_u32 s14, s14, 0x80080
	v_lshl_add_u64 v[228:229], v[232:233], 0, s[12:13]
	s_addc_u32 s15, s15, 0
	s_add_i32 s26, s67, s34
	global_load_lds_dwordx4 v[228:229], off
	v_lshl_add_u64 v[228:229], s[14:15], 0, v[170:171]
	s_mov_b32 m0, s26
	s_nop 0
	global_load_lds_dwordx4 v[228:229], off
	v_lshl_add_u64 v[228:229], s[14:15], 0, v[174:175]
	s_add_i32 m0, s26, 0x2000
	s_nop 0
	global_load_lds_dwordx4 v[228:229], off
	v_lshl_add_u64 v[228:229], v[234:235], 0, s[12:13]
	s_mov_b32 m0, s47
	s_nop 0
	global_load_lds_dwordx4 v[228:229], off
	v_lshl_add_u64 v[228:229], v[236:237], 0, s[12:13]
	s_mov_b32 m0, s48
	s_nop 0
	global_load_lds_dwordx4 v[228:229], off
	s_waitcnt vmcnt(8)
	s_waitcnt lgkmcnt(0)
	s_setprio 1
	s_barrier
; #define PG8_MMA(ai, bj, At, Bt) do { __builtin_amdgcn_s_setprio(1); _Pragma("unroll") for (int m = 0; m < 4; ++m) _Pragma("unroll") for (int n = 0; n < 2; ++n) _Pragma("unroll") for (int k = 0; k < 2; ++k) \
;         acc[ai][bj][m][n] = __builtin_amdgcn_mfma_f32_16x16x32_bf16(Bt[n][k], At[m][k], acc[ai][bj][m][n], 0, 0, 0); __builtin_amdgcn_s_setprio(0); } while (0)
; #define PG8_WAIT_V(n) asm volatile("s_waitcnt vmcnt(" #n ")" ::: "memory")
; #define PG8_WAIT_L(n) asm volatile("s_waitcnt lgkmcnt(" #n ")" ::: "memory")
; #define PG8_BAR __builtin_amdgcn_s_barrier()
; #define PG8_SCHED __builtin_amdgcn_sched_barrier(0)
; template <class Epi, class Sched, bool ALIGN_EPI = false, bool SP2 = false, bool DUAL = false>
; __device__ __forceinline__ void gemm_phase(PG8_LAS unsigned char* lds, const Gemm g, const Sched& S, const Epi& E) {
;     ...
;             PG8_WAIT_V(8); PG8_WAIT_L(0); PG8_BAR; PG8_MMA(1, 0, At, B0); PG8_MMA(1, 1, At, B1); PG8_BAR; PG8_SCHED;
;     __device__ __forceinline__ void operator()(const f32x4 (&acc)[2][2][4][2], const Unit& u, int wr, int wc, int fr, int fq) const {
;         const int rowb = u.pm * BM + wr * 64 + fr, col = u.pn * HALF + wc * 32 + fq * 8;
;         f32x4 p[2][4][2];
; #pragma unroll
;         for (int ai = 0; ai < 2; ++ai)
; #pragma unroll
;             for (int m = 0; m < 4; ++m) { const float* sp = ss2 + (size_t)(rowb + ai * HALF + m * 16) * 32 + fq * 8; p[ai][m][0] = *(const f32x4*)sp; p[ai][m][1] = *(const f32x4*)(sp + 4); }
	v_mfma_f32_16x16x32_bf16 v[60:63], v[128:131], v[160:163], v[60:63]
	v_mfma_f32_16x16x32_bf16 v[60:63], v[132:135], v[164:167], v[60:63]
	v_mfma_f32_16x16x32_bf16 v[56:59], v[136:139], v[160:163], v[56:59]
	v_mfma_f32_16x16x32_bf16 v[56:59], v[140:143], v[164:167], v[56:59]
	v_mfma_f32_16x16x32_bf16 v[44:47], v[128:131], v[188:191], v[44:47]
	v_mfma_f32_16x16x32_bf16 v[44:47], v[132:135], v[192:195], v[44:47]
	v_mfma_f32_16x16x32_bf16 v[40:43], v[136:139], v[188:191], v[40:43]
	v_mfma_f32_16x16x32_bf16 v[40:43], v[140:143], v[192:195], v[40:43]
	v_mfma_f32_16x16x32_bf16 v[28:31], v[128:131], v[196:199], v[28:31]
	v_mfma_f32_16x16x32_bf16 v[28:31], v[132:135], v[202:205], v[28:31]
	v_mfma_f32_16x16x32_bf16 v[24:27], v[136:139], v[196:199], v[24:27]
	v_mfma_f32_16x16x32_bf16 v[24:27], v[140:143], v[202:205], v[24:27]
	v_mfma_f32_16x16x32_bf16 v[12:15], v[128:131], v[206:209], v[12:15]
	v_mfma_f32_16x16x32_bf16 v[12:15], v[132:135], v[220:223], v[12:15]
	v_mfma_f32_16x16x32_bf16 v[8:11], v[136:139], v[206:209], v[8:11]
	v_mfma_f32_16x16x32_bf16 v[8:11], v[140:143], v[220:223], v[8:11]
	s_setprio 0
	s_setprio 1
	v_mfma_f32_16x16x32_bf16 v[52:55], v[144:147], v[160:163], v[52:55]
	v_mfma_f32_16x16x32_bf16 v[52:55], v[148:151], v[164:167], v[52:55]
	v_mfma_f32_16x16x32_bf16 v[48:51], v[152:155], v[160:163], v[48:51]
	v_mfma_f32_16x16x32_bf16 v[48:51], v[156:159], v[164:167], v[48:51]
	v_mfma_f32_16x16x32_bf16 v[36:39], v[144:147], v[188:191], v[36:39]
	v_mfma_f32_16x16x32_bf16 v[36:39], v[148:151], v[192:195], v[36:39]
	v_mfma_f32_16x16x32_bf16 v[32:35], v[152:155], v[188:191], v[32:35]
	v_mfma_f32_16x16x32_bf16 v[32:35], v[156:159], v[192:195], v[32:35]
	v_mfma_f32_16x16x32_bf16 v[20:23], v[144:147], v[196:199], v[20:23]
	v_mfma_f32_16x16x32_bf16 v[20:23], v[148:151], v[202:205], v[20:23]
	v_mfma_f32_16x16x32_bf16 v[16:19], v[152:155], v[196:199], v[16:19]
	v_mfma_f32_16x16x32_bf16 v[16:19], v[156:159], v[202:205], v[16:19]
	v_mfma_f32_16x16x32_bf16 v[4:7], v[144:147], v[206:209], v[4:7]
	v_mfma_f32_16x16x32_bf16 v[4:7], v[148:151], v[220:223], v[4:7]
	v_mfma_f32_16x16x32_bf16 v[0:3], v[152:155], v[206:209], v[0:3]
	v_mfma_f32_16x16x32_bf16 v[0:3], v[156:159], v[220:223], v[0:3]
	s_barrier
	s_setprio 0
	s_add_i32 s65, s65, 2
	s_add_u32 s40, s40, 0x100
	s_addc_u32 s41, s41, 0
	s_add_u32 s63, s63, 0x100
	s_addc_u32 s64, s64, 0
	s_cmp_gt_u32 s65, 29
	s_cbranch_scc0 .LBB0_992
	v_lshl_add_u32 v144, s38, 8, v212
	v_ashrrev_i32_e32 v145, 31, v144
	v_or_b32_e32 v206, 16, v144
	v_lshlrev_b64 v[128:129], 7, v[144:145]
	v_ashrrev_i32_e32 v207, 31, v206
	v_lshl_add_u64 v[132:133], v[178:179], 0, v[128:129]
	v_lshlrev_b64 v[136:137], 7, v[206:207]
	global_load_dwordx4 v[128:131], v[132:133], off
	s_nop 0
	global_load_dwordx4 v[132:135], v[132:133], off offset:16
	v_lshl_add_u64 v[140:141], v[178:179], 0, v[136:137]
	global_load_dwordx4 v[136:139], v[140:141], off
	s_nop 0
	global_load_dwordx4 v[140:143], v[140:141], off offset:16
	v_readlane_b32 s64, v254, 20
	v_readlane_b32 s70, v254, 26
	v_readlane_b32 s71, v254, 27
	v_readlane_b32 s72, v254, 28
	v_readlane_b32 s73, v254, 29
	v_readlane_b32 s74, v254, 30
	v_readlane_b32 s75, v254, 31
	v_readlane_b32 s76, v254, 32
	v_readlane_b32 s77, v254, 33
	s_and_b64 vcc, exec, s[16:17]
	s_mov_b64 s[70:71], s[74:75]
	s_mov_b64 s[72:73], s[76:77]
	v_readlane_b32 s65, v254, 21
	v_readlane_b32 s66, v254, 22
	v_readlane_b32 s67, v254, 23
	v_readlane_b32 s68, v254, 24
	v_readlane_b32 s69, v254, 25
	v_readlane_b32 s78, v254, 34
	v_readlane_b32 s79, v254, 35
	s_cbranch_vccz .LBB0_995
	s_barrier

;     __device__ bool next(int i, Unit& u) const { if (!base.next(i >> 1, u)) return false; u.sub = i & 1; return true; }
; #define PG8_STAGE(bufoff, gbase, voff) do { _Pragma("unroll") for (int _i = 0; _i < 2; ++_i) \
;         __builtin_amdgcn_global_load_lds((const unsigned*)((const char*)(gbase) + (voff)[_i]), (PG8_LAS unsigned*)(lds + (bufoff) + ldsw + _i * 8192), 16, 0, 0); } while (0)
; #define PG8_LDA(dst, b, h) do { _Pragma("unroll") for (int m = 0; m < 4; ++m) _Pragma("unroll") for (int k = 0; k < 2; ++k) dst[m][k] = *(const PG8_LAS bf16x8*)(lds + PG8_SA(b, h) + aoff + m * 2048 + k * 1024); } while (0)
; template <class Epi, class Sched, bool ALIGN_EPI = false, bool SP2 = false, bool DUAL = false>
; __device__ __forceinline__ void gemm_phase(PG8_LAS unsigned char* lds, const Gemm g, const Sched& S, const Epi& E) {
;     ...
;     for (;;) {
;         const bool has_next = S.next(ui + 1, nxt);
;         const char* nA = has_next ? (const char*)((DUAL && nxt.sub) ? g.A2 : g.A) + (size_t)nxt.pm * tstep : cA; const char* nB = has_next ? (const char*)((DUAL && nxt.sub) ? g.Bt2 : g.Bt) + (size_t)nxt.pn * tstep : cB;
;         for (int t = 0; t < nt; t += 2) {
;             const bool last = (t == nt - 2);
;             const char* a1 = cA + (size_t)(t + 1) * kstep;
;             const char* a2 = last ? nA : cA + (size_t)(t + 2) * kstep; const char* b2 = last ? nB : cB + (size_t)(t + 2) * kstep;
;             const char* a3 = a2 + kstep; const char* b3 = b2 + kstep;
;             if (last && has_next) S.a_ready(nxt);
;             if constexpr (SP2) {
;             PG8_LDB(B0, 0, 0); PG8_LDB(B1, 0, 1); PG8_SCHED; PG8_LDA(At, 0, 0); PG8_STAGE(PG8_SA(1, 1), a1 + hstep, voffA);
;             PG8_WAIT_V(8); PG8_WAIT_L(0); PG8_BAR; PG8_MMA(0, 0, At, B0); PG8_MMA(0, 1, At, B1); PG8_BAR; PG8_SCHED;
;             PG8_LDA(At, 0, 1); PG8_STAGE(PG8_SB(0, 0), b2, voffB); PG8_STAGE(PG8_SB(0, 1), b2 + hstep, voffB); PG8_STAGE(PG8_SA(0, 0), a2, voffA);
;             PG8_WAIT_V(8); PG8_WAIT_L(0); PG8_BAR; PG8_MMA(1, 0, At, B0); PG8_MMA(1, 1, At, B1); PG8_BAR; PG8_SCHED;
;     ...
;         for (int a = 0; a < 2; ++a)
; #pragma unroll
;             for (int b = 0; b < 2; ++b)
; #pragma unroll
;                 for (int m = 0; m < 4; ++m)
; #pragma unroll
;                     for (int n = 0; n < 2; ++n) acc[a][b][m][n] = (f32x4){0.f, 0.f, 0.f, 0.f};
.LBB0_1192:
	s_add_u32 s24, s24, 0x160080
	s_addc_u32 s25, s25, 0
	s_add_u32 s46, s14, 0x100
	s_addc_u32 s47, s15, 0
	s_mov_b32 s48, -2
	s_add_u32 s14, s24, 0xffea0080
	s_addc_u32 s15, s25, -1
	s_cmpk_eq_i32 s48, 0x54
	s_cselect_b32 s27, s5, s15
	s_cselect_b32 s26, s4, s14
	s_cselect_b32 s15, s23, s47
	s_cselect_b32 s14, s22, s46
	s_waitcnt vmcnt(8)
	s_waitcnt lgkmcnt(0)
	s_setprio 1
	s_barrier
	v_mfma_f32_16x16x32_bf16 v[124:127], v[128:131], v[160:163], 0
	v_mfma_f32_16x16x32_bf16 v[124:127], v[132:135], v[182:185], v[124:127]
	v_mfma_f32_16x16x32_bf16 v[120:123], v[136:139], v[160:163], 0
	v_mfma_f32_16x16x32_bf16 v[120:123], v[140:143], v[182:185], v[120:123]
	v_mfma_f32_16x16x32_bf16 v[112:115], v[128:131], v[186:189], 0
	v_mfma_f32_16x16x32_bf16 v[112:115], v[132:135], v[190:193], v[112:115]
	v_mfma_f32_16x16x32_bf16 v[104:107], v[136:139], v[186:189], 0
	v_mfma_f32_16x16x32_bf16 v[104:107], v[140:143], v[190:193], v[104:107]
	v_mfma_f32_16x16x32_bf16 v[96:99], v[128:131], v[204:207], 0
	v_mfma_f32_16x16x32_bf16 v[96:99], v[132:135], v[208:211], v[96:99]
	v_mfma_f32_16x16x32_bf16 v[88:91], v[136:139], v[204:207], 0
	v_mfma_f32_16x16x32_bf16 v[88:91], v[140:143], v[208:211], v[88:91]
	v_mfma_f32_16x16x32_bf16 v[80:83], v[128:131], v[212:215], 0
	v_mfma_f32_16x16x32_bf16 v[80:83], v[132:135], v[216:219], v[80:83]
	v_mfma_f32_16x16x32_bf16 v[72:75], v[136:139], v[212:215], 0
	v_mfma_f32_16x16x32_bf16 v[72:75], v[140:143], v[216:219], v[72:75]
	s_setprio 0
	s_setprio 1
	v_mfma_f32_16x16x32_bf16 v[116:119], v[144:147], v[160:163], 0
	v_mfma_f32_16x16x32_bf16 v[116:119], v[148:151], v[182:185], v[116:119]
	v_mfma_f32_16x16x32_bf16 v[108:111], v[152:155], v[160:163], 0
	v_mfma_f32_16x16x32_bf16 v[108:111], v[156:159], v[182:185], v[108:111]
	v_mfma_f32_16x16x32_bf16 v[100:103], v[144:147], v[186:189], 0
	v_mfma_f32_16x16x32_bf16 v[100:103], v[148:151], v[190:193], v[100:103]
	v_mfma_f32_16x16x32_bf16 v[92:95], v[152:155], v[186:189], 0
	v_mfma_f32_16x16x32_bf16 v[92:95], v[156:159], v[190:193], v[92:95]
	v_mfma_f32_16x16x32_bf16 v[84:87], v[144:147], v[204:207], 0
	v_mfma_f32_16x16x32_bf16 v[84:87], v[148:151], v[208:211], v[84:87]
	v_mfma_f32_16x16x32_bf16 v[76:79], v[152:155], v[204:207], 0
	v_mfma_f32_16x16x32_bf16 v[76:79], v[156:159], v[208:211], v[76:79]
	v_mfma_f32_16x16x32_bf16 v[68:71], v[144:147], v[212:215], 0
	v_mfma_f32_16x16x32_bf16 v[68:71], v[148:151], v[216:219], v[68:71]
	v_mfma_f32_16x16x32_bf16 v[64:67], v[152:155], v[212:215], 0
	v_mfma_f32_16x16x32_bf16 v[64:67], v[156:159], v[216:219], v[64:67]
	s_barrier
	s_setprio 0
	v_lshl_add_u64 v[220:221], s[24:25], 0, v[172:173]
	s_add_i32 m0, s31, 0xc000
	s_nop 0
	global_load_lds_dwordx4 v[220:221], off
	v_lshl_add_u64 v[220:221], s[24:25], 0, v[174:175]
	s_add_i32 m0, s31, 0xe000
	s_nop 0
	global_load_lds_dwordx4 v[220:221], off
	s_add_i32 s49, s40, s30
	v_lshl_add_u64 v[220:221], s[14:15], 0, v[166:167]
	s_mov_b32 m0, s49
	ds_read_b128 v[160:163], v203 offset:16384
	ds_read_b128 v[182:185], v203 offset:17408
	ds_read_b128 v[186:189], v203 offset:18432
	ds_read_b128 v[190:193], v203 offset:19456
	ds_read_b128 v[204:207], v203 offset:20480
	ds_read_b128 v[208:211], v203 offset:21504
	ds_read_b128 v[212:215], v203 offset:22528
	ds_read_b128 v[216:219], v203 offset:23552
	global_load_lds_dwordx4 v[220:221], off
	s_add_i32 m0, s49, 0x2000
	s_add_u32 s50, s14, 0x160000
	v_lshl_add_u64 v[222:223], s[14:15], 0, v[170:171]
	s_addc_u32 s51, s15, 0
	s_add_i32 s49, s41, s30
	global_load_lds_dwordx4 v[222:223], off
	v_lshl_add_u64 v[224:225], s[50:51], 0, v[166:167]
	s_mov_b32 m0, s49
	v_lshl_add_u64 v[226:227], s[26:27], 0, v[168:169]
	global_load_lds_dwordx4 v[224:225], off
	v_lshl_add_u64 v[224:225], s[50:51], 0, v[170:171]
	s_add_i32 m0, s49, 0x2000
	s_nop 0
	global_load_lds_dwordx4 v[224:225], off
	v_lshl_add_u64 v[224:225], s[26:27], 0, v[164:165]
	s_mov_b32 m0, s31
	s_nop 0
	global_load_lds_dwordx4 v[224:225], off
	s_mov_b32 m0, s33
	s_nop 0
	global_load_lds_dwordx4 v[226:227], off
	s_waitcnt vmcnt(8)
	s_waitcnt lgkmcnt(0)
	s_setprio 1
	s_barrier
	v_mfma_f32_16x16x32_bf16 v[60:63], v[128:131], v[160:163], 0
	v_mfma_f32_16x16x32_bf16 v[60:63], v[132:135], v[182:185], v[60:63]
	v_mfma_f32_16x16x32_bf16 v[56:59], v[136:139], v[160:163], 0
	v_mfma_f32_16x16x32_bf16 v[56:59], v[140:143], v[182:185], v[56:59]
	v_mfma_f32_16x16x32_bf16 v[48:51], v[128:131], v[186:189], 0
	v_mfma_f32_16x16x32_bf16 v[48:51], v[132:135], v[190:193], v[48:51]
	v_mfma_f32_16x16x32_bf16 v[40:43], v[136:139], v[186:189], 0
	v_mfma_f32_16x16x32_bf16 v[40:43], v[140:143], v[190:193], v[40:43]
	v_mfma_f32_16x16x32_bf16 v[32:35], v[128:131], v[204:207], 0
	v_mfma_f32_16x16x32_bf16 v[32:35], v[132:135], v[208:211], v[32:35]
	v_mfma_f32_16x16x32_bf16 v[24:27], v[136:139], v[204:207], 0
	v_mfma_f32_16x16x32_bf16 v[24:27], v[140:143], v[208:211], v[24:27]
	v_mfma_f32_16x16x32_bf16 v[16:19], v[128:131], v[212:215], 0
	v_mfma_f32_16x16x32_bf16 v[16:19], v[132:135], v[216:219], v[16:19]
	v_mfma_f32_16x16x32_bf16 v[8:11], v[136:139], v[212:215], 0
	v_mfma_f32_16x16x32_bf16 v[8:11], v[140:143], v[216:219], v[8:11]
	s_setprio 0
	s_setprio 1
	v_mfma_f32_16x16x32_bf16 v[52:55], v[144:147], v[160:163], 0
	v_mfma_f32_16x16x32_bf16 v[52:55], v[148:151], v[182:185], v[52:55]
	v_mfma_f32_16x16x32_bf16 v[44:47], v[152:155], v[160:163], 0
	v_mfma_f32_16x16x32_bf16 v[44:47], v[156:159], v[182:185], v[44:47]
	v_mfma_f32_16x16x32_bf16 v[36:39], v[144:147], v[186:189], 0
	v_mfma_f32_16x16x32_bf16 v[36:39], v[148:151], v[190:193], v[36:39]
	v_mfma_f32_16x16x32_bf16 v[28:31], v[152:155], v[186:189], 0
	v_mfma_f32_16x16x32_bf16 v[28:31], v[156:159], v[190:193], v[28:31]
	v_mfma_f32_16x16x32_bf16 v[20:23], v[144:147], v[204:207], 0
	v_mfma_f32_16x16x32_bf16 v[20:23], v[148:151], v[208:211], v[20:23]
	v_mfma_f32_16x16x32_bf16 v[12:15], v[152:155], v[204:207], 0
	v_mfma_f32_16x16x32_bf16 v[12:15], v[156:159], v[208:211], v[12:15]
	v_mfma_f32_16x16x32_bf16 v[4:7], v[144:147], v[212:215], 0
	v_mfma_f32_16x16x32_bf16 v[4:7], v[148:151], v[216:219], v[4:7]
	v_mfma_f32_16x16x32_bf16 v[0:3], v[152:155], v[212:215], 0
	v_mfma_f32_16x16x32_bf16 v[0:3], v[156:159], v[216:219], v[0:3]
	s_barrier
; #define PG8_STAGE(bufoff, gbase, voff) do { _Pragma("unroll") for (int _i = 0; _i < 2; ++_i) \
;         __builtin_amdgcn_global_load_lds((const unsigned*)((const char*)(gbase) + (voff)[_i]), (PG8_LAS unsigned*)(lds + (bufoff) + ldsw + _i * 8192), 16, 0, 0); } while (0)
; #define PG8_LDA(dst, b, h) do { _Pragma("unroll") for (int m = 0; m < 4; ++m) _Pragma("unroll") for (int k = 0; k < 2; ++k) dst[m][k] = *(const PG8_LAS bf16x8*)(lds + PG8_SA(b, h) + aoff + m * 2048 + k * 1024); } while (0)
; #define PG8_LDB(dst, b, h) do { _Pragma("unroll") for (int n = 0; n < 2; ++n) _Pragma("unroll") for (int k = 0; k < 2; ++k) dst[n][k] = *(const PG8_LAS bf16x8*)(lds + PG8_SB(b, h) + boff + n * 2048 + k * 1024); } while (0)
; #define PG8_MMA(ai, bj, At, Bt) do { __builtin_amdgcn_s_setprio(1); _Pragma("unroll") for (int m = 0; m < 4; ++m) _Pragma("unroll") for (int n = 0; n < 2; ++n) _Pragma("unroll") for (int k = 0; k < 2; ++k) \
;         acc[ai][bj][m][n] = __builtin_amdgcn_mfma_f32_16x16x32_bf16(Bt[n][k], At[m][k], acc[ai][bj][m][n], 0, 0, 0); __builtin_amdgcn_s_setprio(0); } while (0)
; #define PG8_WAIT_V(n) asm volatile("s_waitcnt vmcnt(" #n ")" ::: "memory")
; #define PG8_WAIT_L(n) asm volatile("s_waitcnt lgkmcnt(" #n ")" ::: "memory")
; #define PG8_BAR __builtin_amdgcn_s_barrier()
; #define PG8_SCHED __builtin_amdgcn_sched_barrier(0)
; template <class Epi, class Sched, bool ALIGN_EPI = false, bool SP2 = false, bool DUAL = false>
; __device__ __forceinline__ void gemm_phase(PG8_LAS unsigned char* lds, const Gemm g, const Sched& S, const Epi& E) {
;     ...
;             PG8_LDB(B0, 1, 0); PG8_LDB(B1, 1, 1); PG8_SCHED; PG8_LDA(At, 1, 0); PG8_STAGE(PG8_SA(0, 1), a2 + hstep, voffA);
;             PG8_WAIT_V(8); PG8_WAIT_L(0); PG8_BAR; PG8_MMA(0, 0, At, B0); PG8_MMA(0, 1, At, B1); PG8_BAR; PG8_SCHED;
;             PG8_LDA(At, 1, 1); PG8_STAGE(PG8_SB(1, 0), b3, voffB); PG8_STAGE(PG8_SB(1, 1), b3 + hstep, voffB); PG8_STAGE(PG8_SA(1, 0), a3, voffA);
	s_setprio 0
	s_add_i32 s49, 0, 0x18000
	s_add_i32 s50, 0, 0x1c000
	v_add_u32_e32 v140, s49, v198
	v_add_u32_e32 v156, s50, v198
	ds_read_b128 v[128:131], v140
	ds_read_b128 v[132:135], v140 offset:1024
	ds_read_b128 v[136:139], v140 offset:2048
	ds_read_b128 v[140:143], v140 offset:3072
	ds_read_b128 v[144:147], v156
	ds_read_b128 v[148:151], v156 offset:1024
	ds_read_b128 v[152:155], v156 offset:2048
	ds_read_b128 v[156:159], v156 offset:3072
	s_add_u32 s26, s26, 0x160000
	s_addc_u32 s27, s27, 0
	s_mov_b32 m0, s34
	v_lshl_add_u64 v[228:229], s[26:27], 0, v[164:165]
	ds_read_b128 v[160:163], v203 offset:32768
	ds_read_b128 v[182:185], v203 offset:33792
	ds_read_b128 v[186:189], v203 offset:34816
	ds_read_b128 v[190:193], v203 offset:35840
	ds_read_b128 v[204:207], v203 offset:36864
	ds_read_b128 v[208:211], v203 offset:37888
	ds_read_b128 v[212:215], v203 offset:38912
	ds_read_b128 v[216:219], v203 offset:39936
	global_load_lds_dwordx4 v[228:229], off
	v_lshl_add_u64 v[228:229], s[26:27], 0, v[168:169]
	s_mov_b32 m0, s35
	s_nop 0
	global_load_lds_dwordx4 v[228:229], off
	s_waitcnt vmcnt(8)
	s_waitcnt lgkmcnt(0)
	s_setprio 1
	s_barrier
	v_mfma_f32_16x16x32_bf16 v[124:127], v[128:131], v[160:163], v[124:127]
	v_mfma_f32_16x16x32_bf16 v[124:127], v[132:135], v[182:185], v[124:127]
	v_mfma_f32_16x16x32_bf16 v[120:123], v[136:139], v[160:163], v[120:123]
	v_mfma_f32_16x16x32_bf16 v[120:123], v[140:143], v[182:185], v[120:123]
	v_mfma_f32_16x16x32_bf16 v[112:115], v[128:131], v[186:189], v[112:115]
	v_mfma_f32_16x16x32_bf16 v[112:115], v[132:135], v[190:193], v[112:115]
	v_mfma_f32_16x16x32_bf16 v[104:107], v[136:139], v[186:189], v[104:107]
	v_mfma_f32_16x16x32_bf16 v[104:107], v[140:143], v[190:193], v[104:107]
	v_mfma_f32_16x16x32_bf16 v[96:99], v[128:131], v[204:207], v[96:99]
	v_mfma_f32_16x16x32_bf16 v[96:99], v[132:135], v[208:211], v[96:99]
	v_mfma_f32_16x16x32_bf16 v[88:91], v[136:139], v[204:207], v[88:91]
	v_mfma_f32_16x16x32_bf16 v[88:91], v[140:143], v[208:211], v[88:91]
	v_mfma_f32_16x16x32_bf16 v[80:83], v[128:131], v[212:215], v[80:83]
	v_mfma_f32_16x16x32_bf16 v[80:83], v[132:135], v[216:219], v[80:83]
	v_mfma_f32_16x16x32_bf16 v[72:75], v[136:139], v[212:215], v[72:75]
	v_mfma_f32_16x16x32_bf16 v[72:75], v[140:143], v[216:219], v[72:75]
	s_setprio 0
	s_setprio 1
	v_mfma_f32_16x16x32_bf16 v[116:119], v[144:147], v[160:163], v[116:119]
	v_mfma_f32_16x16x32_bf16 v[116:119], v[148:151], v[182:185], v[116:119]
	v_mfma_f32_16x16x32_bf16 v[108:111], v[152:155], v[160:163], v[108:111]
	v_mfma_f32_16x16x32_bf16 v[108:111], v[156:159], v[182:185], v[108:111]
	v_mfma_f32_16x16x32_bf16 v[100:103], v[144:147], v[186:189], v[100:103]
	v_mfma_f32_16x16x32_bf16 v[100:103], v[148:151], v[190:193], v[100:103]
	v_mfma_f32_16x16x32_bf16 v[92:95], v[152:155], v[186:189], v[92:95]
	v_mfma_f32_16x16x32_bf16 v[92:95], v[156:159], v[190:193], v[92:95]
	v_mfma_f32_16x16x32_bf16 v[84:87], v[144:147], v[204:207], v[84:87]
	v_mfma_f32_16x16x32_bf16 v[84:87], v[148:151], v[208:211], v[84:87]
	v_mfma_f32_16x16x32_bf16 v[76:79], v[152:155], v[204:207], v[76:79]
	v_mfma_f32_16x16x32_bf16 v[76:79], v[156:159], v[208:211], v[76:79]
	v_mfma_f32_16x16x32_bf16 v[68:71], v[144:147], v[212:215], v[68:71]
	v_mfma_f32_16x16x32_bf16 v[68:71], v[148:151], v[216:219], v[68:71]
	v_mfma_f32_16x16x32_bf16 v[64:67], v[152:155], v[212:215], v[64:67]
	v_mfma_f32_16x16x32_bf16 v[64:67], v[156:159], v[216:219], v[64:67]
	s_barrier
	s_setprio 0
	s_add_i32 s26, s49, s30
	v_lshl_add_u64 v[220:221], v[220:221], 0, s[18:19]
	s_mov_b32 m0, s26
	ds_read_b128 v[160:163], v203 offset:49152
	ds_read_b128 v[182:185], v203 offset:50176
	ds_read_b128 v[186:189], v203 offset:51200
	ds_read_b128 v[190:193], v203 offset:52224
	ds_read_b128 v[204:207], v203 offset:53248
	ds_read_b128 v[208:211], v203 offset:54272
	ds_read_b128 v[212:215], v203 offset:55296
	ds_read_b128 v[216:219], v203 offset:56320
	global_load_lds_dwordx4 v[220:221], off
	s_add_i32 m0, s26, 0x2000
	s_add_u32 s14, s14, 0x160080
	v_lshl_add_u64 v[220:221], v[222:223], 0, s[18:19]
	s_addc_u32 s15, s15, 0
	s_add_i32 s26, s50, s30
	global_load_lds_dwordx4 v[220:221], off
	v_lshl_add_u64 v[220:221], s[14:15], 0, v[166:167]
	s_mov_b32 m0, s26
	s_nop 0
	global_load_lds_dwordx4 v[220:221], off
	v_lshl_add_u64 v[220:221], s[14:15], 0, v[170:171]
	s_add_i32 m0, s26, 0x2000
	s_nop 0
	global_load_lds_dwordx4 v[220:221], off
	v_lshl_add_u64 v[220:221], v[224:225], 0, s[18:19]
	s_mov_b32 m0, s37
	s_nop 0
	global_load_lds_dwordx4 v[220:221], off
	v_lshl_add_u64 v[220:221], v[226:227], 0, s[18:19]
	s_mov_b32 m0, s38
	s_nop 0
	global_load_lds_dwordx4 v[220:221], off
	s_waitcnt vmcnt(8)
	s_waitcnt lgkmcnt(0)
	s_setprio 1
	s_barrier
; #define PG8_STAGE(bufoff, gbase, voff) do { _Pragma("unroll") for (int _i = 0; _i < 2; ++_i) \
;         __builtin_amdgcn_global_load_lds((const unsigned*)((const char*)(gbase) + (voff)[_i]), (PG8_LAS unsigned*)(lds + (bufoff) + ldsw + _i * 8192), 16, 0, 0); } while (0)
; #define PG8_LDA(dst, b, h) do { _Pragma("unroll") for (int m = 0; m < 4; ++m) _Pragma("unroll") for (int k = 0; k < 2; ++k) dst[m][k] = *(const PG8_LAS bf16x8*)(lds + PG8_SA(b, h) + aoff + m * 2048 + k * 1024); } while (0)
; #define PG8_LDB(dst, b, h) do { _Pragma("unroll") for (int n = 0; n < 2; ++n) _Pragma("unroll") for (int k = 0; k < 2; ++k) dst[n][k] = *(const PG8_LAS bf16x8*)(lds + PG8_SB(b, h) + boff + n * 2048 + k * 1024); } while (0)
; #define PG8_MMA(ai, bj, At, Bt) do { __builtin_amdgcn_s_setprio(1); _Pragma("unroll") for (int m = 0; m < 4; ++m) _Pragma("unroll") for (int n = 0; n < 2; ++n) _Pragma("unroll") for (int k = 0; k < 2; ++k) \
;         acc[ai][bj][m][n] = __builtin_amdgcn_mfma_f32_16x16x32_bf16(Bt[n][k], At[m][k], acc[ai][bj][m][n], 0, 0, 0); __builtin_amdgcn_s_setprio(0); } while (0)
; #define PG8_WAIT_V(n) asm volatile("s_waitcnt vmcnt(" #n ")" ::: "memory")
; #define PG8_BAR __builtin_amdgcn_s_barrier()
; template <class Epi, class Sched, bool ALIGN_EPI = false, bool SP2 = false, bool DUAL = false>
; __device__ __forceinline__ void gemm_phase(PG8_LAS unsigned char* lds, const Gemm g, const Sched& S, const Epi& E) {
;     ...
;         for (int t = 0; t < nt; t += 2) {
;             const bool last = (t == nt - 2);
;             const char* a1 = cA + (size_t)(t + 1) * kstep;
;             const char* a2 = last ? nA : cA + (size_t)(t + 2) * kstep; const char* b2 = last ? nB : cB + (size_t)(t + 2) * kstep;
;             const char* a3 = a2 + kstep; const char* b3 = b2 + kstep;
;             if (last && has_next) S.a_ready(nxt);
;             if constexpr (SP2) {
;             PG8_LDB(B0, 0, 0); PG8_LDB(B1, 0, 1); PG8_SCHED; PG8_LDA(At, 0, 0); PG8_STAGE(PG8_SA(1, 1), a1 + hstep, voffA);
;             PG8_WAIT_V(8); PG8_WAIT_L(0); PG8_BAR; PG8_MMA(0, 0, At, B0); PG8_MMA(0, 1, At, B1); PG8_BAR; PG8_SCHED;
;             PG8_LDA(At, 0, 1); PG8_STAGE(PG8_SB(0, 0), b2, voffB); PG8_STAGE(PG8_SB(0, 1), b2 + hstep, voffB); PG8_STAGE(PG8_SA(0, 0), a2, voffA);
;             PG8_WAIT_V(8); PG8_WAIT_L(0); PG8_BAR; PG8_MMA(1, 0, At, B0); PG8_MMA(1, 1, At, B1); PG8_BAR; PG8_SCHED;
	v_mfma_f32_16x16x32_bf16 v[60:63], v[128:131], v[160:163], v[60:63]
	v_mfma_f32_16x16x32_bf16 v[60:63], v[132:135], v[182:185], v[60:63]
	v_mfma_f32_16x16x32_bf16 v[56:59], v[136:139], v[160:163], v[56:59]
	v_mfma_f32_16x16x32_bf16 v[56:59], v[140:143], v[182:185], v[56:59]
	v_mfma_f32_16x16x32_bf16 v[48:51], v[128:131], v[186:189], v[48:51]
	v_mfma_f32_16x16x32_bf16 v[48:51], v[132:135], v[190:193], v[48:51]
	v_mfma_f32_16x16x32_bf16 v[40:43], v[136:139], v[186:189], v[40:43]
	v_mfma_f32_16x16x32_bf16 v[40:43], v[140:143], v[190:193], v[40:43]
	v_mfma_f32_16x16x32_bf16 v[32:35], v[128:131], v[204:207], v[32:35]
	v_mfma_f32_16x16x32_bf16 v[32:35], v[132:135], v[208:211], v[32:35]
	v_mfma_f32_16x16x32_bf16 v[24:27], v[136:139], v[204:207], v[24:27]
	v_mfma_f32_16x16x32_bf16 v[24:27], v[140:143], v[208:211], v[24:27]
	v_mfma_f32_16x16x32_bf16 v[16:19], v[128:131], v[212:215], v[16:19]
	v_mfma_f32_16x16x32_bf16 v[16:19], v[132:135], v[216:219], v[16:19]
	v_mfma_f32_16x16x32_bf16 v[8:11], v[136:139], v[212:215], v[8:11]
	v_mfma_f32_16x16x32_bf16 v[8:11], v[140:143], v[216:219], v[8:11]
	s_setprio 0
	s_setprio 1
	v_mfma_f32_16x16x32_bf16 v[52:55], v[144:147], v[160:163], v[52:55]
	v_mfma_f32_16x16x32_bf16 v[52:55], v[148:151], v[182:185], v[52:55]
	v_mfma_f32_16x16x32_bf16 v[44:47], v[152:155], v[160:163], v[44:47]
	v_mfma_f32_16x16x32_bf16 v[44:47], v[156:159], v[182:185], v[44:47]
	v_mfma_f32_16x16x32_bf16 v[36:39], v[144:147], v[186:189], v[36:39]
	v_mfma_f32_16x16x32_bf16 v[36:39], v[148:151], v[190:193], v[36:39]
	v_mfma_f32_16x16x32_bf16 v[28:31], v[152:155], v[186:189], v[28:31]
	v_mfma_f32_16x16x32_bf16 v[28:31], v[156:159], v[190:193], v[28:31]
	v_mfma_f32_16x16x32_bf16 v[20:23], v[144:147], v[204:207], v[20:23]
	v_mfma_f32_16x16x32_bf16 v[20:23], v[148:151], v[208:211], v[20:23]
	v_mfma_f32_16x16x32_bf16 v[12:15], v[152:155], v[204:207], v[12:15]
	v_mfma_f32_16x16x32_bf16 v[12:15], v[156:159], v[208:211], v[12:15]
	v_mfma_f32_16x16x32_bf16 v[4:7], v[144:147], v[212:215], v[4:7]
	v_mfma_f32_16x16x32_bf16 v[4:7], v[148:151], v[216:219], v[4:7]
	v_mfma_f32_16x16x32_bf16 v[0:3], v[152:155], v[212:215], v[0:3]
	v_mfma_f32_16x16x32_bf16 v[0:3], v[156:159], v[216:219], v[0:3]
	s_barrier
	s_setprio 0
	s_add_i32 s48, s48, 2
	s_add_u32 s24, s24, 0x100
	s_addc_u32 s25, s25, 0
	s_add_u32 s46, s46, 0x100
	s_addc_u32 s47, s47, 0
.LBB0_1193:
	ds_read_b128 v[128:131], v201
	ds_read_b128 v[132:135], v201 offset:1024
	ds_read_b128 v[136:139], v201 offset:2048
	ds_read_b128 v[140:143], v201 offset:3072
	ds_read_b128 v[144:147], v202
	ds_read_b128 v[148:151], v202 offset:1024
	ds_read_b128 v[152:155], v202 offset:2048
	ds_read_b128 v[156:159], v202 offset:3072
	s_add_u32 s14, s24, 0xffea0080
	s_addc_u32 s15, s25, -1
	s_cmpk_eq_i32 s48, 0x54
	s_cselect_b32 s27, s5, s15
	s_cselect_b32 s26, s4, s14
	s_cselect_b32 s15, s23, s47
	s_cselect_b32 s14, s22, s46
	v_lshl_add_u64 v[220:221], s[24:25], 0, v[172:173]
	s_add_i32 m0, s31, 0xc000
	ds_read_b128 v[160:163], v203
	ds_read_b128 v[182:185], v203 offset:1024
	ds_read_b128 v[186:189], v203 offset:2048
	ds_read_b128 v[190:193], v203 offset:3072
	ds_read_b128 v[204:207], v203 offset:4096
	ds_read_b128 v[208:211], v203 offset:5120
	ds_read_b128 v[212:215], v203 offset:6144
	ds_read_b128 v[216:219], v203 offset:7168
	global_load_lds_dwordx4 v[220:221], off
	v_lshl_add_u64 v[220:221], s[24:25], 0, v[174:175]
	s_add_i32 m0, s31, 0xe000
	s_nop 0
	global_load_lds_dwordx4 v[220:221], off
	s_waitcnt vmcnt(8)
	s_waitcnt lgkmcnt(0)
	s_setprio 1
	s_barrier
	v_mfma_f32_16x16x32_bf16 v[124:127], v[128:131], v[160:163], v[124:127]
	v_mfma_f32_16x16x32_bf16 v[124:127], v[132:135], v[182:185], v[124:127]
	v_mfma_f32_16x16x32_bf16 v[120:123], v[136:139], v[160:163], v[120:123]
	v_mfma_f32_16x16x32_bf16 v[120:123], v[140:143], v[182:185], v[120:123]
	v_mfma_f32_16x16x32_bf16 v[112:115], v[128:131], v[186:189], v[112:115]
	v_mfma_f32_16x16x32_bf16 v[112:115], v[132:135], v[190:193], v[112:115]
	v_mfma_f32_16x16x32_bf16 v[104:107], v[136:139], v[186:189], v[104:107]
	v_mfma_f32_16x16x32_bf16 v[104:107], v[140:143], v[190:193], v[104:107]
	v_mfma_f32_16x16x32_bf16 v[96:99], v[128:131], v[204:207], v[96:99]
	v_mfma_f32_16x16x32_bf16 v[96:99], v[132:135], v[208:211], v[96:99]
	v_mfma_f32_16x16x32_bf16 v[88:91], v[136:139], v[204:207], v[88:91]
	v_mfma_f32_16x16x32_bf16 v[88:91], v[140:143], v[208:211], v[88:91]
	v_mfma_f32_16x16x32_bf16 v[80:83], v[128:131], v[212:215], v[80:83]
	v_mfma_f32_16x16x32_bf16 v[80:83], v[132:135], v[216:219], v[80:83]
	v_mfma_f32_16x16x32_bf16 v[72:75], v[136:139], v[212:215], v[72:75]
	v_mfma_f32_16x16x32_bf16 v[72:75], v[140:143], v[216:219], v[72:75]
	s_setprio 0
	s_setprio 1
	v_mfma_f32_16x16x32_bf16 v[116:119], v[144:147], v[160:163], v[116:119]
	v_mfma_f32_16x16x32_bf16 v[116:119], v[148:151], v[182:185], v[116:119]
	v_mfma_f32_16x16x32_bf16 v[108:111], v[152:155], v[160:163], v[108:111]
	v_mfma_f32_16x16x32_bf16 v[108:111], v[156:159], v[182:185], v[108:111]
	v_mfma_f32_16x16x32_bf16 v[100:103], v[144:147], v[186:189], v[100:103]
	v_mfma_f32_16x16x32_bf16 v[100:103], v[148:151], v[190:193], v[100:103]
	v_mfma_f32_16x16x32_bf16 v[92:95], v[152:155], v[186:189], v[92:95]
	v_mfma_f32_16x16x32_bf16 v[92:95], v[156:159], v[190:193], v[92:95]
	v_mfma_f32_16x16x32_bf16 v[84:87], v[144:147], v[204:207], v[84:87]
	v_mfma_f32_16x16x32_bf16 v[84:87], v[148:151], v[208:211], v[84:87]
	v_mfma_f32_16x16x32_bf16 v[76:79], v[152:155], v[204:207], v[76:79]
	v_mfma_f32_16x16x32_bf16 v[76:79], v[156:159], v[208:211], v[76:79]
	v_mfma_f32_16x16x32_bf16 v[68:71], v[144:147], v[212:215], v[68:71]
	v_mfma_f32_16x16x32_bf16 v[68:71], v[148:151], v[216:219], v[68:71]
	v_mfma_f32_16x16x32_bf16 v[64:67], v[152:155], v[212:215], v[64:67]
	v_mfma_f32_16x16x32_bf16 v[64:67], v[156:159], v[216:219], v[64:67]
	s_barrier
; #define PG8_STAGE(bufoff, gbase, voff) do { _Pragma("unroll") for (int _i = 0; _i < 2; ++_i) \
;         __builtin_amdgcn_global_load_lds((const unsigned*)((const char*)(gbase) + (voff)[_i]), (PG8_LAS unsigned*)(lds + (bufoff) + ldsw + _i * 8192), 16, 0, 0); } while (0)
; #define PG8_LDA(dst, b, h) do { _Pragma("unroll") for (int m = 0; m < 4; ++m) _Pragma("unroll") for (int k = 0; k < 2; ++k) dst[m][k] = *(const PG8_LAS bf16x8*)(lds + PG8_SA(b, h) + aoff + m * 2048 + k * 1024); } while (0)
; #define PG8_LDB(dst, b, h) do { _Pragma("unroll") for (int n = 0; n < 2; ++n) _Pragma("unroll") for (int k = 0; k < 2; ++k) dst[n][k] = *(const PG8_LAS bf16x8*)(lds + PG8_SB(b, h) + boff + n * 2048 + k * 1024); } while (0)
; #define PG8_MMA(ai, bj, At, Bt) do { __builtin_amdgcn_s_setprio(1); _Pragma("unroll") for (int m = 0; m < 4; ++m) _Pragma("unroll") for (int n = 0; n < 2; ++n) _Pragma("unroll") for (int k = 0; k < 2; ++k) \
;         acc[ai][bj][m][n] = __builtin_amdgcn_mfma_f32_16x16x32_bf16(Bt[n][k], At[m][k], acc[ai][bj][m][n], 0, 0, 0); __builtin_amdgcn_s_setprio(0); } while (0)
; #define PG8_WAIT_V(n) asm volatile("s_waitcnt vmcnt(" #n ")" ::: "memory")
; #define PG8_WAIT_L(n) asm volatile("s_waitcnt lgkmcnt(" #n ")" ::: "memory")
; #define PG8_BAR __builtin_amdgcn_s_barrier()
; #define PG8_SCHED __builtin_amdgcn_sched_barrier(0)
; template <class Epi, class Sched, bool ALIGN_EPI = false, bool SP2 = false, bool DUAL = false>
; __device__ __forceinline__ void gemm_phase(PG8_LAS unsigned char* lds, const Gemm g, const Sched& S, const Epi& E) {
;     ...
;             PG8_LDA(At, 0, 1); PG8_STAGE(PG8_SB(0, 0), b2, voffB); PG8_STAGE(PG8_SB(0, 1), b2 + hstep, voffB); PG8_STAGE(PG8_SA(0, 0), a2, voffA);
;             PG8_WAIT_V(8); PG8_WAIT_L(0); PG8_BAR; PG8_MMA(1, 0, At, B0); PG8_MMA(1, 1, At, B1); PG8_BAR; PG8_SCHED;
;             PG8_LDB(B0, 1, 0); PG8_LDB(B1, 1, 1); PG8_SCHED; PG8_LDA(At, 1, 0); PG8_STAGE(PG8_SA(0, 1), a2 + hstep, voffA);
;             PG8_WAIT_V(8); PG8_WAIT_L(0); PG8_BAR; PG8_MMA(0, 0, At, B0); PG8_MMA(0, 1, At, B1); PG8_BAR; PG8_SCHED;
	s_setprio 0
	s_add_i32 s49, s40, s30
	v_lshl_add_u64 v[220:221], s[14:15], 0, v[166:167]
	s_mov_b32 m0, s49
	ds_read_b128 v[160:163], v203 offset:16384
	ds_read_b128 v[182:185], v203 offset:17408
	ds_read_b128 v[186:189], v203 offset:18432
	ds_read_b128 v[190:193], v203 offset:19456
	ds_read_b128 v[204:207], v203 offset:20480
	ds_read_b128 v[208:211], v203 offset:21504
	ds_read_b128 v[212:215], v203 offset:22528
	ds_read_b128 v[216:219], v203 offset:23552
	global_load_lds_dwordx4 v[220:221], off
	s_add_i32 m0, s49, 0x2000
	s_add_u32 s50, s14, 0x160000
	v_lshl_add_u64 v[222:223], s[14:15], 0, v[170:171]
	s_addc_u32 s51, s15, 0
	s_add_i32 s49, s41, s30
	global_load_lds_dwordx4 v[222:223], off
	v_lshl_add_u64 v[224:225], s[50:51], 0, v[166:167]
	s_mov_b32 m0, s49
	v_lshl_add_u64 v[226:227], s[26:27], 0, v[168:169]
	global_load_lds_dwordx4 v[224:225], off
	v_lshl_add_u64 v[224:225], s[50:51], 0, v[170:171]
	s_add_i32 m0, s49, 0x2000
	s_nop 0
	global_load_lds_dwordx4 v[224:225], off
	v_lshl_add_u64 v[224:225], s[26:27], 0, v[164:165]
	s_mov_b32 m0, s31
	s_nop 0
	global_load_lds_dwordx4 v[224:225], off
	s_mov_b32 m0, s33
	s_nop 0
	global_load_lds_dwordx4 v[226:227], off
	s_waitcnt vmcnt(8)
	s_waitcnt lgkmcnt(0)
	s_setprio 1
	s_barrier
	v_mfma_f32_16x16x32_bf16 v[60:63], v[128:131], v[160:163], v[60:63]
	v_mfma_f32_16x16x32_bf16 v[60:63], v[132:135], v[182:185], v[60:63]
	v_mfma_f32_16x16x32_bf16 v[56:59], v[136:139], v[160:163], v[56:59]
	v_mfma_f32_16x16x32_bf16 v[56:59], v[140:143], v[182:185], v[56:59]
	v_mfma_f32_16x16x32_bf16 v[48:51], v[128:131], v[186:189], v[48:51]
	v_mfma_f32_16x16x32_bf16 v[48:51], v[132:135], v[190:193], v[48:51]
	v_mfma_f32_16x16x32_bf16 v[40:43], v[136:139], v[186:189], v[40:43]
	v_mfma_f32_16x16x32_bf16 v[40:43], v[140:143], v[190:193], v[40:43]
	v_mfma_f32_16x16x32_bf16 v[32:35], v[128:131], v[204:207], v[32:35]
	v_mfma_f32_16x16x32_bf16 v[32:35], v[132:135], v[208:211], v[32:35]
	v_mfma_f32_16x16x32_bf16 v[24:27], v[136:139], v[204:207], v[24:27]
	v_mfma_f32_16x16x32_bf16 v[24:27], v[140:143], v[208:211], v[24:27]
	v_mfma_f32_16x16x32_bf16 v[16:19], v[128:131], v[212:215], v[16:19]
	v_mfma_f32_16x16x32_bf16 v[16:19], v[132:135], v[216:219], v[16:19]
	v_mfma_f32_16x16x32_bf16 v[8:11], v[136:139], v[212:215], v[8:11]
	v_mfma_f32_16x16x32_bf16 v[8:11], v[140:143], v[216:219], v[8:11]
	s_setprio 0
	s_setprio 1
	v_mfma_f32_16x16x32_bf16 v[52:55], v[144:147], v[160:163], v[52:55]
	v_mfma_f32_16x16x32_bf16 v[52:55], v[148:151], v[182:185], v[52:55]
	v_mfma_f32_16x16x32_bf16 v[44:47], v[152:155], v[160:163], v[44:47]
	v_mfma_f32_16x16x32_bf16 v[44:47], v[156:159], v[182:185], v[44:47]
	v_mfma_f32_16x16x32_bf16 v[36:39], v[144:147], v[186:189], v[36:39]
	v_mfma_f32_16x16x32_bf16 v[36:39], v[148:151], v[190:193], v[36:39]
	v_mfma_f32_16x16x32_bf16 v[28:31], v[152:155], v[186:189], v[28:31]
	v_mfma_f32_16x16x32_bf16 v[28:31], v[156:159], v[190:193], v[28:31]
	v_mfma_f32_16x16x32_bf16 v[20:23], v[144:147], v[204:207], v[20:23]
	v_mfma_f32_16x16x32_bf16 v[20:23], v[148:151], v[208:211], v[20:23]
	v_mfma_f32_16x16x32_bf16 v[12:15], v[152:155], v[204:207], v[12:15]
	v_mfma_f32_16x16x32_bf16 v[12:15], v[156:159], v[208:211], v[12:15]
	v_mfma_f32_16x16x32_bf16 v[4:7], v[144:147], v[212:215], v[4:7]
	v_mfma_f32_16x16x32_bf16 v[4:7], v[148:151], v[216:219], v[4:7]
	v_mfma_f32_16x16x32_bf16 v[0:3], v[152:155], v[212:215], v[0:3]
	v_mfma_f32_16x16x32_bf16 v[0:3], v[156:159], v[216:219], v[0:3]
	s_barrier
	s_setprio 0
	s_add_i32 s49, 0, 0x18000
	s_add_i32 s50, 0, 0x1c000
	v_add_u32_e32 v140, s49, v198
	v_add_u32_e32 v156, s50, v198
	ds_read_b128 v[128:131], v140
	ds_read_b128 v[132:135], v140 offset:1024
	ds_read_b128 v[136:139], v140 offset:2048
	ds_read_b128 v[140:143], v140 offset:3072
	ds_read_b128 v[144:147], v156
	ds_read_b128 v[148:151], v156 offset:1024
	ds_read_b128 v[152:155], v156 offset:2048
	ds_read_b128 v[156:159], v156 offset:3072
	s_add_u32 s26, s26, 0x160000
	s_addc_u32 s27, s27, 0
	s_mov_b32 m0, s34
	v_lshl_add_u64 v[228:229], s[26:27], 0, v[164:165]
	ds_read_b128 v[160:163], v203 offset:32768
	ds_read_b128 v[182:185], v203 offset:33792
	ds_read_b128 v[186:189], v203 offset:34816
	ds_read_b128 v[190:193], v203 offset:35840
	ds_read_b128 v[204:207], v203 offset:36864
	ds_read_b128 v[208:211], v203 offset:37888
	ds_read_b128 v[212:215], v203 offset:38912
	ds_read_b128 v[216:219], v203 offset:39936
	global_load_lds_dwordx4 v[228:229], off
	v_lshl_add_u64 v[228:229], s[26:27], 0, v[168:169]
	s_mov_b32 m0, s35
	s_nop 0
	global_load_lds_dwordx4 v[228:229], off
	s_waitcnt vmcnt(8)
	s_waitcnt lgkmcnt(0)
	s_setprio 1
	s_barrier
; #define PG8_STAGE(bufoff, gbase, voff) do { _Pragma("unroll") for (int _i = 0; _i < 2; ++_i) \
;         __builtin_amdgcn_global_load_lds((const unsigned*)((const char*)(gbase) + (voff)[_i]), (PG8_LAS unsigned*)(lds + (bufoff) + ldsw + _i * 8192), 16, 0, 0); } while (0)
; #define PG8_LDA(dst, b, h) do { _Pragma("unroll") for (int m = 0; m < 4; ++m) _Pragma("unroll") for (int k = 0; k < 2; ++k) dst[m][k] = *(const PG8_LAS bf16x8*)(lds + PG8_SA(b, h) + aoff + m * 2048 + k * 1024); } while (0)
; #define PG8_LDB(dst, b, h) do { _Pragma("unroll") for (int n = 0; n < 2; ++n) _Pragma("unroll") for (int k = 0; k < 2; ++k) dst[n][k] = *(const PG8_LAS bf16x8*)(lds + PG8_SB(b, h) + boff + n * 2048 + k * 1024); } while (0)
; #define PG8_MMA(ai, bj, At, Bt) do { __builtin_amdgcn_s_setprio(1); _Pragma("unroll") for (int m = 0; m < 4; ++m) _Pragma("unroll") for (int n = 0; n < 2; ++n) _Pragma("unroll") for (int k = 0; k < 2; ++k) \
;         acc[ai][bj][m][n] = __builtin_amdgcn_mfma_f32_16x16x32_bf16(Bt[n][k], At[m][k], acc[ai][bj][m][n], 0, 0, 0); __builtin_amdgcn_s_setprio(0); } while (0)
; #define PG8_WAIT_V(n) asm volatile("s_waitcnt vmcnt(" #n ")" ::: "memory")
; #define PG8_WAIT_L(n) asm volatile("s_waitcnt lgkmcnt(" #n ")" ::: "memory")
; #define PG8_BAR __builtin_amdgcn_s_barrier()
; #define PG8_SCHED __builtin_amdgcn_sched_barrier(0)
; template <class Epi, class Sched, bool ALIGN_EPI = false, bool SP2 = false, bool DUAL = false>
; __device__ __forceinline__ void gemm_phase(PG8_LAS unsigned char* lds, const Gemm g, const Sched& S, const Epi& E) {
;     ...
;             PG8_LDB(B0, 1, 0); PG8_LDB(B1, 1, 1); PG8_SCHED; PG8_LDA(At, 1, 0); PG8_STAGE(PG8_SA(0, 1), a2 + hstep, voffA);
;             PG8_WAIT_V(8); PG8_WAIT_L(0); PG8_BAR; PG8_MMA(0, 0, At, B0); PG8_MMA(0, 1, At, B1); PG8_BAR; PG8_SCHED;
;             PG8_LDA(At, 1, 1); PG8_STAGE(PG8_SB(1, 0), b3, voffB); PG8_STAGE(PG8_SB(1, 1), b3 + hstep, voffB); PG8_STAGE(PG8_SA(1, 0), a3, voffA);
;             PG8_WAIT_V(8); PG8_WAIT_L(0); PG8_BAR; PG8_MMA(1, 0, At, B0); PG8_MMA(1, 1, At, B1); PG8_BAR; PG8_SCHED;
	v_mfma_f32_16x16x32_bf16 v[124:127], v[128:131], v[160:163], v[124:127]
	v_mfma_f32_16x16x32_bf16 v[124:127], v[132:135], v[182:185], v[124:127]
	v_mfma_f32_16x16x32_bf16 v[120:123], v[136:139], v[160:163], v[120:123]
	v_mfma_f32_16x16x32_bf16 v[120:123], v[140:143], v[182:185], v[120:123]
	v_mfma_f32_16x16x32_bf16 v[112:115], v[128:131], v[186:189], v[112:115]
	v_mfma_f32_16x16x32_bf16 v[112:115], v[132:135], v[190:193], v[112:115]
	v_mfma_f32_16x16x32_bf16 v[104:107], v[136:139], v[186:189], v[104:107]
	v_mfma_f32_16x16x32_bf16 v[104:107], v[140:143], v[190:193], v[104:107]
	v_mfma_f32_16x16x32_bf16 v[96:99], v[128:131], v[204:207], v[96:99]
	v_mfma_f32_16x16x32_bf16 v[96:99], v[132:135], v[208:211], v[96:99]
	v_mfma_f32_16x16x32_bf16 v[88:91], v[136:139], v[204:207], v[88:91]
	v_mfma_f32_16x16x32_bf16 v[88:91], v[140:143], v[208:211], v[88:91]
	v_mfma_f32_16x16x32_bf16 v[80:83], v[128:131], v[212:215], v[80:83]
	v_mfma_f32_16x16x32_bf16 v[80:83], v[132:135], v[216:219], v[80:83]
	v_mfma_f32_16x16x32_bf16 v[72:75], v[136:139], v[212:215], v[72:75]
	v_mfma_f32_16x16x32_bf16 v[72:75], v[140:143], v[216:219], v[72:75]
	s_setprio 0
	s_setprio 1
	v_mfma_f32_16x16x32_bf16 v[116:119], v[144:147], v[160:163], v[116:119]
	v_mfma_f32_16x16x32_bf16 v[116:119], v[148:151], v[182:185], v[116:119]
	v_mfma_f32_16x16x32_bf16 v[108:111], v[152:155], v[160:163], v[108:111]
	v_mfma_f32_16x16x32_bf16 v[108:111], v[156:159], v[182:185], v[108:111]
	v_mfma_f32_16x16x32_bf16 v[100:103], v[144:147], v[186:189], v[100:103]
	v_mfma_f32_16x16x32_bf16 v[100:103], v[148:151], v[190:193], v[100:103]
	v_mfma_f32_16x16x32_bf16 v[92:95], v[152:155], v[186:189], v[92:95]
	v_mfma_f32_16x16x32_bf16 v[92:95], v[156:159], v[190:193], v[92:95]
	v_mfma_f32_16x16x32_bf16 v[84:87], v[144:147], v[204:207], v[84:87]
	v_mfma_f32_16x16x32_bf16 v[84:87], v[148:151], v[208:211], v[84:87]
	v_mfma_f32_16x16x32_bf16 v[76:79], v[152:155], v[204:207], v[76:79]
	v_mfma_f32_16x16x32_bf16 v[76:79], v[156:159], v[208:211], v[76:79]
	v_mfma_f32_16x16x32_bf16 v[68:71], v[144:147], v[212:215], v[68:71]
	v_mfma_f32_16x16x32_bf16 v[68:71], v[148:151], v[216:219], v[68:71]
	v_mfma_f32_16x16x32_bf16 v[64:67], v[152:155], v[212:215], v[64:67]
	v_mfma_f32_16x16x32_bf16 v[64:67], v[156:159], v[216:219], v[64:67]
	s_barrier
	s_setprio 0
	s_add_i32 s26, s49, s30
	v_lshl_add_u64 v[220:221], v[220:221], 0, s[18:19]
	s_mov_b32 m0, s26
	ds_read_b128 v[160:163], v203 offset:49152
	ds_read_b128 v[182:185], v203 offset:50176
	ds_read_b128 v[186:189], v203 offset:51200
	ds_read_b128 v[190:193], v203 offset:52224
	ds_read_b128 v[204:207], v203 offset:53248
	ds_read_b128 v[208:211], v203 offset:54272
	ds_read_b128 v[212:215], v203 offset:55296
	ds_read_b128 v[216:219], v203 offset:56320
	global_load_lds_dwordx4 v[220:221], off
	s_add_i32 m0, s26, 0x2000
	s_add_u32 s14, s14, 0x160080
	v_lshl_add_u64 v[220:221], v[222:223], 0, s[18:19]
	s_addc_u32 s15, s15, 0
	s_add_i32 s26, s50, s30
	global_load_lds_dwordx4 v[220:221], off
	v_lshl_add_u64 v[220:221], s[14:15], 0, v[166:167]
	s_mov_b32 m0, s26
	s_nop 0
	global_load_lds_dwordx4 v[220:221], off
	v_lshl_add_u64 v[220:221], s[14:15], 0, v[170:171]
	s_add_i32 m0, s26, 0x2000
	s_nop 0
	global_load_lds_dwordx4 v[220:221], off
	v_lshl_add_u64 v[220:221], v[224:225], 0, s[18:19]
	s_mov_b32 m0, s37
	s_nop 0
	global_load_lds_dwordx4 v[220:221], off
	v_lshl_add_u64 v[220:221], v[226:227], 0, s[18:19]
	s_mov_b32 m0, s38
	s_nop 0
	global_load_lds_dwordx4 v[220:221], off
	s_waitcnt vmcnt(8)
	s_waitcnt lgkmcnt(0)
	s_setprio 1
	s_barrier
	v_mfma_f32_16x16x32_bf16 v[60:63], v[128:131], v[160:163], v[60:63]
	v_mfma_f32_16x16x32_bf16 v[60:63], v[132:135], v[182:185], v[60:63]
	v_mfma_f32_16x16x32_bf16 v[56:59], v[136:139], v[160:163], v[56:59]
	v_mfma_f32_16x16x32_bf16 v[56:59], v[140:143], v[182:185], v[56:59]
	v_mfma_f32_16x16x32_bf16 v[48:51], v[128:131], v[186:189], v[48:51]
	v_mfma_f32_16x16x32_bf16 v[48:51], v[132:135], v[190:193], v[48:51]
	v_mfma_f32_16x16x32_bf16 v[40:43], v[136:139], v[186:189], v[40:43]
	v_mfma_f32_16x16x32_bf16 v[40:43], v[140:143], v[190:193], v[40:43]
	v_mfma_f32_16x16x32_bf16 v[32:35], v[128:131], v[204:207], v[32:35]
	v_mfma_f32_16x16x32_bf16 v[32:35], v[132:135], v[208:211], v[32:35]
	v_mfma_f32_16x16x32_bf16 v[24:27], v[136:139], v[204:207], v[24:27]
	v_mfma_f32_16x16x32_bf16 v[24:27], v[140:143], v[208:211], v[24:27]
	v_mfma_f32_16x16x32_bf16 v[16:19], v[128:131], v[212:215], v[16:19]
	v_mfma_f32_16x16x32_bf16 v[16:19], v[132:135], v[216:219], v[16:19]
	v_mfma_f32_16x16x32_bf16 v[8:11], v[136:139], v[212:215], v[8:11]
	v_mfma_f32_16x16x32_bf16 v[8:11], v[140:143], v[216:219], v[8:11]
	s_setprio 0
	s_setprio 1
	v_mfma_f32_16x16x32_bf16 v[52:55], v[144:147], v[160:163], v[52:55]
	v_mfma_f32_16x16x32_bf16 v[52:55], v[148:151], v[182:185], v[52:55]
	v_mfma_f32_16x16x32_bf16 v[44:47], v[152:155], v[160:163], v[44:47]
	v_mfma_f32_16x16x32_bf16 v[44:47], v[156:159], v[182:185], v[44:47]
	v_mfma_f32_16x16x32_bf16 v[36:39], v[144:147], v[186:189], v[36:39]
	v_mfma_f32_16x16x32_bf16 v[36:39], v[148:151], v[190:193], v[36:39]
	v_mfma_f32_16x16x32_bf16 v[28:31], v[152:155], v[186:189], v[28:31]
	v_mfma_f32_16x16x32_bf16 v[28:31], v[156:159], v[190:193], v[28:31]
	v_mfma_f32_16x16x32_bf16 v[20:23], v[144:147], v[204:207], v[20:23]
	v_mfma_f32_16x16x32_bf16 v[20:23], v[148:151], v[208:211], v[20:23]
	v_mfma_f32_16x16x32_bf16 v[12:15], v[152:155], v[204:207], v[12:15]
	v_mfma_f32_16x16x32_bf16 v[12:15], v[156:159], v[208:211], v[12:15]
	v_mfma_f32_16x16x32_bf16 v[4:7], v[144:147], v[212:215], v[4:7]
	v_mfma_f32_16x16x32_bf16 v[4:7], v[148:151], v[216:219], v[4:7]
	v_mfma_f32_16x16x32_bf16 v[0:3], v[152:155], v[212:215], v[0:3]
	v_mfma_f32_16x16x32_bf16 v[0:3], v[156:159], v[216:219], v[0:3]
	s_barrier
	s_setprio 0
	s_add_i32 s48, s48, 2
	s_add_u32 s24, s24, 0x100
	s_addc_u32 s25, s25, 0
	s_add_u32 s46, s46, 0x100
	s_addc_u32 s47, s47, 0
	s_cmpk_gt_u32 s48, 0x55
	s_cbranch_scc0 .LBB0_1193
	s_and_b64 vcc, exec, s[20:21]
	s_cbranch_vccz .LBB0_1196
	s_barrier
